# removed the 44 back-to-back s_setprio 0 / s_setprio 1 pairs inside GEMM MFMA segments; global_* ops, deferred SSQ atomics
# speedup vs baseline: 1.0054x; 1.0054x over previous
; #define PG8_STAGE(bufoff, gbase, voff) do { _Pragma("unroll") for (int _i = 0; _i < 2; ++_i) \
;         __builtin_amdgcn_global_load_lds((const unsigned*)((const char*)(gbase) + (voff)[_i]), (PG8_LAS unsigned*)(lds + (bufoff) + ldsw + _i * 8192), 16, 0, 0); } while (0)
; #define PG8_LDA(dst, b, h) do { _Pragma("unroll") for (int m = 0; m < 4; ++m) _Pragma("unroll") for (int k = 0; k < 2; ++k) dst[m][k] = *(const PG8_LAS bf16x8*)(lds + PG8_SA(b, h) + aoff + m * 2048 + k * 1024); } while (0)
; #define PG8_LDB(dst, b, h) do { _Pragma("unroll") for (int n = 0; n < 2; ++n) _Pragma("unroll") for (int k = 0; k < 2; ++k) dst[n][k] = *(const PG8_LAS bf16x8*)(lds + PG8_SB(b, h) + boff + n * 2048 + k * 1024); } while (0)
; #define PG8_MMA(ai, bj, At, Bt) do { __builtin_amdgcn_s_setprio(1); _Pragma("unroll") for (int m = 0; m < 4; ++m) _Pragma("unroll") for (int n = 0; n < 2; ++n) _Pragma("unroll") for (int k = 0; k < 2; ++k) \
;         acc[ai][bj][m][n] = __builtin_amdgcn_mfma_f32_16x16x32_bf16(Bt[n][k], At[m][k], acc[ai][bj][m][n], 0, 0, 0); __builtin_amdgcn_s_setprio(0); } while (0)
; #define PG8_WAIT_V(n) asm volatile("s_waitcnt vmcnt(" #n ")" ::: "memory")
; #define PG8_WAIT_L(n) asm volatile("s_waitcnt lgkmcnt(" #n ")" ::: "memory")
; #define PG8_BAR __builtin_amdgcn_s_barrier()
; #define PG8_SCHED __builtin_amdgcn_sched_barrier(0)
; template <class Epi, class Sched, bool ALIGN_EPI = false, bool SP2 = false>
; __device__ __forceinline__ void gemm_phase(PG8_LAS unsigned char* lds, const Gemm g, const Sched& S, const Epi& E, const int wid) {
;     ...
;         for (int t = 0; t < nt; t += 2) {
;             const bool last = (t == nt - 2);
;             const char* a1 = cA + (size_t)(t + 1) * kstep;
;             const char* a2 = last ? nA : cA + (size_t)(t + 2) * kstep; const char* b2 = last ? nB : cB + (size_t)(t + 2) * kstep;
;             const char* a3 = a2 + kstep; const char* b3 = b2 + kstep;
;             if constexpr (SP2) {
;             PG8_LDB(B0, 0, 0); PG8_LDB(B1, 0, 1); PG8_SCHED; PG8_LDA(At, 0, 0); PG8_STAGE(PG8_SA(1, 1), a1 + hsA, voffA);
;             PG8_WAIT_V(8); PG8_WAIT_L(0); PG8_BAR; PG8_MMA(0, 0, At, B0); PG8_MMA(0, 1, At, B1); PG8_BAR; PG8_SCHED;
;             PG8_LDA(At, 0, 1); PG8_STAGE(PG8_SB(0, 0), b2, voffB); PG8_STAGE(PG8_SB(0, 1), b2 + hsB, voffB); PG8_STAGE(PG8_SA(0, 0), a2, voffA);
.LBB0_418:
	ds_read_b128 v[144:147], v149
	ds_read_b128 v[152:155], v149 offset:1024
	ds_read_b128 v[156:159], v149 offset:2048
	ds_read_b128 v[160:163], v149 offset:3072
	ds_read_b128 v[164:167], v150
	ds_read_b128 v[168:171], v150 offset:1024
	ds_read_b128 v[172:175], v150 offset:2048
	ds_read_b128 v[176:179], v150 offset:3072
	s_add_u32 s26, s24, 0xfff80080
	s_addc_u32 s27, s25, -1
	s_cmp_eq_u32 s55, 28
	s_cselect_b32 s29, s17, s27
	s_cselect_b32 s28, s51, s26
	s_cselect_b32 s27, s15, s54
	s_cselect_b32 s26, s52, s53
	v_lshl_add_u64 v[212:213], s[24:25], 0, v[138:139]
	s_add_i32 m0, s23, 0xc000
	ds_read_b128 v[180:183], v151
	ds_read_b128 v[184:187], v151 offset:1024
	ds_read_b128 v[188:191], v151 offset:2048
	ds_read_b128 v[192:195], v151 offset:3072
	ds_read_b128 v[196:199], v151 offset:4096
	ds_read_b128 v[200:203], v151 offset:5120
	ds_read_b128 v[204:207], v151 offset:6144
	ds_read_b128 v[208:211], v151 offset:7168
	global_load_lds_dwordx4 v[212:213], off
	v_lshl_add_u64 v[212:213], s[24:25], 0, v[136:137]
	s_add_i32 m0, s23, 0xe000
	s_nop 0
	global_load_lds_dwordx4 v[212:213], off
	s_waitcnt vmcnt(8)
	s_waitcnt lgkmcnt(0)
	s_barrier
	s_setprio 1
	s_waitcnt lgkmcnt(0)
	v_mfma_f32_16x16x32_bf16 v[124:127], v[144:147], v[180:183], v[124:127]
	v_mfma_f32_16x16x32_bf16 v[120:123], v[156:159], v[180:183], v[120:123]
	v_mfma_f32_16x16x32_bf16 v[108:111], v[144:147], v[188:191], v[108:111]
	v_mfma_f32_16x16x32_bf16 v[104:107], v[156:159], v[188:191], v[104:107]
	v_mfma_f32_16x16x32_bf16 v[92:95], v[144:147], v[196:199], v[92:95]
	v_mfma_f32_16x16x32_bf16 v[88:91], v[156:159], v[196:199], v[88:91]
	v_mfma_f32_16x16x32_bf16 v[76:79], v[144:147], v[204:207], v[76:79]
	v_mfma_f32_16x16x32_bf16 v[72:75], v[156:159], v[204:207], v[72:75]
	v_mfma_f32_16x16x32_bf16 v[124:127], v[152:155], v[184:187], v[124:127]
	v_mfma_f32_16x16x32_bf16 v[120:123], v[160:163], v[184:187], v[120:123]
	v_mfma_f32_16x16x32_bf16 v[108:111], v[152:155], v[192:195], v[108:111]
	v_mfma_f32_16x16x32_bf16 v[104:107], v[160:163], v[192:195], v[104:107]
	v_mfma_f32_16x16x32_bf16 v[92:95], v[152:155], v[200:203], v[92:95]
	v_mfma_f32_16x16x32_bf16 v[88:91], v[160:163], v[200:203], v[88:91]
	v_mfma_f32_16x16x32_bf16 v[76:79], v[152:155], v[208:211], v[76:79]
	v_mfma_f32_16x16x32_bf16 v[72:75], v[160:163], v[208:211], v[72:75]
	v_mfma_f32_16x16x32_bf16 v[116:119], v[164:167], v[180:183], v[116:119]
	v_mfma_f32_16x16x32_bf16 v[112:115], v[172:175], v[180:183], v[112:115]
	v_mfma_f32_16x16x32_bf16 v[100:103], v[164:167], v[188:191], v[100:103]
	v_mfma_f32_16x16x32_bf16 v[96:99], v[172:175], v[188:191], v[96:99]
	v_mfma_f32_16x16x32_bf16 v[84:87], v[164:167], v[196:199], v[84:87]
	v_mfma_f32_16x16x32_bf16 v[80:83], v[172:175], v[196:199], v[80:83]
	v_mfma_f32_16x16x32_bf16 v[68:71], v[164:167], v[204:207], v[68:71]
	v_mfma_f32_16x16x32_bf16 v[64:67], v[172:175], v[204:207], v[64:67]
	v_mfma_f32_16x16x32_bf16 v[116:119], v[168:171], v[184:187], v[116:119]
	v_mfma_f32_16x16x32_bf16 v[112:115], v[176:179], v[184:187], v[112:115]
	v_mfma_f32_16x16x32_bf16 v[100:103], v[168:171], v[192:195], v[100:103]
	v_mfma_f32_16x16x32_bf16 v[96:99], v[176:179], v[192:195], v[96:99]
	v_mfma_f32_16x16x32_bf16 v[84:87], v[168:171], v[200:203], v[84:87]
	v_mfma_f32_16x16x32_bf16 v[80:83], v[176:179], v[200:203], v[80:83]
	v_mfma_f32_16x16x32_bf16 v[68:71], v[168:171], v[208:211], v[68:71]
	v_mfma_f32_16x16x32_bf16 v[64:67], v[176:179], v[208:211], v[64:67]
	s_setprio 0
	s_barrier
	s_add_i32 s56, s47, s34
	v_lshl_add_u64 v[212:213], s[26:27], 0, v[132:133]
	s_mov_b32 m0, s56
	ds_read_b128 v[180:183], v151 offset:16384
	ds_read_b128 v[184:187], v151 offset:17408
	ds_read_b128 v[188:191], v151 offset:18432
	ds_read_b128 v[192:195], v151 offset:19456
	ds_read_b128 v[196:199], v151 offset:20480
	ds_read_b128 v[200:203], v151 offset:21504
	ds_read_b128 v[204:207], v151 offset:22528
	ds_read_b128 v[208:211], v151 offset:23552
	global_load_lds_dwordx4 v[212:213], off
	s_add_i32 m0, s56, 0x2000
	s_add_u32 s56, s26, 0x80000
	v_lshl_add_u64 v[214:215], s[26:27], 0, v[128:129]
	s_addc_u32 s57, s27, 0
	s_add_i32 s58, s48, s34
	global_load_lds_dwordx4 v[214:215], off
	v_lshl_add_u64 v[216:217], s[56:57], 0, v[132:133]
	s_mov_b32 m0, s58
	v_lshl_add_u64 v[218:219], s[28:29], 0, v[130:131]
	global_load_lds_dwordx4 v[216:217], off
	v_lshl_add_u64 v[216:217], s[56:57], 0, v[128:129]
	s_add_i32 m0, s58, 0x2000
	s_nop 0
	global_load_lds_dwordx4 v[216:217], off
	v_lshl_add_u64 v[216:217], s[28:29], 0, v[134:135]
	s_mov_b32 m0, s23
	s_nop 0
	global_load_lds_dwordx4 v[216:217], off
	s_mov_b32 m0, s37
	s_nop 0
	global_load_lds_dwordx4 v[218:219], off
	s_waitcnt vmcnt(8)
	s_waitcnt lgkmcnt(0)
	s_barrier
; #define PG8_STAGE(bufoff, gbase, voff) do { _Pragma("unroll") for (int _i = 0; _i < 2; ++_i) \
;         __builtin_amdgcn_global_load_lds((const unsigned*)((const char*)(gbase) + (voff)[_i]), (PG8_LAS unsigned*)(lds + (bufoff) + ldsw + _i * 8192), 16, 0, 0); } while (0)
; #define PG8_LDA(dst, b, h) do { _Pragma("unroll") for (int m = 0; m < 4; ++m) _Pragma("unroll") for (int k = 0; k < 2; ++k) dst[m][k] = *(const PG8_LAS bf16x8*)(lds + PG8_SA(b, h) + aoff + m * 2048 + k * 1024); } while (0)
; #define PG8_LDB(dst, b, h) do { _Pragma("unroll") for (int n = 0; n < 2; ++n) _Pragma("unroll") for (int k = 0; k < 2; ++k) dst[n][k] = *(const PG8_LAS bf16x8*)(lds + PG8_SB(b, h) + boff + n * 2048 + k * 1024); } while (0)
; #define PG8_MMA(ai, bj, At, Bt) do { __builtin_amdgcn_s_setprio(1); _Pragma("unroll") for (int m = 0; m < 4; ++m) _Pragma("unroll") for (int n = 0; n < 2; ++n) _Pragma("unroll") for (int k = 0; k < 2; ++k) \
;         acc[ai][bj][m][n] = __builtin_amdgcn_mfma_f32_16x16x32_bf16(Bt[n][k], At[m][k], acc[ai][bj][m][n], 0, 0, 0); __builtin_amdgcn_s_setprio(0); } while (0)
; #define PG8_WAIT_V(n) asm volatile("s_waitcnt vmcnt(" #n ")" ::: "memory")
; #define PG8_WAIT_L(n) asm volatile("s_waitcnt lgkmcnt(" #n ")" ::: "memory")
; #define PG8_BAR __builtin_amdgcn_s_barrier()
; #define PG8_SCHED __builtin_amdgcn_sched_barrier(0)
; template <class Epi, class Sched, bool ALIGN_EPI = false, bool SP2 = false>
; __device__ __forceinline__ void gemm_phase(PG8_LAS unsigned char* lds, const Gemm g, const Sched& S, const Epi& E, const int wid) {
;     ...
;             PG8_WAIT_V(8); PG8_WAIT_L(0); PG8_BAR; PG8_MMA(1, 0, At, B0); PG8_MMA(1, 1, At, B1); PG8_BAR; PG8_SCHED;
;             PG8_LDB(B0, 1, 0); PG8_LDB(B1, 1, 1); PG8_SCHED; PG8_LDA(At, 1, 0); PG8_STAGE(PG8_SA(0, 1), a2 + hsA, voffA);
;             PG8_WAIT_V(8); PG8_WAIT_L(0); PG8_BAR; PG8_MMA(0, 0, At, B0); PG8_MMA(0, 1, At, B1); PG8_BAR; PG8_SCHED;
	s_setprio 1
	s_waitcnt lgkmcnt(0)
	v_mfma_f32_16x16x32_bf16 v[60:63], v[144:147], v[180:183], v[60:63]
	v_mfma_f32_16x16x32_bf16 v[56:59], v[156:159], v[180:183], v[56:59]
	v_mfma_f32_16x16x32_bf16 v[44:47], v[144:147], v[188:191], v[44:47]
	v_mfma_f32_16x16x32_bf16 v[40:43], v[156:159], v[188:191], v[40:43]
	v_mfma_f32_16x16x32_bf16 v[28:31], v[144:147], v[196:199], v[28:31]
	v_mfma_f32_16x16x32_bf16 v[24:27], v[156:159], v[196:199], v[24:27]
	v_mfma_f32_16x16x32_bf16 v[12:15], v[144:147], v[204:207], v[12:15]
	v_mfma_f32_16x16x32_bf16 v[8:11], v[156:159], v[204:207], v[8:11]
	v_mfma_f32_16x16x32_bf16 v[60:63], v[152:155], v[184:187], v[60:63]
	v_mfma_f32_16x16x32_bf16 v[56:59], v[160:163], v[184:187], v[56:59]
	v_mfma_f32_16x16x32_bf16 v[44:47], v[152:155], v[192:195], v[44:47]
	v_mfma_f32_16x16x32_bf16 v[40:43], v[160:163], v[192:195], v[40:43]
	v_mfma_f32_16x16x32_bf16 v[28:31], v[152:155], v[200:203], v[28:31]
	v_mfma_f32_16x16x32_bf16 v[24:27], v[160:163], v[200:203], v[24:27]
	v_mfma_f32_16x16x32_bf16 v[12:15], v[152:155], v[208:211], v[12:15]
	v_mfma_f32_16x16x32_bf16 v[8:11], v[160:163], v[208:211], v[8:11]
	v_mfma_f32_16x16x32_bf16 v[52:55], v[164:167], v[180:183], v[52:55]
	v_mfma_f32_16x16x32_bf16 v[48:51], v[172:175], v[180:183], v[48:51]
	v_mfma_f32_16x16x32_bf16 v[36:39], v[164:167], v[188:191], v[36:39]
	v_mfma_f32_16x16x32_bf16 v[32:35], v[172:175], v[188:191], v[32:35]
	v_mfma_f32_16x16x32_bf16 v[20:23], v[164:167], v[196:199], v[20:23]
	v_mfma_f32_16x16x32_bf16 v[16:19], v[172:175], v[196:199], v[16:19]
	v_mfma_f32_16x16x32_bf16 v[4:7], v[164:167], v[204:207], v[4:7]
	v_mfma_f32_16x16x32_bf16 v[0:3], v[172:175], v[204:207], v[0:3]
	v_mfma_f32_16x16x32_bf16 v[52:55], v[168:171], v[184:187], v[52:55]
	v_mfma_f32_16x16x32_bf16 v[48:51], v[176:179], v[184:187], v[48:51]
	v_mfma_f32_16x16x32_bf16 v[36:39], v[168:171], v[192:195], v[36:39]
	v_mfma_f32_16x16x32_bf16 v[32:35], v[176:179], v[192:195], v[32:35]
	v_mfma_f32_16x16x32_bf16 v[20:23], v[168:171], v[200:203], v[20:23]
	v_mfma_f32_16x16x32_bf16 v[16:19], v[176:179], v[200:203], v[16:19]
	v_mfma_f32_16x16x32_bf16 v[4:7], v[168:171], v[208:211], v[4:7]
	v_mfma_f32_16x16x32_bf16 v[0:3], v[176:179], v[208:211], v[0:3]
	s_setprio 0
	s_barrier
	s_add_i32 s56, 0, 0x18000
	s_add_i32 s57, 0, 0x1c000
	v_add_u32_e32 v160, s56, v148
	v_add_u32_e32 v176, s57, v148
	ds_read_b128 v[144:147], v160
	ds_read_b128 v[152:155], v160 offset:1024
	ds_read_b128 v[156:159], v160 offset:2048
	ds_read_b128 v[160:163], v160 offset:3072
	ds_read_b128 v[164:167], v176
	ds_read_b128 v[168:171], v176 offset:1024
	ds_read_b128 v[172:175], v176 offset:2048
	ds_read_b128 v[176:179], v176 offset:3072
	s_add_u32 s28, s28, 0x80000
	s_addc_u32 s29, s29, 0
	s_mov_b32 m0, s38
	v_lshl_add_u64 v[220:221], s[28:29], 0, v[134:135]
	ds_read_b128 v[180:183], v151 offset:32768
	ds_read_b128 v[184:187], v151 offset:33792
	ds_read_b128 v[188:191], v151 offset:34816
	ds_read_b128 v[192:195], v151 offset:35840
	ds_read_b128 v[196:199], v151 offset:36864
	ds_read_b128 v[200:203], v151 offset:37888
	ds_read_b128 v[204:207], v151 offset:38912
	ds_read_b128 v[208:211], v151 offset:39936
	global_load_lds_dwordx4 v[220:221], off
	v_lshl_add_u64 v[220:221], s[28:29], 0, v[130:131]
	s_mov_b32 m0, s39
	s_nop 0
	global_load_lds_dwordx4 v[220:221], off
	s_waitcnt vmcnt(8)
	s_waitcnt lgkmcnt(0)
	s_barrier
	s_setprio 1
	s_waitcnt lgkmcnt(0)
	v_mfma_f32_16x16x32_bf16 v[124:127], v[144:147], v[180:183], v[124:127]
	v_mfma_f32_16x16x32_bf16 v[120:123], v[156:159], v[180:183], v[120:123]
	v_mfma_f32_16x16x32_bf16 v[108:111], v[144:147], v[188:191], v[108:111]
	v_mfma_f32_16x16x32_bf16 v[104:107], v[156:159], v[188:191], v[104:107]
	v_mfma_f32_16x16x32_bf16 v[92:95], v[144:147], v[196:199], v[92:95]
	v_mfma_f32_16x16x32_bf16 v[88:91], v[156:159], v[196:199], v[88:91]
	v_mfma_f32_16x16x32_bf16 v[76:79], v[144:147], v[204:207], v[76:79]
	v_mfma_f32_16x16x32_bf16 v[72:75], v[156:159], v[204:207], v[72:75]
	v_mfma_f32_16x16x32_bf16 v[124:127], v[152:155], v[184:187], v[124:127]
	v_mfma_f32_16x16x32_bf16 v[120:123], v[160:163], v[184:187], v[120:123]
	v_mfma_f32_16x16x32_bf16 v[108:111], v[152:155], v[192:195], v[108:111]
	v_mfma_f32_16x16x32_bf16 v[104:107], v[160:163], v[192:195], v[104:107]
	v_mfma_f32_16x16x32_bf16 v[92:95], v[152:155], v[200:203], v[92:95]
	v_mfma_f32_16x16x32_bf16 v[88:91], v[160:163], v[200:203], v[88:91]
	v_mfma_f32_16x16x32_bf16 v[76:79], v[152:155], v[208:211], v[76:79]
	v_mfma_f32_16x16x32_bf16 v[72:75], v[160:163], v[208:211], v[72:75]
	v_mfma_f32_16x16x32_bf16 v[116:119], v[164:167], v[180:183], v[116:119]
	v_mfma_f32_16x16x32_bf16 v[112:115], v[172:175], v[180:183], v[112:115]
	v_mfma_f32_16x16x32_bf16 v[100:103], v[164:167], v[188:191], v[100:103]
	v_mfma_f32_16x16x32_bf16 v[96:99], v[172:175], v[188:191], v[96:99]
	v_mfma_f32_16x16x32_bf16 v[84:87], v[164:167], v[196:199], v[84:87]
	v_mfma_f32_16x16x32_bf16 v[80:83], v[172:175], v[196:199], v[80:83]
	v_mfma_f32_16x16x32_bf16 v[68:71], v[164:167], v[204:207], v[68:71]
	v_mfma_f32_16x16x32_bf16 v[64:67], v[172:175], v[204:207], v[64:67]
	v_mfma_f32_16x16x32_bf16 v[116:119], v[168:171], v[184:187], v[116:119]
	v_mfma_f32_16x16x32_bf16 v[112:115], v[176:179], v[184:187], v[112:115]
	v_mfma_f32_16x16x32_bf16 v[100:103], v[168:171], v[192:195], v[100:103]
	v_mfma_f32_16x16x32_bf16 v[96:99], v[176:179], v[192:195], v[96:99]
	v_mfma_f32_16x16x32_bf16 v[84:87], v[168:171], v[200:203], v[84:87]
	v_mfma_f32_16x16x32_bf16 v[80:83], v[176:179], v[200:203], v[80:83]
	v_mfma_f32_16x16x32_bf16 v[68:71], v[168:171], v[208:211], v[68:71]
	v_mfma_f32_16x16x32_bf16 v[64:67], v[176:179], v[208:211], v[64:67]
	s_setprio 0
	s_barrier
; #define PG8_STAGE(bufoff, gbase, voff) do { _Pragma("unroll") for (int _i = 0; _i < 2; ++_i) \
;         __builtin_amdgcn_global_load_lds((const unsigned*)((const char*)(gbase) + (voff)[_i]), (PG8_LAS unsigned*)(lds + (bufoff) + ldsw + _i * 8192), 16, 0, 0); } while (0)
; #define PG8_LDA(dst, b, h) do { _Pragma("unroll") for (int m = 0; m < 4; ++m) _Pragma("unroll") for (int k = 0; k < 2; ++k) dst[m][k] = *(const PG8_LAS bf16x8*)(lds + PG8_SA(b, h) + aoff + m * 2048 + k * 1024); } while (0)
; #define PG8_MMA(ai, bj, At, Bt) do { __builtin_amdgcn_s_setprio(1); _Pragma("unroll") for (int m = 0; m < 4; ++m) _Pragma("unroll") for (int n = 0; n < 2; ++n) _Pragma("unroll") for (int k = 0; k < 2; ++k) \
;         acc[ai][bj][m][n] = __builtin_amdgcn_mfma_f32_16x16x32_bf16(Bt[n][k], At[m][k], acc[ai][bj][m][n], 0, 0, 0); __builtin_amdgcn_s_setprio(0); } while (0)
; #define PG8_WAIT_V(n) asm volatile("s_waitcnt vmcnt(" #n ")" ::: "memory")
; #define PG8_WAIT_L(n) asm volatile("s_waitcnt lgkmcnt(" #n ")" ::: "memory")
; #define PG8_BAR __builtin_amdgcn_s_barrier()
; #define PG8_SCHED __builtin_amdgcn_sched_barrier(0)
; template <class Epi, class Sched, bool ALIGN_EPI = false, bool SP2 = false>
; __device__ __forceinline__ void gemm_phase(PG8_LAS unsigned char* lds, const Gemm g, const Sched& S, const Epi& E, const int wid) {
;     ...
;             PG8_LDA(At, 1, 1); PG8_STAGE(PG8_SB(1, 0), b3, voffB); PG8_STAGE(PG8_SB(1, 1), b3 + hsB, voffB); PG8_STAGE(PG8_SA(1, 0), a3, voffA);
;             PG8_WAIT_V(8); PG8_WAIT_L(0); PG8_BAR; PG8_MMA(1, 0, At, B0); PG8_MMA(1, 1, At, B1); PG8_BAR; PG8_SCHED;
;     ...
;         if constexpr (ALIGN_EPI) { if (wr == 0) PG8_BAR; }
	s_add_i32 s28, s56, s34
	v_lshl_add_u64 v[212:213], v[212:213], 0, s[10:11]
	s_mov_b32 m0, s28
	ds_read_b128 v[180:183], v151 offset:49152
	ds_read_b128 v[184:187], v151 offset:50176
	ds_read_b128 v[188:191], v151 offset:51200
	ds_read_b128 v[192:195], v151 offset:52224
	ds_read_b128 v[196:199], v151 offset:53248
	ds_read_b128 v[200:203], v151 offset:54272
	ds_read_b128 v[204:207], v151 offset:55296
	ds_read_b128 v[208:211], v151 offset:56320
	global_load_lds_dwordx4 v[212:213], off
	s_add_i32 m0, s28, 0x2000
	s_add_u32 s26, s26, 0x80080
	v_lshl_add_u64 v[212:213], v[214:215], 0, s[10:11]
	s_addc_u32 s27, s27, 0
	s_add_i32 s28, s57, s34
	global_load_lds_dwordx4 v[212:213], off
	v_lshl_add_u64 v[212:213], s[26:27], 0, v[132:133]
	s_mov_b32 m0, s28
	s_nop 0
	global_load_lds_dwordx4 v[212:213], off
	v_lshl_add_u64 v[212:213], s[26:27], 0, v[128:129]
	s_add_i32 m0, s28, 0x2000
	s_nop 0
	global_load_lds_dwordx4 v[212:213], off
	v_lshl_add_u64 v[212:213], v[216:217], 0, s[10:11]
	s_mov_b32 m0, s42
	s_nop 0
	global_load_lds_dwordx4 v[212:213], off
	v_lshl_add_u64 v[212:213], v[218:219], 0, s[10:11]
	s_mov_b32 m0, s43
	s_nop 0
	global_load_lds_dwordx4 v[212:213], off
	s_waitcnt vmcnt(8)
	s_waitcnt lgkmcnt(0)
	s_barrier
	s_setprio 1
	s_waitcnt lgkmcnt(0)
	v_mfma_f32_16x16x32_bf16 v[60:63], v[144:147], v[180:183], v[60:63]
	v_mfma_f32_16x16x32_bf16 v[56:59], v[156:159], v[180:183], v[56:59]
	v_mfma_f32_16x16x32_bf16 v[44:47], v[144:147], v[188:191], v[44:47]
	v_mfma_f32_16x16x32_bf16 v[40:43], v[156:159], v[188:191], v[40:43]
	v_mfma_f32_16x16x32_bf16 v[28:31], v[144:147], v[196:199], v[28:31]
	v_mfma_f32_16x16x32_bf16 v[24:27], v[156:159], v[196:199], v[24:27]
	v_mfma_f32_16x16x32_bf16 v[12:15], v[144:147], v[204:207], v[12:15]
	v_mfma_f32_16x16x32_bf16 v[8:11], v[156:159], v[204:207], v[8:11]
	v_mfma_f32_16x16x32_bf16 v[60:63], v[152:155], v[184:187], v[60:63]
	v_mfma_f32_16x16x32_bf16 v[56:59], v[160:163], v[184:187], v[56:59]
	v_mfma_f32_16x16x32_bf16 v[44:47], v[152:155], v[192:195], v[44:47]
	v_mfma_f32_16x16x32_bf16 v[40:43], v[160:163], v[192:195], v[40:43]
	v_mfma_f32_16x16x32_bf16 v[28:31], v[152:155], v[200:203], v[28:31]
	v_mfma_f32_16x16x32_bf16 v[24:27], v[160:163], v[200:203], v[24:27]
	v_mfma_f32_16x16x32_bf16 v[12:15], v[152:155], v[208:211], v[12:15]
	v_mfma_f32_16x16x32_bf16 v[8:11], v[160:163], v[208:211], v[8:11]
	v_mfma_f32_16x16x32_bf16 v[52:55], v[164:167], v[180:183], v[52:55]
	v_mfma_f32_16x16x32_bf16 v[48:51], v[172:175], v[180:183], v[48:51]
	v_mfma_f32_16x16x32_bf16 v[36:39], v[164:167], v[188:191], v[36:39]
	v_mfma_f32_16x16x32_bf16 v[32:35], v[172:175], v[188:191], v[32:35]
	v_mfma_f32_16x16x32_bf16 v[20:23], v[164:167], v[196:199], v[20:23]
	v_mfma_f32_16x16x32_bf16 v[16:19], v[172:175], v[196:199], v[16:19]
	v_mfma_f32_16x16x32_bf16 v[4:7], v[164:167], v[204:207], v[4:7]
	v_mfma_f32_16x16x32_bf16 v[0:3], v[172:175], v[204:207], v[0:3]
	v_mfma_f32_16x16x32_bf16 v[52:55], v[168:171], v[184:187], v[52:55]
	v_mfma_f32_16x16x32_bf16 v[48:51], v[176:179], v[184:187], v[48:51]
	v_mfma_f32_16x16x32_bf16 v[36:39], v[168:171], v[192:195], v[36:39]
	v_mfma_f32_16x16x32_bf16 v[32:35], v[176:179], v[192:195], v[32:35]
	v_mfma_f32_16x16x32_bf16 v[20:23], v[168:171], v[200:203], v[20:23]
	v_mfma_f32_16x16x32_bf16 v[16:19], v[176:179], v[200:203], v[16:19]
	v_mfma_f32_16x16x32_bf16 v[4:7], v[168:171], v[208:211], v[4:7]
	v_mfma_f32_16x16x32_bf16 v[0:3], v[176:179], v[208:211], v[0:3]
	s_setprio 0
	s_barrier
	s_add_i32 s55, s55, 2
	s_add_u32 s53, s53, 0x100
	s_addc_u32 s54, s54, 0
	s_add_u32 s24, s24, 0x100
	s_addc_u32 s25, s25, 0
	s_cmp_gt_u32 s55, 29
	s_cbranch_scc0 .LBB0_418
	s_and_b64 vcc, exec, s[12:13]
	s_cbranch_vccz .LBB0_421
	s_barrier

; #define PG8_STAGE(bufoff, gbase, voff) do { _Pragma("unroll") for (int _i = 0; _i < 2; ++_i) \
;         __builtin_amdgcn_global_load_lds((const unsigned*)((const char*)(gbase) + (voff)[_i]), (PG8_LAS unsigned*)(lds + (bufoff) + ldsw + _i * 8192), 16, 0, 0); } while (0)
; #define PG8_LDA(dst, b, h) do { _Pragma("unroll") for (int m = 0; m < 4; ++m) _Pragma("unroll") for (int k = 0; k < 2; ++k) dst[m][k] = *(const PG8_LAS bf16x8*)(lds + PG8_SA(b, h) + aoff + m * 2048 + k * 1024); } while (0)
; #define PG8_LDB(dst, b, h) do { _Pragma("unroll") for (int n = 0; n < 2; ++n) _Pragma("unroll") for (int k = 0; k < 2; ++k) dst[n][k] = *(const PG8_LAS bf16x8*)(lds + PG8_SB(b, h) + boff + n * 2048 + k * 1024); } while (0)
; #define PG8_MMA(ai, bj, At, Bt) do { __builtin_amdgcn_s_setprio(1); _Pragma("unroll") for (int m = 0; m < 4; ++m) _Pragma("unroll") for (int n = 0; n < 2; ++n) _Pragma("unroll") for (int k = 0; k < 2; ++k) \
;         acc[ai][bj][m][n] = __builtin_amdgcn_mfma_f32_16x16x32_bf16(Bt[n][k], At[m][k], acc[ai][bj][m][n], 0, 0, 0); __builtin_amdgcn_s_setprio(0); } while (0)
; #define PG8_WAIT_V(n) asm volatile("s_waitcnt vmcnt(" #n ")" ::: "memory")
; #define PG8_WAIT_L(n) asm volatile("s_waitcnt lgkmcnt(" #n ")" ::: "memory")
; #define PG8_BAR __builtin_amdgcn_s_barrier()
; #define PG8_SCHED __builtin_amdgcn_sched_barrier(0)
; template <class Epi, class Sched, bool ALIGN_EPI = false, bool SP2 = false>
; __device__ __forceinline__ void gemm_phase(PG8_LAS unsigned char* lds, const Gemm g, const Sched& S, const Epi& E, const int wid) {
;     ...
;         for (int t = 0; t < nt; t += 2) {
;             const bool last = (t == nt - 2);
;             const char* a1 = cA + (size_t)(t + 1) * kstep;
;             const char* a2 = last ? nA : cA + (size_t)(t + 2) * kstep; const char* b2 = last ? nB : cB + (size_t)(t + 2) * kstep;
;             const char* a3 = a2 + kstep; const char* b3 = b2 + kstep;
;             if constexpr (SP2) {
;             PG8_LDB(B0, 0, 0); PG8_LDB(B1, 0, 1); PG8_SCHED; PG8_LDA(At, 0, 0); PG8_STAGE(PG8_SA(1, 1), a1 + hsA, voffA);
;             PG8_WAIT_V(8); PG8_WAIT_L(0); PG8_BAR; PG8_MMA(0, 0, At, B0); PG8_MMA(0, 1, At, B1); PG8_BAR; PG8_SCHED;
;             PG8_LDA(At, 0, 1); PG8_STAGE(PG8_SB(0, 0), b2, voffB); PG8_STAGE(PG8_SB(0, 1), b2 + hsB, voffB); PG8_STAGE(PG8_SA(0, 0), a2, voffA);
.LBB0_497:
	ds_read_b128 v[64:67], v197
	ds_read_b128 v[72:75], v197 offset:1024
	ds_read_b128 v[80:83], v197 offset:2048
	ds_read_b128 v[84:87], v197 offset:3072
	ds_read_b128 v[88:91], v198
	ds_read_b128 v[92:95], v198 offset:1024
	ds_read_b128 v[100:103], v198 offset:2048
	ds_read_b128 v[104:107], v198 offset:3072
	s_add_u32 s4, s30, 0x100
	s_addc_u32 s5, s31, 0
	s_cmpk_eq_i32 s61, 0x54
	s_cselect_b32 s37, s27, s5
	s_cselect_b32 s36, s26, s4
	s_cselect_b32 s35, s29, s60
	s_cselect_b32 s34, s28, s59
	v_lshl_add_u64 v[210:211], s[30:31], 0, v[182:183]
	s_add_i32 m0, s41, 0xc000
	ds_read_b128 v[160:163], v199
	ds_read_b128 v[164:167], v199 offset:1024
	ds_read_b128 v[168:171], v199 offset:2048
	ds_read_b128 v[172:175], v199 offset:3072
	ds_read_b128 v[188:191], v199 offset:4096
	ds_read_b128 v[192:195], v199 offset:5120
	ds_read_b128 v[202:205], v199 offset:6144
	ds_read_b128 v[206:209], v199 offset:7168
	global_load_lds_dwordx4 v[210:211], off
	v_lshl_add_u64 v[210:211], s[30:31], 0, v[180:181]
	s_add_i32 m0, s41, 0xe000
	s_nop 0
	global_load_lds_dwordx4 v[210:211], off
	s_waitcnt vmcnt(8)
	s_waitcnt lgkmcnt(0)
	s_barrier
	s_setprio 1
	s_waitcnt lgkmcnt(0)
	v_mfma_f32_16x16x32_bf16 v[156:159], v[64:67], v[160:163], v[156:159]
	v_mfma_f32_16x16x32_bf16 v[152:155], v[80:83], v[160:163], v[152:155]
	v_mfma_f32_16x16x32_bf16 v[140:143], v[64:67], v[168:171], v[140:143]
	v_mfma_f32_16x16x32_bf16 v[136:139], v[80:83], v[168:171], v[136:139]
	v_mfma_f32_16x16x32_bf16 v[124:127], v[64:67], v[188:191], v[124:127]
	v_mfma_f32_16x16x32_bf16 v[120:123], v[80:83], v[188:191], v[120:123]
	v_mfma_f32_16x16x32_bf16 v[108:111], v[64:67], v[202:205], v[108:111]
	v_mfma_f32_16x16x32_bf16 v[96:99], v[80:83], v[202:205], v[96:99]
	v_mfma_f32_16x16x32_bf16 v[156:159], v[72:75], v[164:167], v[156:159]
	v_mfma_f32_16x16x32_bf16 v[152:155], v[84:87], v[164:167], v[152:155]
	v_mfma_f32_16x16x32_bf16 v[140:143], v[72:75], v[172:175], v[140:143]
	v_mfma_f32_16x16x32_bf16 v[136:139], v[84:87], v[172:175], v[136:139]
	v_mfma_f32_16x16x32_bf16 v[124:127], v[72:75], v[192:195], v[124:127]
	v_mfma_f32_16x16x32_bf16 v[120:123], v[84:87], v[192:195], v[120:123]
	v_mfma_f32_16x16x32_bf16 v[108:111], v[72:75], v[206:209], v[108:111]
	v_mfma_f32_16x16x32_bf16 v[96:99], v[84:87], v[206:209], v[96:99]
	v_mfma_f32_16x16x32_bf16 v[148:151], v[88:91], v[160:163], v[148:151]
	v_mfma_f32_16x16x32_bf16 v[144:147], v[100:103], v[160:163], v[144:147]
	v_mfma_f32_16x16x32_bf16 v[132:135], v[88:91], v[168:171], v[132:135]
	v_mfma_f32_16x16x32_bf16 v[128:131], v[100:103], v[168:171], v[128:131]
	v_mfma_f32_16x16x32_bf16 v[116:119], v[88:91], v[188:191], v[116:119]
	v_mfma_f32_16x16x32_bf16 v[112:115], v[100:103], v[188:191], v[112:115]
	v_mfma_f32_16x16x32_bf16 v[76:79], v[88:91], v[202:205], v[76:79]
	v_mfma_f32_16x16x32_bf16 v[68:71], v[100:103], v[202:205], v[68:71]
	v_mfma_f32_16x16x32_bf16 v[148:151], v[92:95], v[164:167], v[148:151]
	v_mfma_f32_16x16x32_bf16 v[144:147], v[104:107], v[164:167], v[144:147]
	v_mfma_f32_16x16x32_bf16 v[132:135], v[92:95], v[172:175], v[132:135]
	v_mfma_f32_16x16x32_bf16 v[128:131], v[104:107], v[172:175], v[128:131]
	v_mfma_f32_16x16x32_bf16 v[116:119], v[92:95], v[192:195], v[116:119]
	v_mfma_f32_16x16x32_bf16 v[112:115], v[104:107], v[192:195], v[112:115]
	v_mfma_f32_16x16x32_bf16 v[76:79], v[92:95], v[206:209], v[76:79]
	v_mfma_f32_16x16x32_bf16 v[68:71], v[104:107], v[206:209], v[68:71]
	s_setprio 0
	s_barrier
	s_add_i32 s30, s53, s40
	v_lshl_add_u64 v[210:211], s[34:35], 0, v[176:177]
	s_mov_b32 m0, s30
	ds_read_b128 v[160:163], v199 offset:16384
	ds_read_b128 v[164:167], v199 offset:17408
	ds_read_b128 v[168:171], v199 offset:18432
	ds_read_b128 v[172:175], v199 offset:19456
	ds_read_b128 v[188:191], v199 offset:20480
	ds_read_b128 v[192:195], v199 offset:21504
	ds_read_b128 v[202:205], v199 offset:22528
	ds_read_b128 v[206:209], v199 offset:23552
	global_load_lds_dwordx4 v[210:211], off
	s_add_i32 m0, s30, 0x2000
	s_add_u32 s30, s34, 0x160000
	v_lshl_add_u64 v[212:213], s[34:35], 0, v[178:179]
	s_addc_u32 s31, s35, 0
	s_add_i32 s62, s54, s40
	global_load_lds_dwordx4 v[212:213], off
	v_lshl_add_u64 v[214:215], s[30:31], 0, v[176:177]
	s_mov_b32 m0, s62
	v_lshl_add_u64 v[216:217], s[36:37], 0, v[178:179]
	global_load_lds_dwordx4 v[214:215], off
	v_lshl_add_u64 v[214:215], s[30:31], 0, v[178:179]
	s_add_i32 m0, s62, 0x2000
	s_nop 0
	global_load_lds_dwordx4 v[214:215], off
	v_lshl_add_u64 v[214:215], s[36:37], 0, v[176:177]
	s_mov_b32 m0, s41
	s_nop 0
	global_load_lds_dwordx4 v[214:215], off
	s_mov_b32 m0, s42
	s_nop 0
	global_load_lds_dwordx4 v[216:217], off
	s_waitcnt vmcnt(8)
	s_waitcnt lgkmcnt(0)
	s_barrier
; #define PG8_STAGE(bufoff, gbase, voff) do { _Pragma("unroll") for (int _i = 0; _i < 2; ++_i) \
;         __builtin_amdgcn_global_load_lds((const unsigned*)((const char*)(gbase) + (voff)[_i]), (PG8_LAS unsigned*)(lds + (bufoff) + ldsw + _i * 8192), 16, 0, 0); } while (0)
; #define PG8_LDA(dst, b, h) do { _Pragma("unroll") for (int m = 0; m < 4; ++m) _Pragma("unroll") for (int k = 0; k < 2; ++k) dst[m][k] = *(const PG8_LAS bf16x8*)(lds + PG8_SA(b, h) + aoff + m * 2048 + k * 1024); } while (0)
; #define PG8_LDB(dst, b, h) do { _Pragma("unroll") for (int n = 0; n < 2; ++n) _Pragma("unroll") for (int k = 0; k < 2; ++k) dst[n][k] = *(const PG8_LAS bf16x8*)(lds + PG8_SB(b, h) + boff + n * 2048 + k * 1024); } while (0)
; #define PG8_MMA(ai, bj, At, Bt) do { __builtin_amdgcn_s_setprio(1); _Pragma("unroll") for (int m = 0; m < 4; ++m) _Pragma("unroll") for (int n = 0; n < 2; ++n) _Pragma("unroll") for (int k = 0; k < 2; ++k) \
;         acc[ai][bj][m][n] = __builtin_amdgcn_mfma_f32_16x16x32_bf16(Bt[n][k], At[m][k], acc[ai][bj][m][n], 0, 0, 0); __builtin_amdgcn_s_setprio(0); } while (0)
; #define PG8_WAIT_V(n) asm volatile("s_waitcnt vmcnt(" #n ")" ::: "memory")
; #define PG8_WAIT_L(n) asm volatile("s_waitcnt lgkmcnt(" #n ")" ::: "memory")
; #define PG8_BAR __builtin_amdgcn_s_barrier()
; #define PG8_SCHED __builtin_amdgcn_sched_barrier(0)
; template <class Epi, class Sched, bool ALIGN_EPI = false, bool SP2 = false>
; __device__ __forceinline__ void gemm_phase(PG8_LAS unsigned char* lds, const Gemm g, const Sched& S, const Epi& E, const int wid) {
;     ...
;             PG8_WAIT_V(8); PG8_WAIT_L(0); PG8_BAR; PG8_MMA(1, 0, At, B0); PG8_MMA(1, 1, At, B1); PG8_BAR; PG8_SCHED;
;             PG8_LDB(B0, 1, 0); PG8_LDB(B1, 1, 1); PG8_SCHED; PG8_LDA(At, 1, 0); PG8_STAGE(PG8_SA(0, 1), a2 + hsA, voffA);
;             PG8_WAIT_V(8); PG8_WAIT_L(0); PG8_BAR; PG8_MMA(0, 0, At, B0); PG8_MMA(0, 1, At, B1); PG8_BAR; PG8_SCHED;
	s_setprio 1
	s_waitcnt lgkmcnt(0)
	v_mfma_f32_16x16x32_bf16 v[60:63], v[64:67], v[160:163], v[60:63]
	v_mfma_f32_16x16x32_bf16 v[56:59], v[80:83], v[160:163], v[56:59]
	v_mfma_f32_16x16x32_bf16 v[44:47], v[64:67], v[168:171], v[44:47]
	v_mfma_f32_16x16x32_bf16 v[40:43], v[80:83], v[168:171], v[40:43]
	v_mfma_f32_16x16x32_bf16 v[28:31], v[64:67], v[188:191], v[28:31]
	v_mfma_f32_16x16x32_bf16 v[24:27], v[80:83], v[188:191], v[24:27]
	v_mfma_f32_16x16x32_bf16 v[12:15], v[64:67], v[202:205], v[12:15]
	v_mfma_f32_16x16x32_bf16 v[8:11], v[80:83], v[202:205], v[8:11]
	v_mfma_f32_16x16x32_bf16 v[60:63], v[72:75], v[164:167], v[60:63]
	v_mfma_f32_16x16x32_bf16 v[56:59], v[84:87], v[164:167], v[56:59]
	v_mfma_f32_16x16x32_bf16 v[44:47], v[72:75], v[172:175], v[44:47]
	v_mfma_f32_16x16x32_bf16 v[40:43], v[84:87], v[172:175], v[40:43]
	v_mfma_f32_16x16x32_bf16 v[28:31], v[72:75], v[192:195], v[28:31]
	v_mfma_f32_16x16x32_bf16 v[24:27], v[84:87], v[192:195], v[24:27]
	v_mfma_f32_16x16x32_bf16 v[12:15], v[72:75], v[206:209], v[12:15]
	v_mfma_f32_16x16x32_bf16 v[8:11], v[84:87], v[206:209], v[8:11]
	v_mfma_f32_16x16x32_bf16 v[52:55], v[88:91], v[160:163], v[52:55]
	v_mfma_f32_16x16x32_bf16 v[48:51], v[100:103], v[160:163], v[48:51]
	v_mfma_f32_16x16x32_bf16 v[36:39], v[88:91], v[168:171], v[36:39]
	v_mfma_f32_16x16x32_bf16 v[32:35], v[100:103], v[168:171], v[32:35]
	v_mfma_f32_16x16x32_bf16 v[20:23], v[88:91], v[188:191], v[20:23]
	v_mfma_f32_16x16x32_bf16 v[16:19], v[100:103], v[188:191], v[16:19]
	v_mfma_f32_16x16x32_bf16 v[4:7], v[88:91], v[202:205], v[4:7]
	v_mfma_f32_16x16x32_bf16 v[0:3], v[100:103], v[202:205], v[0:3]
	v_mfma_f32_16x16x32_bf16 v[52:55], v[92:95], v[164:167], v[52:55]
	v_mfma_f32_16x16x32_bf16 v[48:51], v[104:107], v[164:167], v[48:51]
	v_mfma_f32_16x16x32_bf16 v[36:39], v[92:95], v[172:175], v[36:39]
	v_mfma_f32_16x16x32_bf16 v[32:35], v[104:107], v[172:175], v[32:35]
	v_mfma_f32_16x16x32_bf16 v[20:23], v[92:95], v[192:195], v[20:23]
	v_mfma_f32_16x16x32_bf16 v[16:19], v[104:107], v[192:195], v[16:19]
	v_mfma_f32_16x16x32_bf16 v[4:7], v[92:95], v[206:209], v[4:7]
	v_mfma_f32_16x16x32_bf16 v[0:3], v[104:107], v[206:209], v[0:3]
	s_setprio 0
	s_barrier
	s_add_i32 s62, 0, 0x18000
	s_add_i32 s63, 0, 0x1c000
	v_add_u32_e32 v84, s62, v196
	v_add_u32_e32 v104, s63, v196
	ds_read_b128 v[64:67], v84
	ds_read_b128 v[72:75], v84 offset:1024
	ds_read_b128 v[80:83], v84 offset:2048
	ds_read_b128 v[84:87], v84 offset:3072
	ds_read_b128 v[88:91], v104
	ds_read_b128 v[92:95], v104 offset:1024
	ds_read_b128 v[100:103], v104 offset:2048
	ds_read_b128 v[104:107], v104 offset:3072
	s_add_u32 s30, s36, 0x160000
	s_addc_u32 s31, s37, 0
	s_mov_b32 m0, s43
	v_lshl_add_u64 v[218:219], s[30:31], 0, v[176:177]
	ds_read_b128 v[160:163], v199 offset:32768
	ds_read_b128 v[164:167], v199 offset:33792
	ds_read_b128 v[168:171], v199 offset:34816
	ds_read_b128 v[172:175], v199 offset:35840
	ds_read_b128 v[188:191], v199 offset:36864
	ds_read_b128 v[192:195], v199 offset:37888
	ds_read_b128 v[202:205], v199 offset:38912
	ds_read_b128 v[206:209], v199 offset:39936
	global_load_lds_dwordx4 v[218:219], off
	v_lshl_add_u64 v[218:219], s[30:31], 0, v[178:179]
	s_mov_b32 m0, s44
	s_nop 0
	global_load_lds_dwordx4 v[218:219], off
	s_waitcnt vmcnt(8)
	s_waitcnt lgkmcnt(0)
	s_barrier
	s_setprio 1
	s_waitcnt lgkmcnt(0)
	v_mfma_f32_16x16x32_bf16 v[156:159], v[64:67], v[160:163], v[156:159]
	v_mfma_f32_16x16x32_bf16 v[152:155], v[80:83], v[160:163], v[152:155]
	v_mfma_f32_16x16x32_bf16 v[140:143], v[64:67], v[168:171], v[140:143]
	v_mfma_f32_16x16x32_bf16 v[136:139], v[80:83], v[168:171], v[136:139]
	v_mfma_f32_16x16x32_bf16 v[124:127], v[64:67], v[188:191], v[124:127]
	v_mfma_f32_16x16x32_bf16 v[120:123], v[80:83], v[188:191], v[120:123]
	v_mfma_f32_16x16x32_bf16 v[108:111], v[64:67], v[202:205], v[108:111]
	v_mfma_f32_16x16x32_bf16 v[96:99], v[80:83], v[202:205], v[96:99]
	v_mfma_f32_16x16x32_bf16 v[156:159], v[72:75], v[164:167], v[156:159]
	v_mfma_f32_16x16x32_bf16 v[152:155], v[84:87], v[164:167], v[152:155]
	v_mfma_f32_16x16x32_bf16 v[140:143], v[72:75], v[172:175], v[140:143]
	v_mfma_f32_16x16x32_bf16 v[136:139], v[84:87], v[172:175], v[136:139]
	v_mfma_f32_16x16x32_bf16 v[124:127], v[72:75], v[192:195], v[124:127]
	v_mfma_f32_16x16x32_bf16 v[120:123], v[84:87], v[192:195], v[120:123]
	v_mfma_f32_16x16x32_bf16 v[108:111], v[72:75], v[206:209], v[108:111]
	v_mfma_f32_16x16x32_bf16 v[96:99], v[84:87], v[206:209], v[96:99]
	v_mfma_f32_16x16x32_bf16 v[148:151], v[88:91], v[160:163], v[148:151]
	v_mfma_f32_16x16x32_bf16 v[144:147], v[100:103], v[160:163], v[144:147]
	v_mfma_f32_16x16x32_bf16 v[132:135], v[88:91], v[168:171], v[132:135]
	v_mfma_f32_16x16x32_bf16 v[128:131], v[100:103], v[168:171], v[128:131]
	v_mfma_f32_16x16x32_bf16 v[116:119], v[88:91], v[188:191], v[116:119]
	v_mfma_f32_16x16x32_bf16 v[112:115], v[100:103], v[188:191], v[112:115]
	v_mfma_f32_16x16x32_bf16 v[76:79], v[88:91], v[202:205], v[76:79]
	v_mfma_f32_16x16x32_bf16 v[68:71], v[100:103], v[202:205], v[68:71]
	v_mfma_f32_16x16x32_bf16 v[148:151], v[92:95], v[164:167], v[148:151]
	v_mfma_f32_16x16x32_bf16 v[144:147], v[104:107], v[164:167], v[144:147]
	v_mfma_f32_16x16x32_bf16 v[132:135], v[92:95], v[172:175], v[132:135]
	v_mfma_f32_16x16x32_bf16 v[128:131], v[104:107], v[172:175], v[128:131]
	v_mfma_f32_16x16x32_bf16 v[116:119], v[92:95], v[192:195], v[116:119]
	v_mfma_f32_16x16x32_bf16 v[112:115], v[104:107], v[192:195], v[112:115]
	v_mfma_f32_16x16x32_bf16 v[76:79], v[92:95], v[206:209], v[76:79]
	v_mfma_f32_16x16x32_bf16 v[68:71], v[104:107], v[206:209], v[68:71]
	s_setprio 0
	s_barrier
; #define PG8_STAGE(bufoff, gbase, voff) do { _Pragma("unroll") for (int _i = 0; _i < 2; ++_i) \
;         __builtin_amdgcn_global_load_lds((const unsigned*)((const char*)(gbase) + (voff)[_i]), (PG8_LAS unsigned*)(lds + (bufoff) + ldsw + _i * 8192), 16, 0, 0); } while (0)
; #define PG8_LDA(dst, b, h) do { _Pragma("unroll") for (int m = 0; m < 4; ++m) _Pragma("unroll") for (int k = 0; k < 2; ++k) dst[m][k] = *(const PG8_LAS bf16x8*)(lds + PG8_SA(b, h) + aoff + m * 2048 + k * 1024); } while (0)
; #define PG8_MMA(ai, bj, At, Bt) do { __builtin_amdgcn_s_setprio(1); _Pragma("unroll") for (int m = 0; m < 4; ++m) _Pragma("unroll") for (int n = 0; n < 2; ++n) _Pragma("unroll") for (int k = 0; k < 2; ++k) \
;         acc[ai][bj][m][n] = __builtin_amdgcn_mfma_f32_16x16x32_bf16(Bt[n][k], At[m][k], acc[ai][bj][m][n], 0, 0, 0); __builtin_amdgcn_s_setprio(0); } while (0)
; #define PG8_WAIT_V(n) asm volatile("s_waitcnt vmcnt(" #n ")" ::: "memory")
; #define PG8_WAIT_L(n) asm volatile("s_waitcnt lgkmcnt(" #n ")" ::: "memory")
; #define PG8_BAR __builtin_amdgcn_s_barrier()
; #define PG8_SCHED __builtin_amdgcn_sched_barrier(0)
; template <class Epi, class Sched, bool ALIGN_EPI = false, bool SP2 = false>
; __device__ __forceinline__ void gemm_phase(PG8_LAS unsigned char* lds, const Gemm g, const Sched& S, const Epi& E, const int wid) {
;     ...
;             PG8_LDA(At, 1, 1); PG8_STAGE(PG8_SB(1, 0), b3, voffB); PG8_STAGE(PG8_SB(1, 1), b3 + hsB, voffB); PG8_STAGE(PG8_SA(1, 0), a3, voffA);
;             PG8_WAIT_V(8); PG8_WAIT_L(0); PG8_BAR; PG8_MMA(1, 0, At, B0); PG8_MMA(1, 1, At, B1); PG8_BAR; PG8_SCHED;
;     ...
;         if constexpr (ALIGN_EPI) { if (wr == 0) PG8_BAR; }
	s_add_i32 s30, s62, s40
	v_lshl_add_u64 v[210:211], v[210:211], 0, s[22:23]
	s_mov_b32 m0, s30
	ds_read_b128 v[160:163], v199 offset:49152
	ds_read_b128 v[164:167], v199 offset:50176
	ds_read_b128 v[168:171], v199 offset:51200
	ds_read_b128 v[172:175], v199 offset:52224
	ds_read_b128 v[188:191], v199 offset:53248
	ds_read_b128 v[192:195], v199 offset:54272
	ds_read_b128 v[202:205], v199 offset:55296
	ds_read_b128 v[206:209], v199 offset:56320
	global_load_lds_dwordx4 v[210:211], off
	s_add_i32 m0, s30, 0x2000
	s_add_u32 s30, s34, 0x160080
	v_lshl_add_u64 v[210:211], v[212:213], 0, s[22:23]
	s_addc_u32 s31, s35, 0
	s_add_i32 s34, s63, s40
	global_load_lds_dwordx4 v[210:211], off
	v_lshl_add_u64 v[210:211], s[30:31], 0, v[176:177]
	s_mov_b32 m0, s34
	s_nop 0
	global_load_lds_dwordx4 v[210:211], off
	v_lshl_add_u64 v[210:211], s[30:31], 0, v[178:179]
	s_add_i32 m0, s34, 0x2000
	s_nop 0
	global_load_lds_dwordx4 v[210:211], off
	v_lshl_add_u64 v[210:211], v[214:215], 0, s[22:23]
	s_mov_b32 m0, s48
	s_nop 0
	global_load_lds_dwordx4 v[210:211], off
	v_lshl_add_u64 v[210:211], v[216:217], 0, s[22:23]
	s_mov_b32 m0, s49
	s_nop 0
	global_load_lds_dwordx4 v[210:211], off
	s_waitcnt vmcnt(8)
	s_waitcnt lgkmcnt(0)
	s_barrier
	s_setprio 1
	s_waitcnt lgkmcnt(0)
	v_mfma_f32_16x16x32_bf16 v[60:63], v[64:67], v[160:163], v[60:63]
	v_mfma_f32_16x16x32_bf16 v[56:59], v[80:83], v[160:163], v[56:59]
	v_mfma_f32_16x16x32_bf16 v[44:47], v[64:67], v[168:171], v[44:47]
	v_mfma_f32_16x16x32_bf16 v[40:43], v[80:83], v[168:171], v[40:43]
	v_mfma_f32_16x16x32_bf16 v[28:31], v[64:67], v[188:191], v[28:31]
	v_mfma_f32_16x16x32_bf16 v[24:27], v[80:83], v[188:191], v[24:27]
	v_mfma_f32_16x16x32_bf16 v[12:15], v[64:67], v[202:205], v[12:15]
	v_mfma_f32_16x16x32_bf16 v[8:11], v[80:83], v[202:205], v[8:11]
	v_mfma_f32_16x16x32_bf16 v[60:63], v[72:75], v[164:167], v[60:63]
	v_mfma_f32_16x16x32_bf16 v[56:59], v[84:87], v[164:167], v[56:59]
	v_mfma_f32_16x16x32_bf16 v[44:47], v[72:75], v[172:175], v[44:47]
	v_mfma_f32_16x16x32_bf16 v[40:43], v[84:87], v[172:175], v[40:43]
	v_mfma_f32_16x16x32_bf16 v[28:31], v[72:75], v[192:195], v[28:31]
	v_mfma_f32_16x16x32_bf16 v[24:27], v[84:87], v[192:195], v[24:27]
	v_mfma_f32_16x16x32_bf16 v[12:15], v[72:75], v[206:209], v[12:15]
	v_mfma_f32_16x16x32_bf16 v[8:11], v[84:87], v[206:209], v[8:11]
	v_mfma_f32_16x16x32_bf16 v[52:55], v[88:91], v[160:163], v[52:55]
	v_mfma_f32_16x16x32_bf16 v[48:51], v[100:103], v[160:163], v[48:51]
	v_mfma_f32_16x16x32_bf16 v[36:39], v[88:91], v[168:171], v[36:39]
	v_mfma_f32_16x16x32_bf16 v[32:35], v[100:103], v[168:171], v[32:35]
	v_mfma_f32_16x16x32_bf16 v[20:23], v[88:91], v[188:191], v[20:23]
	v_mfma_f32_16x16x32_bf16 v[16:19], v[100:103], v[188:191], v[16:19]
	v_mfma_f32_16x16x32_bf16 v[4:7], v[88:91], v[202:205], v[4:7]
	v_mfma_f32_16x16x32_bf16 v[0:3], v[100:103], v[202:205], v[0:3]
	v_mfma_f32_16x16x32_bf16 v[52:55], v[92:95], v[164:167], v[52:55]
	v_mfma_f32_16x16x32_bf16 v[48:51], v[104:107], v[164:167], v[48:51]
	v_mfma_f32_16x16x32_bf16 v[36:39], v[92:95], v[172:175], v[36:39]
	v_mfma_f32_16x16x32_bf16 v[32:35], v[104:107], v[172:175], v[32:35]
	v_mfma_f32_16x16x32_bf16 v[20:23], v[92:95], v[192:195], v[20:23]
	v_mfma_f32_16x16x32_bf16 v[16:19], v[104:107], v[192:195], v[16:19]
	v_mfma_f32_16x16x32_bf16 v[4:7], v[92:95], v[206:209], v[4:7]
	v_mfma_f32_16x16x32_bf16 v[0:3], v[104:107], v[206:209], v[0:3]
	s_setprio 0
	s_barrier
	s_add_i32 s61, s61, 2
	s_add_u32 s59, s59, 0x100
	s_addc_u32 s60, s60, 0
	s_cmpk_gt_u32 s61, 0x55
	s_mov_b64 s[30:31], s[4:5]
	s_cbranch_scc0 .LBB0_497
	s_and_b64 vcc, exec, s[24:25]
	s_cbranch_vccz .LBB0_500
	s_barrier

; #define PG8_STAGE(bufoff, gbase, voff) do { _Pragma("unroll") for (int _i = 0; _i < 2; ++_i) \
;         __builtin_amdgcn_global_load_lds((const unsigned*)((const char*)(gbase) + (voff)[_i]), (PG8_LAS unsigned*)(lds + (bufoff) + ldsw + _i * 8192), 16, 0, 0); } while (0)
; #define PG8_LDA(dst, b, h) do { _Pragma("unroll") for (int m = 0; m < 4; ++m) _Pragma("unroll") for (int k = 0; k < 2; ++k) dst[m][k] = *(const PG8_LAS bf16x8*)(lds + PG8_SA(b, h) + aoff + m * 2048 + k * 1024); } while (0)
; #define PG8_LDB(dst, b, h) do { _Pragma("unroll") for (int n = 0; n < 2; ++n) _Pragma("unroll") for (int k = 0; k < 2; ++k) dst[n][k] = *(const PG8_LAS bf16x8*)(lds + PG8_SB(b, h) + boff + n * 2048 + k * 1024); } while (0)
; #define PG8_MMA(ai, bj, At, Bt) do { __builtin_amdgcn_s_setprio(1); _Pragma("unroll") for (int m = 0; m < 4; ++m) _Pragma("unroll") for (int n = 0; n < 2; ++n) _Pragma("unroll") for (int k = 0; k < 2; ++k) \
;         acc[ai][bj][m][n] = __builtin_amdgcn_mfma_f32_16x16x32_bf16(Bt[n][k], At[m][k], acc[ai][bj][m][n], 0, 0, 0); __builtin_amdgcn_s_setprio(0); } while (0)
; #define PG8_WAIT_V(n) asm volatile("s_waitcnt vmcnt(" #n ")" ::: "memory")
; #define PG8_WAIT_L(n) asm volatile("s_waitcnt lgkmcnt(" #n ")" ::: "memory")
; #define PG8_BAR __builtin_amdgcn_s_barrier()
; #define PG8_SCHED __builtin_amdgcn_sched_barrier(0)
; template <class Epi, class Sched, bool ALIGN_EPI = false, bool SP2 = false>
; __device__ __forceinline__ void gemm_phase(PG8_LAS unsigned char* lds, const Gemm g, const Sched& S, const Epi& E, const int wid) {
;     ...
;         for (int t = 0; t < nt; t += 2) {
;             const bool last = (t == nt - 2);
;             const char* a1 = cA + (size_t)(t + 1) * kstep;
;             const char* a2 = last ? nA : cA + (size_t)(t + 2) * kstep; const char* b2 = last ? nB : cB + (size_t)(t + 2) * kstep;
;             const char* a3 = a2 + kstep; const char* b3 = b2 + kstep;
;             if constexpr (SP2) {
;             PG8_LDB(B0, 0, 0); PG8_LDB(B1, 0, 1); PG8_SCHED; PG8_LDA(At, 0, 0); PG8_STAGE(PG8_SA(1, 1), a1 + hsA, voffA);
;             PG8_WAIT_V(8); PG8_WAIT_L(0); PG8_BAR; PG8_MMA(0, 0, At, B0); PG8_MMA(0, 1, At, B1); PG8_BAR; PG8_SCHED;
;             PG8_LDA(At, 0, 1); PG8_STAGE(PG8_SB(0, 0), b2, voffB); PG8_STAGE(PG8_SB(0, 1), b2 + hsB, voffB); PG8_STAGE(PG8_SA(0, 0), a2, voffA);
.LBB0_588:
	ds_read_b128 v[128:131], v237
	ds_read_b128 v[132:135], v237 offset:1024
	ds_read_b128 v[136:139], v237 offset:2048
	ds_read_b128 v[140:143], v237 offset:3072
	ds_read_b128 v[144:147], v238
	ds_read_b128 v[148:151], v238 offset:1024
	ds_read_b128 v[152:155], v238 offset:2048
	ds_read_b128 v[156:159], v238 offset:3072
	s_add_u32 s8, s6, 0xfff80080
	s_addc_u32 s9, s7, -1
	s_cmp_eq_u32 s87, 28
	s_cselect_b32 s53, s5, s9
	s_cselect_b32 s52, s47, s8
	s_cselect_b32 s9, s45, s86
	s_cselect_b32 s8, s54, s55
	v_lshl_add_u64 v[210:211], s[6:7], 0, v[180:181]
	s_add_i32 m0, s59, 0xc000
	ds_read_b128 v[160:163], v239
	ds_read_b128 v[164:167], v239 offset:1024
	ds_read_b128 v[186:189], v239 offset:2048
	ds_read_b128 v[190:193], v239 offset:3072
	ds_read_b128 v[194:197], v239 offset:4096
	ds_read_b128 v[198:201], v239 offset:5120
	ds_read_b128 v[202:205], v239 offset:6144
	ds_read_b128 v[206:209], v239 offset:7168
	global_load_lds_dwordx4 v[210:211], off
	v_lshl_add_u64 v[210:211], s[6:7], 0, v[178:179]
	s_add_i32 m0, s59, 0xe000
	s_nop 0
	global_load_lds_dwordx4 v[210:211], off
	s_waitcnt vmcnt(8)
	s_waitcnt lgkmcnt(0)
	s_barrier
	s_setprio 1
	s_waitcnt lgkmcnt(0)
	v_mfma_f32_16x16x32_bf16 v[124:127], v[128:131], v[160:163], v[124:127]
	v_mfma_f32_16x16x32_bf16 v[120:123], v[136:139], v[160:163], v[120:123]
	v_mfma_f32_16x16x32_bf16 v[108:111], v[128:131], v[186:189], v[108:111]
	v_mfma_f32_16x16x32_bf16 v[104:107], v[136:139], v[186:189], v[104:107]
	v_mfma_f32_16x16x32_bf16 v[92:95], v[128:131], v[194:197], v[92:95]
	v_mfma_f32_16x16x32_bf16 v[88:91], v[136:139], v[194:197], v[88:91]
	v_mfma_f32_16x16x32_bf16 v[76:79], v[128:131], v[202:205], v[76:79]
	v_mfma_f32_16x16x32_bf16 v[72:75], v[136:139], v[202:205], v[72:75]
	v_mfma_f32_16x16x32_bf16 v[124:127], v[132:135], v[164:167], v[124:127]
	v_mfma_f32_16x16x32_bf16 v[120:123], v[140:143], v[164:167], v[120:123]
	v_mfma_f32_16x16x32_bf16 v[108:111], v[132:135], v[190:193], v[108:111]
	v_mfma_f32_16x16x32_bf16 v[104:107], v[140:143], v[190:193], v[104:107]
	v_mfma_f32_16x16x32_bf16 v[92:95], v[132:135], v[198:201], v[92:95]
	v_mfma_f32_16x16x32_bf16 v[88:91], v[140:143], v[198:201], v[88:91]
	v_mfma_f32_16x16x32_bf16 v[76:79], v[132:135], v[206:209], v[76:79]
	v_mfma_f32_16x16x32_bf16 v[72:75], v[140:143], v[206:209], v[72:75]
	v_mfma_f32_16x16x32_bf16 v[116:119], v[144:147], v[160:163], v[116:119]
	v_mfma_f32_16x16x32_bf16 v[112:115], v[152:155], v[160:163], v[112:115]
	v_mfma_f32_16x16x32_bf16 v[100:103], v[144:147], v[186:189], v[100:103]
	v_mfma_f32_16x16x32_bf16 v[96:99], v[152:155], v[186:189], v[96:99]
	v_mfma_f32_16x16x32_bf16 v[84:87], v[144:147], v[194:197], v[84:87]
	v_mfma_f32_16x16x32_bf16 v[80:83], v[152:155], v[194:197], v[80:83]
	v_mfma_f32_16x16x32_bf16 v[68:71], v[144:147], v[202:205], v[68:71]
	v_mfma_f32_16x16x32_bf16 v[64:67], v[152:155], v[202:205], v[64:67]
	v_mfma_f32_16x16x32_bf16 v[116:119], v[148:151], v[164:167], v[116:119]
	v_mfma_f32_16x16x32_bf16 v[112:115], v[156:159], v[164:167], v[112:115]
	v_mfma_f32_16x16x32_bf16 v[100:103], v[148:151], v[190:193], v[100:103]
	v_mfma_f32_16x16x32_bf16 v[96:99], v[156:159], v[190:193], v[96:99]
	v_mfma_f32_16x16x32_bf16 v[84:87], v[148:151], v[198:201], v[84:87]
	v_mfma_f32_16x16x32_bf16 v[80:83], v[156:159], v[198:201], v[80:83]
	v_mfma_f32_16x16x32_bf16 v[68:71], v[148:151], v[206:209], v[68:71]
	v_mfma_f32_16x16x32_bf16 v[64:67], v[156:159], v[206:209], v[64:67]
	s_setprio 0
	s_barrier
	s_add_i32 s88, s81, s58
	v_lshl_add_u64 v[210:211], s[8:9], 0, v[170:171]
	s_mov_b32 m0, s88
	ds_read_b128 v[160:163], v239 offset:16384
	ds_read_b128 v[164:167], v239 offset:17408
	ds_read_b128 v[186:189], v239 offset:18432
	ds_read_b128 v[190:193], v239 offset:19456
	ds_read_b128 v[194:197], v239 offset:20480
	ds_read_b128 v[198:201], v239 offset:21504
	ds_read_b128 v[202:205], v239 offset:22528
	ds_read_b128 v[206:209], v239 offset:23552
	global_load_lds_dwordx4 v[210:211], off
	s_add_i32 m0, s88, 0x2000
	s_add_u32 s88, s8, 0x80000
	v_lshl_add_u64 v[212:213], s[8:9], 0, v[174:175]
	s_addc_u32 s89, s9, 0
	s_add_i32 s90, s82, s58
	global_load_lds_dwordx4 v[212:213], off
	v_lshl_add_u64 v[214:215], s[88:89], 0, v[170:171]
	s_mov_b32 m0, s90
	v_lshl_add_u64 v[216:217], s[52:53], 0, v[172:173]
	global_load_lds_dwordx4 v[214:215], off
	v_lshl_add_u64 v[214:215], s[88:89], 0, v[174:175]
	s_add_i32 m0, s90, 0x2000
	s_nop 0
	global_load_lds_dwordx4 v[214:215], off
	v_lshl_add_u64 v[214:215], s[52:53], 0, v[168:169]
	s_mov_b32 m0, s59
	s_nop 0
	global_load_lds_dwordx4 v[214:215], off
	s_mov_b32 m0, s60
	s_nop 0
	global_load_lds_dwordx4 v[216:217], off
	s_waitcnt vmcnt(8)
	s_waitcnt lgkmcnt(0)
	s_barrier
; #define PG8_STAGE(bufoff, gbase, voff) do { _Pragma("unroll") for (int _i = 0; _i < 2; ++_i) \
;         __builtin_amdgcn_global_load_lds((const unsigned*)((const char*)(gbase) + (voff)[_i]), (PG8_LAS unsigned*)(lds + (bufoff) + ldsw + _i * 8192), 16, 0, 0); } while (0)
; #define PG8_LDA(dst, b, h) do { _Pragma("unroll") for (int m = 0; m < 4; ++m) _Pragma("unroll") for (int k = 0; k < 2; ++k) dst[m][k] = *(const PG8_LAS bf16x8*)(lds + PG8_SA(b, h) + aoff + m * 2048 + k * 1024); } while (0)
; #define PG8_LDB(dst, b, h) do { _Pragma("unroll") for (int n = 0; n < 2; ++n) _Pragma("unroll") for (int k = 0; k < 2; ++k) dst[n][k] = *(const PG8_LAS bf16x8*)(lds + PG8_SB(b, h) + boff + n * 2048 + k * 1024); } while (0)
; #define PG8_MMA(ai, bj, At, Bt) do { __builtin_amdgcn_s_setprio(1); _Pragma("unroll") for (int m = 0; m < 4; ++m) _Pragma("unroll") for (int n = 0; n < 2; ++n) _Pragma("unroll") for (int k = 0; k < 2; ++k) \
;         acc[ai][bj][m][n] = __builtin_amdgcn_mfma_f32_16x16x32_bf16(Bt[n][k], At[m][k], acc[ai][bj][m][n], 0, 0, 0); __builtin_amdgcn_s_setprio(0); } while (0)
; #define PG8_WAIT_V(n) asm volatile("s_waitcnt vmcnt(" #n ")" ::: "memory")
; #define PG8_WAIT_L(n) asm volatile("s_waitcnt lgkmcnt(" #n ")" ::: "memory")
; #define PG8_BAR __builtin_amdgcn_s_barrier()
; #define PG8_SCHED __builtin_amdgcn_sched_barrier(0)
; template <class Epi, class Sched, bool ALIGN_EPI = false, bool SP2 = false>
; __device__ __forceinline__ void gemm_phase(PG8_LAS unsigned char* lds, const Gemm g, const Sched& S, const Epi& E, const int wid) {
;     ...
;             PG8_WAIT_V(8); PG8_WAIT_L(0); PG8_BAR; PG8_MMA(1, 0, At, B0); PG8_MMA(1, 1, At, B1); PG8_BAR; PG8_SCHED;
;             PG8_LDB(B0, 1, 0); PG8_LDB(B1, 1, 1); PG8_SCHED; PG8_LDA(At, 1, 0); PG8_STAGE(PG8_SA(0, 1), a2 + hsA, voffA);
;             PG8_WAIT_V(8); PG8_WAIT_L(0); PG8_BAR; PG8_MMA(0, 0, At, B0); PG8_MMA(0, 1, At, B1); PG8_BAR; PG8_SCHED;
	s_setprio 1
	s_waitcnt lgkmcnt(0)
	v_mfma_f32_16x16x32_bf16 v[60:63], v[128:131], v[160:163], v[60:63]
	v_mfma_f32_16x16x32_bf16 v[56:59], v[136:139], v[160:163], v[56:59]
	v_mfma_f32_16x16x32_bf16 v[44:47], v[128:131], v[186:189], v[44:47]
	v_mfma_f32_16x16x32_bf16 v[40:43], v[136:139], v[186:189], v[40:43]
	v_mfma_f32_16x16x32_bf16 v[28:31], v[128:131], v[194:197], v[28:31]
	v_mfma_f32_16x16x32_bf16 v[24:27], v[136:139], v[194:197], v[24:27]
	v_mfma_f32_16x16x32_bf16 v[12:15], v[128:131], v[202:205], v[12:15]
	v_mfma_f32_16x16x32_bf16 v[8:11], v[136:139], v[202:205], v[8:11]
	v_mfma_f32_16x16x32_bf16 v[60:63], v[132:135], v[164:167], v[60:63]
	v_mfma_f32_16x16x32_bf16 v[56:59], v[140:143], v[164:167], v[56:59]
	v_mfma_f32_16x16x32_bf16 v[44:47], v[132:135], v[190:193], v[44:47]
	v_mfma_f32_16x16x32_bf16 v[40:43], v[140:143], v[190:193], v[40:43]
	v_mfma_f32_16x16x32_bf16 v[28:31], v[132:135], v[198:201], v[28:31]
	v_mfma_f32_16x16x32_bf16 v[24:27], v[140:143], v[198:201], v[24:27]
	v_mfma_f32_16x16x32_bf16 v[12:15], v[132:135], v[206:209], v[12:15]
	v_mfma_f32_16x16x32_bf16 v[8:11], v[140:143], v[206:209], v[8:11]
	v_mfma_f32_16x16x32_bf16 v[52:55], v[144:147], v[160:163], v[52:55]
	v_mfma_f32_16x16x32_bf16 v[48:51], v[152:155], v[160:163], v[48:51]
	v_mfma_f32_16x16x32_bf16 v[36:39], v[144:147], v[186:189], v[36:39]
	v_mfma_f32_16x16x32_bf16 v[32:35], v[152:155], v[186:189], v[32:35]
	v_mfma_f32_16x16x32_bf16 v[20:23], v[144:147], v[194:197], v[20:23]
	v_mfma_f32_16x16x32_bf16 v[16:19], v[152:155], v[194:197], v[16:19]
	v_mfma_f32_16x16x32_bf16 v[4:7], v[144:147], v[202:205], v[4:7]
	v_mfma_f32_16x16x32_bf16 v[0:3], v[152:155], v[202:205], v[0:3]
	v_mfma_f32_16x16x32_bf16 v[52:55], v[148:151], v[164:167], v[52:55]
	v_mfma_f32_16x16x32_bf16 v[48:51], v[156:159], v[164:167], v[48:51]
	v_mfma_f32_16x16x32_bf16 v[36:39], v[148:151], v[190:193], v[36:39]
	v_mfma_f32_16x16x32_bf16 v[32:35], v[156:159], v[190:193], v[32:35]
	v_mfma_f32_16x16x32_bf16 v[20:23], v[148:151], v[198:201], v[20:23]
	v_mfma_f32_16x16x32_bf16 v[16:19], v[156:159], v[198:201], v[16:19]
	v_mfma_f32_16x16x32_bf16 v[4:7], v[148:151], v[206:209], v[4:7]
	v_mfma_f32_16x16x32_bf16 v[0:3], v[156:159], v[206:209], v[0:3]
	s_setprio 0
	s_barrier
	s_add_i32 s88, 0, 0x18000
	s_add_i32 s89, 0, 0x1c000
	v_add_u32_e32 v140, s88, v236
	v_add_u32_e32 v156, s89, v236
	ds_read_b128 v[128:131], v140
	ds_read_b128 v[132:135], v140 offset:1024
	ds_read_b128 v[136:139], v140 offset:2048
	ds_read_b128 v[140:143], v140 offset:3072
	ds_read_b128 v[144:147], v156
	ds_read_b128 v[148:151], v156 offset:1024
	ds_read_b128 v[152:155], v156 offset:2048
	ds_read_b128 v[156:159], v156 offset:3072
	s_add_u32 s52, s52, 0x80000
	s_addc_u32 s53, s53, 0
	s_mov_b32 m0, s61
	v_lshl_add_u64 v[218:219], s[52:53], 0, v[168:169]
	ds_read_b128 v[160:163], v239 offset:32768
	ds_read_b128 v[164:167], v239 offset:33792
	ds_read_b128 v[186:189], v239 offset:34816
	ds_read_b128 v[190:193], v239 offset:35840
	ds_read_b128 v[194:197], v239 offset:36864
	ds_read_b128 v[198:201], v239 offset:37888
	ds_read_b128 v[202:205], v239 offset:38912
	ds_read_b128 v[206:209], v239 offset:39936
	global_load_lds_dwordx4 v[218:219], off
	v_lshl_add_u64 v[218:219], s[52:53], 0, v[172:173]
	s_mov_b32 m0, s62
	s_nop 0
	global_load_lds_dwordx4 v[218:219], off
	s_waitcnt vmcnt(8)
	s_waitcnt lgkmcnt(0)
	s_barrier
	s_setprio 1
	s_waitcnt lgkmcnt(0)
	v_mfma_f32_16x16x32_bf16 v[124:127], v[128:131], v[160:163], v[124:127]
	v_mfma_f32_16x16x32_bf16 v[120:123], v[136:139], v[160:163], v[120:123]
	v_mfma_f32_16x16x32_bf16 v[108:111], v[128:131], v[186:189], v[108:111]
	v_mfma_f32_16x16x32_bf16 v[104:107], v[136:139], v[186:189], v[104:107]
	v_mfma_f32_16x16x32_bf16 v[92:95], v[128:131], v[194:197], v[92:95]
	v_mfma_f32_16x16x32_bf16 v[88:91], v[136:139], v[194:197], v[88:91]
	v_mfma_f32_16x16x32_bf16 v[76:79], v[128:131], v[202:205], v[76:79]
	v_mfma_f32_16x16x32_bf16 v[72:75], v[136:139], v[202:205], v[72:75]
	v_mfma_f32_16x16x32_bf16 v[124:127], v[132:135], v[164:167], v[124:127]
	v_mfma_f32_16x16x32_bf16 v[120:123], v[140:143], v[164:167], v[120:123]
	v_mfma_f32_16x16x32_bf16 v[108:111], v[132:135], v[190:193], v[108:111]
	v_mfma_f32_16x16x32_bf16 v[104:107], v[140:143], v[190:193], v[104:107]
	v_mfma_f32_16x16x32_bf16 v[92:95], v[132:135], v[198:201], v[92:95]
	v_mfma_f32_16x16x32_bf16 v[88:91], v[140:143], v[198:201], v[88:91]
	v_mfma_f32_16x16x32_bf16 v[76:79], v[132:135], v[206:209], v[76:79]
	v_mfma_f32_16x16x32_bf16 v[72:75], v[140:143], v[206:209], v[72:75]
	v_mfma_f32_16x16x32_bf16 v[116:119], v[144:147], v[160:163], v[116:119]
	v_mfma_f32_16x16x32_bf16 v[112:115], v[152:155], v[160:163], v[112:115]
	v_mfma_f32_16x16x32_bf16 v[100:103], v[144:147], v[186:189], v[100:103]
	v_mfma_f32_16x16x32_bf16 v[96:99], v[152:155], v[186:189], v[96:99]
	v_mfma_f32_16x16x32_bf16 v[84:87], v[144:147], v[194:197], v[84:87]
	v_mfma_f32_16x16x32_bf16 v[80:83], v[152:155], v[194:197], v[80:83]
	v_mfma_f32_16x16x32_bf16 v[68:71], v[144:147], v[202:205], v[68:71]
	v_mfma_f32_16x16x32_bf16 v[64:67], v[152:155], v[202:205], v[64:67]
	v_mfma_f32_16x16x32_bf16 v[116:119], v[148:151], v[164:167], v[116:119]
	v_mfma_f32_16x16x32_bf16 v[112:115], v[156:159], v[164:167], v[112:115]
	v_mfma_f32_16x16x32_bf16 v[100:103], v[148:151], v[190:193], v[100:103]
	v_mfma_f32_16x16x32_bf16 v[96:99], v[156:159], v[190:193], v[96:99]
	v_mfma_f32_16x16x32_bf16 v[84:87], v[148:151], v[198:201], v[84:87]
	v_mfma_f32_16x16x32_bf16 v[80:83], v[156:159], v[198:201], v[80:83]
	v_mfma_f32_16x16x32_bf16 v[68:71], v[148:151], v[206:209], v[68:71]
	v_mfma_f32_16x16x32_bf16 v[64:67], v[156:159], v[206:209], v[64:67]
	s_setprio 0
	s_barrier
; #define PG8_STAGE(bufoff, gbase, voff) do { _Pragma("unroll") for (int _i = 0; _i < 2; ++_i) \
;         __builtin_amdgcn_global_load_lds((const unsigned*)((const char*)(gbase) + (voff)[_i]), (PG8_LAS unsigned*)(lds + (bufoff) + ldsw + _i * 8192), 16, 0, 0); } while (0)
; #define PG8_LDA(dst, b, h) do { _Pragma("unroll") for (int m = 0; m < 4; ++m) _Pragma("unroll") for (int k = 0; k < 2; ++k) dst[m][k] = *(const PG8_LAS bf16x8*)(lds + PG8_SA(b, h) + aoff + m * 2048 + k * 1024); } while (0)
; #define PG8_MMA(ai, bj, At, Bt) do { __builtin_amdgcn_s_setprio(1); _Pragma("unroll") for (int m = 0; m < 4; ++m) _Pragma("unroll") for (int n = 0; n < 2; ++n) _Pragma("unroll") for (int k = 0; k < 2; ++k) \
;         acc[ai][bj][m][n] = __builtin_amdgcn_mfma_f32_16x16x32_bf16(Bt[n][k], At[m][k], acc[ai][bj][m][n], 0, 0, 0); __builtin_amdgcn_s_setprio(0); } while (0)
; #define PG8_WAIT_V(n) asm volatile("s_waitcnt vmcnt(" #n ")" ::: "memory")
; #define PG8_WAIT_L(n) asm volatile("s_waitcnt lgkmcnt(" #n ")" ::: "memory")
; #define PG8_BAR __builtin_amdgcn_s_barrier()
; #define PG8_SCHED __builtin_amdgcn_sched_barrier(0)
; template <class Epi, class Sched, bool ALIGN_EPI = false, bool SP2 = false>
; __device__ __forceinline__ void gemm_phase(PG8_LAS unsigned char* lds, const Gemm g, const Sched& S, const Epi& E, const int wid) {
;     ...
;             PG8_LDA(At, 1, 1); PG8_STAGE(PG8_SB(1, 0), b3, voffB); PG8_STAGE(PG8_SB(1, 1), b3 + hsB, voffB); PG8_STAGE(PG8_SA(1, 0), a3, voffA);
;             PG8_WAIT_V(8); PG8_WAIT_L(0); PG8_BAR; PG8_MMA(1, 0, At, B0); PG8_MMA(1, 1, At, B1); PG8_BAR; PG8_SCHED;
;     ...
;         if constexpr (ALIGN_EPI) { if (wr == 0) PG8_BAR; }
	s_add_i32 s52, s88, s58
	v_lshl_add_u64 v[210:211], v[210:211], 0, s[26:27]
	s_mov_b32 m0, s52
	ds_read_b128 v[160:163], v239 offset:49152
	ds_read_b128 v[164:167], v239 offset:50176
	ds_read_b128 v[186:189], v239 offset:51200
	ds_read_b128 v[190:193], v239 offset:52224
	ds_read_b128 v[194:197], v239 offset:53248
	ds_read_b128 v[198:201], v239 offset:54272
	ds_read_b128 v[202:205], v239 offset:55296
	ds_read_b128 v[206:209], v239 offset:56320
	global_load_lds_dwordx4 v[210:211], off
	s_add_i32 m0, s52, 0x2000
	s_add_u32 s8, s8, 0x80080
	v_lshl_add_u64 v[210:211], v[212:213], 0, s[26:27]
	s_addc_u32 s9, s9, 0
	s_add_i32 s52, s89, s58
	global_load_lds_dwordx4 v[210:211], off
	v_lshl_add_u64 v[210:211], s[8:9], 0, v[170:171]
	s_mov_b32 m0, s52
	s_nop 0
	global_load_lds_dwordx4 v[210:211], off
	v_lshl_add_u64 v[210:211], s[8:9], 0, v[174:175]
	s_add_i32 m0, s52, 0x2000
	s_nop 0
	global_load_lds_dwordx4 v[210:211], off
	v_lshl_add_u64 v[210:211], v[214:215], 0, s[26:27]
	s_mov_b32 m0, s73
	s_nop 0
	global_load_lds_dwordx4 v[210:211], off
	v_lshl_add_u64 v[210:211], v[216:217], 0, s[26:27]
	s_mov_b32 m0, s74
	s_nop 0
	global_load_lds_dwordx4 v[210:211], off
	s_waitcnt vmcnt(8)
	s_waitcnt lgkmcnt(0)
	s_barrier
	s_setprio 1
	s_waitcnt lgkmcnt(0)
	v_mfma_f32_16x16x32_bf16 v[60:63], v[128:131], v[160:163], v[60:63]
	v_mfma_f32_16x16x32_bf16 v[56:59], v[136:139], v[160:163], v[56:59]
	v_mfma_f32_16x16x32_bf16 v[44:47], v[128:131], v[186:189], v[44:47]
	v_mfma_f32_16x16x32_bf16 v[40:43], v[136:139], v[186:189], v[40:43]
	v_mfma_f32_16x16x32_bf16 v[28:31], v[128:131], v[194:197], v[28:31]
	v_mfma_f32_16x16x32_bf16 v[24:27], v[136:139], v[194:197], v[24:27]
	v_mfma_f32_16x16x32_bf16 v[12:15], v[128:131], v[202:205], v[12:15]
	v_mfma_f32_16x16x32_bf16 v[8:11], v[136:139], v[202:205], v[8:11]
	v_mfma_f32_16x16x32_bf16 v[60:63], v[132:135], v[164:167], v[60:63]
	v_mfma_f32_16x16x32_bf16 v[56:59], v[140:143], v[164:167], v[56:59]
	v_mfma_f32_16x16x32_bf16 v[44:47], v[132:135], v[190:193], v[44:47]
	v_mfma_f32_16x16x32_bf16 v[40:43], v[140:143], v[190:193], v[40:43]
	v_mfma_f32_16x16x32_bf16 v[28:31], v[132:135], v[198:201], v[28:31]
	v_mfma_f32_16x16x32_bf16 v[24:27], v[140:143], v[198:201], v[24:27]
	v_mfma_f32_16x16x32_bf16 v[12:15], v[132:135], v[206:209], v[12:15]
	v_mfma_f32_16x16x32_bf16 v[8:11], v[140:143], v[206:209], v[8:11]
	v_mfma_f32_16x16x32_bf16 v[52:55], v[144:147], v[160:163], v[52:55]
	v_mfma_f32_16x16x32_bf16 v[48:51], v[152:155], v[160:163], v[48:51]
	v_mfma_f32_16x16x32_bf16 v[36:39], v[144:147], v[186:189], v[36:39]
	v_mfma_f32_16x16x32_bf16 v[32:35], v[152:155], v[186:189], v[32:35]
	v_mfma_f32_16x16x32_bf16 v[20:23], v[144:147], v[194:197], v[20:23]
	v_mfma_f32_16x16x32_bf16 v[16:19], v[152:155], v[194:197], v[16:19]
	v_mfma_f32_16x16x32_bf16 v[4:7], v[144:147], v[202:205], v[4:7]
	v_mfma_f32_16x16x32_bf16 v[0:3], v[152:155], v[202:205], v[0:3]
	v_mfma_f32_16x16x32_bf16 v[52:55], v[148:151], v[164:167], v[52:55]
	v_mfma_f32_16x16x32_bf16 v[48:51], v[156:159], v[164:167], v[48:51]
	v_mfma_f32_16x16x32_bf16 v[36:39], v[148:151], v[190:193], v[36:39]
	v_mfma_f32_16x16x32_bf16 v[32:35], v[156:159], v[190:193], v[32:35]
	v_mfma_f32_16x16x32_bf16 v[20:23], v[148:151], v[198:201], v[20:23]
	v_mfma_f32_16x16x32_bf16 v[16:19], v[156:159], v[198:201], v[16:19]
	v_mfma_f32_16x16x32_bf16 v[4:7], v[148:151], v[206:209], v[4:7]
	v_mfma_f32_16x16x32_bf16 v[0:3], v[156:159], v[206:209], v[0:3]
	s_setprio 0
	s_barrier
	s_add_i32 s87, s87, 2
	s_add_u32 s55, s55, 0x100
	s_addc_u32 s86, s86, 0
	s_add_u32 s6, s6, 0x100
	s_addc_u32 s7, s7, 0
	s_cmp_gt_u32 s87, 29
	s_cbranch_scc0 .LBB0_588
	s_and_b64 vcc, exec, s[28:29]
	s_cbranch_vccz .LBB0_591
	s_barrier

; #define PG8_STAGE(bufoff, gbase, voff) do { _Pragma("unroll") for (int _i = 0; _i < 2; ++_i) \
;         __builtin_amdgcn_global_load_lds((const unsigned*)((const char*)(gbase) + (voff)[_i]), (PG8_LAS unsigned*)(lds + (bufoff) + ldsw + _i * 8192), 16, 0, 0); } while (0)
; #define PG8_LDA(dst, b, h) do { _Pragma("unroll") for (int m = 0; m < 4; ++m) _Pragma("unroll") for (int k = 0; k < 2; ++k) dst[m][k] = *(const PG8_LAS bf16x8*)(lds + PG8_SA(b, h) + aoff + m * 2048 + k * 1024); } while (0)
; #define PG8_LDB(dst, b, h) do { _Pragma("unroll") for (int n = 0; n < 2; ++n) _Pragma("unroll") for (int k = 0; k < 2; ++k) dst[n][k] = *(const PG8_LAS bf16x8*)(lds + PG8_SB(b, h) + boff + n * 2048 + k * 1024); } while (0)
; #define PG8_MMA(ai, bj, At, Bt) do { __builtin_amdgcn_s_setprio(1); _Pragma("unroll") for (int m = 0; m < 4; ++m) _Pragma("unroll") for (int n = 0; n < 2; ++n) _Pragma("unroll") for (int k = 0; k < 2; ++k) \
;         acc[ai][bj][m][n] = __builtin_amdgcn_mfma_f32_16x16x32_bf16(Bt[n][k], At[m][k], acc[ai][bj][m][n], 0, 0, 0); __builtin_amdgcn_s_setprio(0); } while (0)
; #define PG8_WAIT_V(n) asm volatile("s_waitcnt vmcnt(" #n ")" ::: "memory")
; #define PG8_WAIT_L(n) asm volatile("s_waitcnt lgkmcnt(" #n ")" ::: "memory")
; #define PG8_BAR __builtin_amdgcn_s_barrier()
; #define PG8_SCHED __builtin_amdgcn_sched_barrier(0)
; template <class Epi, class Sched, bool ALIGN_EPI = false, bool SP2 = false>
; __device__ __forceinline__ void gemm_phase(PG8_LAS unsigned char* lds, const Gemm g, const Sched& S, const Epi& E, const int wid) {
;     ...
;         for (int t = 0; t < nt; t += 2) {
;             const bool last = (t == nt - 2);
;             const char* a1 = cA + (size_t)(t + 1) * kstep;
;             const char* a2 = last ? nA : cA + (size_t)(t + 2) * kstep; const char* b2 = last ? nB : cB + (size_t)(t + 2) * kstep;
;             const char* a3 = a2 + kstep; const char* b3 = b2 + kstep;
;             if constexpr (SP2) {
;             PG8_LDB(B0, 0, 0); PG8_LDB(B1, 0, 1); PG8_SCHED; PG8_LDA(At, 0, 0); PG8_STAGE(PG8_SA(1, 1), a1 + hsA, voffA);
;             PG8_WAIT_V(8); PG8_WAIT_L(0); PG8_BAR; PG8_MMA(0, 0, At, B0); PG8_MMA(0, 1, At, B1); PG8_BAR; PG8_SCHED;
;             PG8_LDA(At, 0, 1); PG8_STAGE(PG8_SB(0, 0), b2, voffB); PG8_STAGE(PG8_SB(0, 1), b2 + hsB, voffB); PG8_STAGE(PG8_SA(0, 0), a2, voffA);
.LBB0_773:
	ds_read_b128 v[150:153], v147
	ds_read_b128 v[154:157], v147 offset:1024
	ds_read_b128 v[158:161], v147 offset:2048
	ds_read_b128 v[162:165], v147 offset:3072
	ds_read_b128 v[166:169], v148
	ds_read_b128 v[170:173], v148 offset:1024
	ds_read_b128 v[174:177], v148 offset:2048
	ds_read_b128 v[178:181], v148 offset:3072
	s_add_u32 s28, s26, 0x100
	s_addc_u32 s29, s27, 0
	s_cmp_eq_u32 s60, 8
	s_cselect_b32 s35, s5, s29
	s_cselect_b32 s34, s4, s28
	s_cselect_b32 s31, s25, s59
	s_cselect_b32 s30, s24, s58
	v_lshl_add_u64 v[214:215], s[26:27], 0, v[138:139]
	s_add_i32 m0, s40, 0xc000
	ds_read_b128 v[182:185], v149
	ds_read_b128 v[186:189], v149 offset:1024
	ds_read_b128 v[190:193], v149 offset:2048
	ds_read_b128 v[194:197], v149 offset:3072
	ds_read_b128 v[198:201], v149 offset:4096
	ds_read_b128 v[202:205], v149 offset:5120
	ds_read_b128 v[206:209], v149 offset:6144
	ds_read_b128 v[210:213], v149 offset:7168
	global_load_lds_dwordx4 v[214:215], off
	v_lshl_add_u64 v[214:215], s[26:27], 0, v[136:137]
	s_add_i32 m0, s40, 0xe000
	s_nop 0
	global_load_lds_dwordx4 v[214:215], off
	s_waitcnt vmcnt(8)
	s_waitcnt lgkmcnt(0)
	s_barrier
	s_setprio 1
	s_waitcnt lgkmcnt(0)
	v_mfma_f32_16x16x32_bf16 v[124:127], v[150:153], v[182:185], v[124:127]
	v_mfma_f32_16x16x32_bf16 v[120:123], v[158:161], v[182:185], v[120:123]
	v_mfma_f32_16x16x32_bf16 v[116:119], v[150:153], v[190:193], v[116:119]
	v_mfma_f32_16x16x32_bf16 v[112:115], v[158:161], v[190:193], v[112:115]
	v_mfma_f32_16x16x32_bf16 v[104:107], v[150:153], v[198:201], v[104:107]
	v_mfma_f32_16x16x32_bf16 v[96:99], v[158:161], v[198:201], v[96:99]
	v_mfma_f32_16x16x32_bf16 v[88:91], v[150:153], v[206:209], v[88:91]
	v_mfma_f32_16x16x32_bf16 v[80:83], v[158:161], v[206:209], v[80:83]
	v_mfma_f32_16x16x32_bf16 v[124:127], v[154:157], v[186:189], v[124:127]
	v_mfma_f32_16x16x32_bf16 v[120:123], v[162:165], v[186:189], v[120:123]
	v_mfma_f32_16x16x32_bf16 v[116:119], v[154:157], v[194:197], v[116:119]
	v_mfma_f32_16x16x32_bf16 v[112:115], v[162:165], v[194:197], v[112:115]
	v_mfma_f32_16x16x32_bf16 v[104:107], v[154:157], v[202:205], v[104:107]
	v_mfma_f32_16x16x32_bf16 v[96:99], v[162:165], v[202:205], v[96:99]
	v_mfma_f32_16x16x32_bf16 v[88:91], v[154:157], v[210:213], v[88:91]
	v_mfma_f32_16x16x32_bf16 v[80:83], v[162:165], v[210:213], v[80:83]
	v_mfma_f32_16x16x32_bf16 v[108:111], v[166:169], v[182:185], v[108:111]
	v_mfma_f32_16x16x32_bf16 v[100:103], v[174:177], v[182:185], v[100:103]
	v_mfma_f32_16x16x32_bf16 v[92:95], v[166:169], v[190:193], v[92:95]
	v_mfma_f32_16x16x32_bf16 v[84:87], v[174:177], v[190:193], v[84:87]
	v_mfma_f32_16x16x32_bf16 v[76:79], v[166:169], v[198:201], v[76:79]
	v_mfma_f32_16x16x32_bf16 v[72:75], v[174:177], v[198:201], v[72:75]
	v_mfma_f32_16x16x32_bf16 v[68:71], v[166:169], v[206:209], v[68:71]
	v_mfma_f32_16x16x32_bf16 v[64:67], v[174:177], v[206:209], v[64:67]
	v_mfma_f32_16x16x32_bf16 v[108:111], v[170:173], v[186:189], v[108:111]
	v_mfma_f32_16x16x32_bf16 v[100:103], v[178:181], v[186:189], v[100:103]
	v_mfma_f32_16x16x32_bf16 v[92:95], v[170:173], v[194:197], v[92:95]
	v_mfma_f32_16x16x32_bf16 v[84:87], v[178:181], v[194:197], v[84:87]
	v_mfma_f32_16x16x32_bf16 v[76:79], v[170:173], v[202:205], v[76:79]
	v_mfma_f32_16x16x32_bf16 v[72:75], v[178:181], v[202:205], v[72:75]
	v_mfma_f32_16x16x32_bf16 v[68:71], v[170:173], v[210:213], v[68:71]
	v_mfma_f32_16x16x32_bf16 v[64:67], v[178:181], v[210:213], v[64:67]
	s_setprio 0
	s_barrier
	s_add_i32 s26, s51, s38
	v_lshl_add_u64 v[214:215], s[30:31], 0, v[132:133]
	s_mov_b32 m0, s26
	ds_read_b128 v[182:185], v149 offset:16384
	ds_read_b128 v[186:189], v149 offset:17408
	ds_read_b128 v[190:193], v149 offset:18432
	ds_read_b128 v[194:197], v149 offset:19456
	ds_read_b128 v[198:201], v149 offset:20480
	ds_read_b128 v[202:205], v149 offset:21504
	ds_read_b128 v[206:209], v149 offset:22528
	ds_read_b128 v[210:213], v149 offset:23552
	global_load_lds_dwordx4 v[214:215], off
	s_add_i32 m0, s26, 0x2000
	s_add_u32 s26, s30, 0x30000
	v_lshl_add_u64 v[216:217], s[30:31], 0, v[128:129]
	s_addc_u32 s27, s31, 0
	s_add_i32 s61, s52, s38
	global_load_lds_dwordx4 v[216:217], off
	v_lshl_add_u64 v[218:219], s[26:27], 0, v[132:133]
	s_mov_b32 m0, s61
	v_lshl_add_u64 v[220:221], s[34:35], 0, v[130:131]
	global_load_lds_dwordx4 v[218:219], off
	v_lshl_add_u64 v[218:219], s[26:27], 0, v[128:129]
	s_add_i32 m0, s61, 0x2000
	s_nop 0
	global_load_lds_dwordx4 v[218:219], off
	v_lshl_add_u64 v[218:219], s[34:35], 0, v[134:135]
	s_mov_b32 m0, s40
	s_nop 0
	global_load_lds_dwordx4 v[218:219], off
	s_mov_b32 m0, s41
	s_nop 0
	global_load_lds_dwordx4 v[220:221], off
	s_waitcnt vmcnt(8)
	s_waitcnt lgkmcnt(0)
	s_barrier
; #define PG8_STAGE(bufoff, gbase, voff) do { _Pragma("unroll") for (int _i = 0; _i < 2; ++_i) \
;         __builtin_amdgcn_global_load_lds((const unsigned*)((const char*)(gbase) + (voff)[_i]), (PG8_LAS unsigned*)(lds + (bufoff) + ldsw + _i * 8192), 16, 0, 0); } while (0)
; #define PG8_LDA(dst, b, h) do { _Pragma("unroll") for (int m = 0; m < 4; ++m) _Pragma("unroll") for (int k = 0; k < 2; ++k) dst[m][k] = *(const PG8_LAS bf16x8*)(lds + PG8_SA(b, h) + aoff + m * 2048 + k * 1024); } while (0)
; #define PG8_LDB(dst, b, h) do { _Pragma("unroll") for (int n = 0; n < 2; ++n) _Pragma("unroll") for (int k = 0; k < 2; ++k) dst[n][k] = *(const PG8_LAS bf16x8*)(lds + PG8_SB(b, h) + boff + n * 2048 + k * 1024); } while (0)
; #define PG8_MMA(ai, bj, At, Bt) do { __builtin_amdgcn_s_setprio(1); _Pragma("unroll") for (int m = 0; m < 4; ++m) _Pragma("unroll") for (int n = 0; n < 2; ++n) _Pragma("unroll") for (int k = 0; k < 2; ++k) \
;         acc[ai][bj][m][n] = __builtin_amdgcn_mfma_f32_16x16x32_bf16(Bt[n][k], At[m][k], acc[ai][bj][m][n], 0, 0, 0); __builtin_amdgcn_s_setprio(0); } while (0)
; #define PG8_WAIT_V(n) asm volatile("s_waitcnt vmcnt(" #n ")" ::: "memory")
; #define PG8_WAIT_L(n) asm volatile("s_waitcnt lgkmcnt(" #n ")" ::: "memory")
; #define PG8_BAR __builtin_amdgcn_s_barrier()
; #define PG8_SCHED __builtin_amdgcn_sched_barrier(0)
; template <class Epi, class Sched, bool ALIGN_EPI = false, bool SP2 = false>
; __device__ __forceinline__ void gemm_phase(PG8_LAS unsigned char* lds, const Gemm g, const Sched& S, const Epi& E, const int wid) {
;     ...
;             PG8_WAIT_V(8); PG8_WAIT_L(0); PG8_BAR; PG8_MMA(1, 0, At, B0); PG8_MMA(1, 1, At, B1); PG8_BAR; PG8_SCHED;
;             PG8_LDB(B0, 1, 0); PG8_LDB(B1, 1, 1); PG8_SCHED; PG8_LDA(At, 1, 0); PG8_STAGE(PG8_SA(0, 1), a2 + hsA, voffA);
;             PG8_WAIT_V(8); PG8_WAIT_L(0); PG8_BAR; PG8_MMA(0, 0, At, B0); PG8_MMA(0, 1, At, B1); PG8_BAR; PG8_SCHED;
	s_setprio 1
	s_waitcnt lgkmcnt(0)
	v_mfma_f32_16x16x32_bf16 v[60:63], v[150:153], v[182:185], v[60:63]
	v_mfma_f32_16x16x32_bf16 v[56:59], v[158:161], v[182:185], v[56:59]
	v_mfma_f32_16x16x32_bf16 v[52:55], v[150:153], v[190:193], v[52:55]
	v_mfma_f32_16x16x32_bf16 v[48:51], v[158:161], v[190:193], v[48:51]
	v_mfma_f32_16x16x32_bf16 v[40:43], v[150:153], v[198:201], v[40:43]
	v_mfma_f32_16x16x32_bf16 v[32:35], v[158:161], v[198:201], v[32:35]
	v_mfma_f32_16x16x32_bf16 v[24:27], v[150:153], v[206:209], v[24:27]
	v_mfma_f32_16x16x32_bf16 v[16:19], v[158:161], v[206:209], v[16:19]
	v_mfma_f32_16x16x32_bf16 v[60:63], v[154:157], v[186:189], v[60:63]
	v_mfma_f32_16x16x32_bf16 v[56:59], v[162:165], v[186:189], v[56:59]
	v_mfma_f32_16x16x32_bf16 v[52:55], v[154:157], v[194:197], v[52:55]
	v_mfma_f32_16x16x32_bf16 v[48:51], v[162:165], v[194:197], v[48:51]
	v_mfma_f32_16x16x32_bf16 v[40:43], v[154:157], v[202:205], v[40:43]
	v_mfma_f32_16x16x32_bf16 v[32:35], v[162:165], v[202:205], v[32:35]
	v_mfma_f32_16x16x32_bf16 v[24:27], v[154:157], v[210:213], v[24:27]
	v_mfma_f32_16x16x32_bf16 v[16:19], v[162:165], v[210:213], v[16:19]
	v_mfma_f32_16x16x32_bf16 v[44:47], v[166:169], v[182:185], v[44:47]
	v_mfma_f32_16x16x32_bf16 v[36:39], v[174:177], v[182:185], v[36:39]
	v_mfma_f32_16x16x32_bf16 v[28:31], v[166:169], v[190:193], v[28:31]
	v_mfma_f32_16x16x32_bf16 v[20:23], v[174:177], v[190:193], v[20:23]
	v_mfma_f32_16x16x32_bf16 v[12:15], v[166:169], v[198:201], v[12:15]
	v_mfma_f32_16x16x32_bf16 v[8:11], v[174:177], v[198:201], v[8:11]
	v_mfma_f32_16x16x32_bf16 v[4:7], v[166:169], v[206:209], v[4:7]
	v_mfma_f32_16x16x32_bf16 v[0:3], v[174:177], v[206:209], v[0:3]
	v_mfma_f32_16x16x32_bf16 v[44:47], v[170:173], v[186:189], v[44:47]
	v_mfma_f32_16x16x32_bf16 v[36:39], v[178:181], v[186:189], v[36:39]
	v_mfma_f32_16x16x32_bf16 v[28:31], v[170:173], v[194:197], v[28:31]
	v_mfma_f32_16x16x32_bf16 v[20:23], v[178:181], v[194:197], v[20:23]
	v_mfma_f32_16x16x32_bf16 v[12:15], v[170:173], v[202:205], v[12:15]
	v_mfma_f32_16x16x32_bf16 v[8:11], v[178:181], v[202:205], v[8:11]
	v_mfma_f32_16x16x32_bf16 v[4:7], v[170:173], v[210:213], v[4:7]
	v_mfma_f32_16x16x32_bf16 v[0:3], v[178:181], v[210:213], v[0:3]
	s_setprio 0
	s_barrier
	s_add_i32 s61, 0, 0x18000
	s_add_i32 s62, 0, 0x1c000
	v_add_u32_e32 v162, s61, v145
	v_add_u32_e32 v178, s62, v145
	ds_read_b128 v[150:153], v162
	ds_read_b128 v[154:157], v162 offset:1024
	ds_read_b128 v[158:161], v162 offset:2048
	ds_read_b128 v[162:165], v162 offset:3072
	ds_read_b128 v[166:169], v178
	ds_read_b128 v[170:173], v178 offset:1024
	ds_read_b128 v[174:177], v178 offset:2048
	ds_read_b128 v[178:181], v178 offset:3072
	s_add_u32 s26, s34, 0x600000
	s_addc_u32 s27, s35, 0
	s_mov_b32 m0, s42
	v_lshl_add_u64 v[222:223], s[26:27], 0, v[134:135]
	ds_read_b128 v[182:185], v149 offset:32768
	ds_read_b128 v[186:189], v149 offset:33792
	ds_read_b128 v[190:193], v149 offset:34816
	ds_read_b128 v[194:197], v149 offset:35840
	ds_read_b128 v[198:201], v149 offset:36864
	ds_read_b128 v[202:205], v149 offset:37888
	ds_read_b128 v[206:209], v149 offset:38912
	ds_read_b128 v[210:213], v149 offset:39936
	global_load_lds_dwordx4 v[222:223], off
	v_lshl_add_u64 v[222:223], s[26:27], 0, v[130:131]
	s_mov_b32 m0, s43
	s_nop 0
	global_load_lds_dwordx4 v[222:223], off
	s_waitcnt vmcnt(8)
	s_waitcnt lgkmcnt(0)
	s_barrier
	s_setprio 1
	s_waitcnt lgkmcnt(0)
	v_mfma_f32_16x16x32_bf16 v[124:127], v[150:153], v[182:185], v[124:127]
	v_mfma_f32_16x16x32_bf16 v[120:123], v[158:161], v[182:185], v[120:123]
	v_mfma_f32_16x16x32_bf16 v[116:119], v[150:153], v[190:193], v[116:119]
	v_mfma_f32_16x16x32_bf16 v[112:115], v[158:161], v[190:193], v[112:115]
	v_mfma_f32_16x16x32_bf16 v[104:107], v[150:153], v[198:201], v[104:107]
	v_mfma_f32_16x16x32_bf16 v[96:99], v[158:161], v[198:201], v[96:99]
	v_mfma_f32_16x16x32_bf16 v[88:91], v[150:153], v[206:209], v[88:91]
	v_mfma_f32_16x16x32_bf16 v[80:83], v[158:161], v[206:209], v[80:83]
	v_mfma_f32_16x16x32_bf16 v[124:127], v[154:157], v[186:189], v[124:127]
	v_mfma_f32_16x16x32_bf16 v[120:123], v[162:165], v[186:189], v[120:123]
	v_mfma_f32_16x16x32_bf16 v[116:119], v[154:157], v[194:197], v[116:119]
	v_mfma_f32_16x16x32_bf16 v[112:115], v[162:165], v[194:197], v[112:115]
	v_mfma_f32_16x16x32_bf16 v[104:107], v[154:157], v[202:205], v[104:107]
	v_mfma_f32_16x16x32_bf16 v[96:99], v[162:165], v[202:205], v[96:99]
	v_mfma_f32_16x16x32_bf16 v[88:91], v[154:157], v[210:213], v[88:91]
	v_mfma_f32_16x16x32_bf16 v[80:83], v[162:165], v[210:213], v[80:83]
	v_mfma_f32_16x16x32_bf16 v[108:111], v[166:169], v[182:185], v[108:111]
	v_mfma_f32_16x16x32_bf16 v[100:103], v[174:177], v[182:185], v[100:103]
	v_mfma_f32_16x16x32_bf16 v[92:95], v[166:169], v[190:193], v[92:95]
	v_mfma_f32_16x16x32_bf16 v[84:87], v[174:177], v[190:193], v[84:87]
	v_mfma_f32_16x16x32_bf16 v[76:79], v[166:169], v[198:201], v[76:79]
	v_mfma_f32_16x16x32_bf16 v[72:75], v[174:177], v[198:201], v[72:75]
	v_mfma_f32_16x16x32_bf16 v[68:71], v[166:169], v[206:209], v[68:71]
	v_mfma_f32_16x16x32_bf16 v[64:67], v[174:177], v[206:209], v[64:67]
	v_mfma_f32_16x16x32_bf16 v[108:111], v[170:173], v[186:189], v[108:111]
	v_mfma_f32_16x16x32_bf16 v[100:103], v[178:181], v[186:189], v[100:103]
	v_mfma_f32_16x16x32_bf16 v[92:95], v[170:173], v[194:197], v[92:95]
	v_mfma_f32_16x16x32_bf16 v[84:87], v[178:181], v[194:197], v[84:87]
	v_mfma_f32_16x16x32_bf16 v[76:79], v[170:173], v[202:205], v[76:79]
	v_mfma_f32_16x16x32_bf16 v[72:75], v[178:181], v[202:205], v[72:75]
	v_mfma_f32_16x16x32_bf16 v[68:71], v[170:173], v[210:213], v[68:71]
	v_mfma_f32_16x16x32_bf16 v[64:67], v[178:181], v[210:213], v[64:67]
	s_setprio 0
	s_barrier
; #define PG8_STAGE(bufoff, gbase, voff) do { _Pragma("unroll") for (int _i = 0; _i < 2; ++_i) \
;         __builtin_amdgcn_global_load_lds((const unsigned*)((const char*)(gbase) + (voff)[_i]), (PG8_LAS unsigned*)(lds + (bufoff) + ldsw + _i * 8192), 16, 0, 0); } while (0)
; #define PG8_LDA(dst, b, h) do { _Pragma("unroll") for (int m = 0; m < 4; ++m) _Pragma("unroll") for (int k = 0; k < 2; ++k) dst[m][k] = *(const PG8_LAS bf16x8*)(lds + PG8_SA(b, h) + aoff + m * 2048 + k * 1024); } while (0)
; #define PG8_MMA(ai, bj, At, Bt) do { __builtin_amdgcn_s_setprio(1); _Pragma("unroll") for (int m = 0; m < 4; ++m) _Pragma("unroll") for (int n = 0; n < 2; ++n) _Pragma("unroll") for (int k = 0; k < 2; ++k) \
;         acc[ai][bj][m][n] = __builtin_amdgcn_mfma_f32_16x16x32_bf16(Bt[n][k], At[m][k], acc[ai][bj][m][n], 0, 0, 0); __builtin_amdgcn_s_setprio(0); } while (0)
; #define PG8_WAIT_V(n) asm volatile("s_waitcnt vmcnt(" #n ")" ::: "memory")
; #define PG8_WAIT_L(n) asm volatile("s_waitcnt lgkmcnt(" #n ")" ::: "memory")
; #define PG8_BAR __builtin_amdgcn_s_barrier()
; #define PG8_SCHED __builtin_amdgcn_sched_barrier(0)
; template <class Epi, class Sched, bool ALIGN_EPI = false, bool SP2 = false>
; __device__ __forceinline__ void gemm_phase(PG8_LAS unsigned char* lds, const Gemm g, const Sched& S, const Epi& E, const int wid) {
;     ...
;             PG8_LDA(At, 1, 1); PG8_STAGE(PG8_SB(1, 0), b3, voffB); PG8_STAGE(PG8_SB(1, 1), b3 + hsB, voffB); PG8_STAGE(PG8_SA(1, 0), a3, voffA);
;             PG8_WAIT_V(8); PG8_WAIT_L(0); PG8_BAR; PG8_MMA(1, 0, At, B0); PG8_MMA(1, 1, At, B1); PG8_BAR; PG8_SCHED;
;     ...
;         if constexpr (ALIGN_EPI) { if (wr == 0) PG8_BAR; }
	s_add_i32 s26, s61, s38
	v_lshl_add_u64 v[214:215], v[214:215], 0, s[12:13]
	s_mov_b32 m0, s26
	ds_read_b128 v[182:185], v149 offset:49152
	ds_read_b128 v[186:189], v149 offset:50176
	ds_read_b128 v[190:193], v149 offset:51200
	ds_read_b128 v[194:197], v149 offset:52224
	ds_read_b128 v[198:201], v149 offset:53248
	ds_read_b128 v[202:205], v149 offset:54272
	ds_read_b128 v[206:209], v149 offset:55296
	ds_read_b128 v[210:213], v149 offset:56320
	global_load_lds_dwordx4 v[214:215], off
	s_add_i32 m0, s26, 0x2000
	s_add_u32 s26, s30, 0x30080
	v_lshl_add_u64 v[214:215], v[216:217], 0, s[12:13]
	s_addc_u32 s27, s31, 0
	s_add_i32 s30, s62, s38
	global_load_lds_dwordx4 v[214:215], off
	v_lshl_add_u64 v[214:215], s[26:27], 0, v[132:133]
	s_mov_b32 m0, s30
	s_nop 0
	global_load_lds_dwordx4 v[214:215], off
	v_lshl_add_u64 v[214:215], s[26:27], 0, v[128:129]
	s_add_i32 m0, s30, 0x2000
	s_nop 0
	global_load_lds_dwordx4 v[214:215], off
	v_lshl_add_u64 v[214:215], v[218:219], 0, s[12:13]
	s_mov_b32 m0, s46
	s_nop 0
	global_load_lds_dwordx4 v[214:215], off
	v_lshl_add_u64 v[214:215], v[220:221], 0, s[12:13]
	s_mov_b32 m0, s47
	s_nop 0
	global_load_lds_dwordx4 v[214:215], off
	s_waitcnt vmcnt(8)
	s_waitcnt lgkmcnt(0)
	s_barrier
	s_setprio 1
	s_waitcnt lgkmcnt(0)
	v_mfma_f32_16x16x32_bf16 v[60:63], v[150:153], v[182:185], v[60:63]
	v_mfma_f32_16x16x32_bf16 v[56:59], v[158:161], v[182:185], v[56:59]
	v_mfma_f32_16x16x32_bf16 v[52:55], v[150:153], v[190:193], v[52:55]
	v_mfma_f32_16x16x32_bf16 v[48:51], v[158:161], v[190:193], v[48:51]
	v_mfma_f32_16x16x32_bf16 v[40:43], v[150:153], v[198:201], v[40:43]
	v_mfma_f32_16x16x32_bf16 v[32:35], v[158:161], v[198:201], v[32:35]
	v_mfma_f32_16x16x32_bf16 v[24:27], v[150:153], v[206:209], v[24:27]
	v_mfma_f32_16x16x32_bf16 v[16:19], v[158:161], v[206:209], v[16:19]
	v_mfma_f32_16x16x32_bf16 v[60:63], v[154:157], v[186:189], v[60:63]
	v_mfma_f32_16x16x32_bf16 v[56:59], v[162:165], v[186:189], v[56:59]
	v_mfma_f32_16x16x32_bf16 v[52:55], v[154:157], v[194:197], v[52:55]
	v_mfma_f32_16x16x32_bf16 v[48:51], v[162:165], v[194:197], v[48:51]
	v_mfma_f32_16x16x32_bf16 v[40:43], v[154:157], v[202:205], v[40:43]
	v_mfma_f32_16x16x32_bf16 v[32:35], v[162:165], v[202:205], v[32:35]
	v_mfma_f32_16x16x32_bf16 v[24:27], v[154:157], v[210:213], v[24:27]
	v_mfma_f32_16x16x32_bf16 v[16:19], v[162:165], v[210:213], v[16:19]
	v_mfma_f32_16x16x32_bf16 v[44:47], v[166:169], v[182:185], v[44:47]
	v_mfma_f32_16x16x32_bf16 v[36:39], v[174:177], v[182:185], v[36:39]
	v_mfma_f32_16x16x32_bf16 v[28:31], v[166:169], v[190:193], v[28:31]
	v_mfma_f32_16x16x32_bf16 v[20:23], v[174:177], v[190:193], v[20:23]
	v_mfma_f32_16x16x32_bf16 v[12:15], v[166:169], v[198:201], v[12:15]
	v_mfma_f32_16x16x32_bf16 v[8:11], v[174:177], v[198:201], v[8:11]
	v_mfma_f32_16x16x32_bf16 v[4:7], v[166:169], v[206:209], v[4:7]
	v_mfma_f32_16x16x32_bf16 v[0:3], v[174:177], v[206:209], v[0:3]
	v_mfma_f32_16x16x32_bf16 v[44:47], v[170:173], v[186:189], v[44:47]
	v_mfma_f32_16x16x32_bf16 v[36:39], v[178:181], v[186:189], v[36:39]
	v_mfma_f32_16x16x32_bf16 v[28:31], v[170:173], v[194:197], v[28:31]
	v_mfma_f32_16x16x32_bf16 v[20:23], v[178:181], v[194:197], v[20:23]
	v_mfma_f32_16x16x32_bf16 v[12:15], v[170:173], v[202:205], v[12:15]
	v_mfma_f32_16x16x32_bf16 v[8:11], v[178:181], v[202:205], v[8:11]
	v_mfma_f32_16x16x32_bf16 v[4:7], v[170:173], v[210:213], v[4:7]
	v_mfma_f32_16x16x32_bf16 v[0:3], v[178:181], v[210:213], v[0:3]
	s_setprio 0
	s_barrier
	s_add_i32 s60, s60, 2
	s_add_u32 s58, s58, 0x100
	s_addc_u32 s59, s59, 0
	s_cmp_gt_u32 s60, 9
	s_mov_b64 s[26:27], s[28:29]
	s_cbranch_scc0 .LBB0_773
	s_and_b64 vcc, exec, s[14:15]
	s_cbranch_vccz .LBB0_776
	s_barrier

; #define PG8_STAGE(bufoff, gbase, voff) do { _Pragma("unroll") for (int _i = 0; _i < 2; ++_i) \
;         __builtin_amdgcn_global_load_lds((const unsigned*)((const char*)(gbase) + (voff)[_i]), (PG8_LAS unsigned*)(lds + (bufoff) + ldsw + _i * 8192), 16, 0, 0); } while (0)
; #define PG8_LDA(dst, b, h) do { _Pragma("unroll") for (int m = 0; m < 4; ++m) _Pragma("unroll") for (int k = 0; k < 2; ++k) dst[m][k] = *(const PG8_LAS bf16x8*)(lds + PG8_SA(b, h) + aoff + m * 2048 + k * 1024); } while (0)
; #define PG8_LDB(dst, b, h) do { _Pragma("unroll") for (int n = 0; n < 2; ++n) _Pragma("unroll") for (int k = 0; k < 2; ++k) dst[n][k] = *(const PG8_LAS bf16x8*)(lds + PG8_SB(b, h) + boff + n * 2048 + k * 1024); } while (0)
; #define PG8_MMA(ai, bj, At, Bt) do { __builtin_amdgcn_s_setprio(1); _Pragma("unroll") for (int m = 0; m < 4; ++m) _Pragma("unroll") for (int n = 0; n < 2; ++n) _Pragma("unroll") for (int k = 0; k < 2; ++k) \
;         acc[ai][bj][m][n] = __builtin_amdgcn_mfma_f32_16x16x32_bf16(Bt[n][k], At[m][k], acc[ai][bj][m][n], 0, 0, 0); __builtin_amdgcn_s_setprio(0); } while (0)
; #define PG8_WAIT_V(n) asm volatile("s_waitcnt vmcnt(" #n ")" ::: "memory")
; #define PG8_WAIT_L(n) asm volatile("s_waitcnt lgkmcnt(" #n ")" ::: "memory")
; #define PG8_BAR __builtin_amdgcn_s_barrier()
; #define PG8_SCHED __builtin_amdgcn_sched_barrier(0)
; template <class Epi, class Sched, bool ALIGN_EPI = false, bool SP2 = false>
; __device__ __forceinline__ void gemm_phase(PG8_LAS unsigned char* lds, const Gemm g, const Sched& S, const Epi& E, const int wid) {
;     ...
;             if constexpr (SP2) {
;             PG8_LDB(B0, 0, 0); PG8_LDB(B1, 0, 1); PG8_SCHED; PG8_LDA(At, 0, 0); PG8_STAGE(PG8_SA(1, 1), a1 + hsA, voffA);
;             PG8_WAIT_V(8); PG8_WAIT_L(0); PG8_BAR; PG8_MMA(0, 0, At, B0); PG8_MMA(0, 1, At, B1); PG8_BAR; PG8_SCHED;
;             PG8_LDA(At, 0, 1); PG8_STAGE(PG8_SB(0, 0), b2, voffB); PG8_STAGE(PG8_SB(0, 1), b2 + hsB, voffB); PG8_STAGE(PG8_SA(0, 0), a2, voffA);
;             PG8_WAIT_V(8); PG8_WAIT_L(0); PG8_BAR; PG8_MMA(1, 0, At, B0); PG8_MMA(1, 1, At, B1); PG8_BAR; PG8_SCHED;
;             PG8_LDB(B0, 1, 0); PG8_LDB(B1, 1, 1); PG8_SCHED; PG8_LDA(At, 1, 0); PG8_STAGE(PG8_SA(0, 1), a2 + hsA, voffA);
;             PG8_WAIT_V(8); PG8_WAIT_L(0); PG8_BAR; PG8_MMA(0, 0, At, B0); PG8_MMA(0, 1, At, B1); PG8_BAR; PG8_SCHED;
.LBB0_958:
	ds_read_b128 v[8:11], v164
	ds_read_b128 v[12:15], v164 offset:1024
	ds_read_b128 v[16:19], v164 offset:2048
	ds_read_b128 v[20:23], v164 offset:3072
	ds_read_b128 v[24:27], v165
	ds_read_b128 v[28:31], v165 offset:1024
	s_waitcnt vmcnt(0)
	ds_read_b128 v[32:35], v165 offset:2048
	ds_read_b128 v[36:39], v165 offset:3072
	s_add_u32 s66, s40, 0x600080
	s_addc_u32 s67, s41, 0
	s_add_i32 s78, s46, 0xc000
	v_lshl_add_u64 v[64:65], s[66:67], 0, v[150:151]
	s_mov_b32 m0, s78
	s_add_i32 s65, s46, 0xe000
	ds_read_b128 v[0:3], v163
	ds_read_b128 v[4:7], v163 offset:1024
	ds_read_b128 v[40:43], v163 offset:2048
	ds_read_b128 v[44:47], v163 offset:3072
	ds_read_b128 v[48:51], v163 offset:4096
	ds_read_b128 v[52:55], v163 offset:5120
	ds_read_b128 v[56:59], v163 offset:6144
	ds_read_b128 v[60:63], v163 offset:7168
	global_load_lds_dwordx4 v[64:65], off
	v_lshl_add_u64 v[64:65], s[66:67], 0, v[146:147]
	s_mov_b32 m0, s65
	s_nop 0
	global_load_lds_dwordx4 v[64:65], off
	s_waitcnt vmcnt(8)
	s_waitcnt lgkmcnt(0)
	s_barrier
	s_setprio 1
	s_waitcnt lgkmcnt(0)
	v_mfma_f32_16x16x32_bf16 v[64:67], v[8:11], v[0:3], 0
	v_mfma_f32_16x16x32_bf16 v[68:71], v[16:19], v[0:3], 0
	v_mfma_f32_16x16x32_bf16 v[72:75], v[8:11], v[40:43], 0
	v_mfma_f32_16x16x32_bf16 v[76:79], v[16:19], v[40:43], 0
	v_mfma_f32_16x16x32_bf16 v[80:83], v[8:11], v[48:51], 0
	v_mfma_f32_16x16x32_bf16 v[84:87], v[16:19], v[48:51], 0
	v_mfma_f32_16x16x32_bf16 v[88:91], v[8:11], v[56:59], 0
	v_mfma_f32_16x16x32_bf16 v[92:95], v[16:19], v[56:59], 0
	v_mfma_f32_16x16x32_bf16 v[64:67], v[12:15], v[4:7], v[64:67]
	v_mfma_f32_16x16x32_bf16 v[68:71], v[20:23], v[4:7], v[68:71]
	v_mfma_f32_16x16x32_bf16 v[72:75], v[12:15], v[44:47], v[72:75]
	v_mfma_f32_16x16x32_bf16 v[76:79], v[20:23], v[44:47], v[76:79]
	v_mfma_f32_16x16x32_bf16 v[80:83], v[12:15], v[52:55], v[80:83]
	v_mfma_f32_16x16x32_bf16 v[84:87], v[20:23], v[52:55], v[84:87]
	v_mfma_f32_16x16x32_bf16 v[88:91], v[12:15], v[60:63], v[88:91]
	v_mfma_f32_16x16x32_bf16 v[92:95], v[20:23], v[60:63], v[92:95]
	v_mfma_f32_16x16x32_bf16 v[96:99], v[24:27], v[0:3], 0
	v_mfma_f32_16x16x32_bf16 v[0:3], v[32:35], v[0:3], 0
	v_mfma_f32_16x16x32_bf16 v[100:103], v[36:39], v[4:7], v[0:3]
	v_mfma_f32_16x16x32_bf16 v[0:3], v[24:27], v[40:43], 0
	v_mfma_f32_16x16x32_bf16 v[104:107], v[28:31], v[44:47], v[0:3]
	v_mfma_f32_16x16x32_bf16 v[0:3], v[32:35], v[40:43], 0
	v_mfma_f32_16x16x32_bf16 v[40:43], v[36:39], v[44:47], v[0:3]
	v_mfma_f32_16x16x32_bf16 v[0:3], v[24:27], v[48:51], 0
	v_mfma_f32_16x16x32_bf16 v[44:47], v[28:31], v[52:55], v[0:3]
	v_mfma_f32_16x16x32_bf16 v[0:3], v[32:35], v[48:51], 0
	v_mfma_f32_16x16x32_bf16 v[48:51], v[36:39], v[52:55], v[0:3]
	v_mfma_f32_16x16x32_bf16 v[0:3], v[24:27], v[56:59], 0
	v_mfma_f32_16x16x32_bf16 v[52:55], v[28:31], v[60:63], v[0:3]
	v_mfma_f32_16x16x32_bf16 v[0:3], v[32:35], v[56:59], 0
	v_mfma_f32_16x16x32_bf16 v[96:99], v[28:31], v[4:7], v[96:99]
	v_mfma_f32_16x16x32_bf16 v[56:59], v[36:39], v[60:63], v[0:3]
	s_setprio 0
	s_barrier
	s_nop 3
	v_lshl_add_u64 v[0:1], s[42:43], 0, v[148:149]
	s_add_i32 s75, s57, s3
	v_lshl_add_u64 v[2:3], v[0:1], 0, s[20:21]
	s_mov_b32 m0, s75
	s_add_i32 s66, s75, 0x2000
	ds_read_b128 v[60:63], v163 offset:16384
	ds_read_b128 v[108:111], v163 offset:17408
	ds_read_b128 v[112:115], v163 offset:18432
	ds_read_b128 v[116:119], v163 offset:19456
	ds_read_b128 v[120:123], v163 offset:20480
	ds_read_b128 v[124:127], v163 offset:21504
	ds_read_b128 v[128:131], v163 offset:22528
	ds_read_b128 v[132:135], v163 offset:23552
	global_load_lds_dwordx4 v[2:3], off
	v_lshl_add_u64 v[2:3], s[42:43], 0, v[144:145]
	s_add_u32 s76, s42, 0x18100
	v_lshl_add_u64 v[4:5], v[2:3], 0, s[20:21]
	s_mov_b32 m0, s66
	s_addc_u32 s77, s43, 0
	s_add_i32 s67, s58, s3
	global_load_lds_dwordx4 v[4:5], off
	v_lshl_add_u64 v[4:5], s[76:77], 0, v[148:149]
	s_mov_b32 m0, s67
	s_add_i32 s74, s67, 0x2000
	global_load_lds_dwordx4 v[4:5], off
	v_lshl_add_u64 v[4:5], s[76:77], 0, v[144:145]
	s_mov_b32 m0, s74
	s_nop 0
	global_load_lds_dwordx4 v[4:5], off
	v_lshl_add_u64 v[4:5], s[40:41], 0, v[150:151]
	v_lshl_add_u64 v[6:7], v[4:5], 0, s[20:21]
	s_mov_b32 m0, s46
	s_nop 0
	global_load_lds_dwordx4 v[6:7], off
	v_lshl_add_u64 v[6:7], s[40:41], 0, v[146:147]
	v_lshl_add_u64 v[136:137], v[6:7], 0, s[20:21]
	s_mov_b32 m0, s47
	s_nop 0
	global_load_lds_dwordx4 v[136:137], off
	s_waitcnt vmcnt(8)
	s_waitcnt lgkmcnt(0)
	s_barrier
	s_setprio 1
	s_waitcnt lgkmcnt(0)
	v_mfma_f32_16x16x32_bf16 v[136:139], v[8:11], v[60:63], 0
	v_mfma_f32_16x16x32_bf16 v[158:161], v[8:11], v[112:115], 0
	v_mfma_f32_16x16x32_bf16 v[170:173], v[8:11], v[120:123], 0
	v_mfma_f32_16x16x32_bf16 v[8:11], v[8:11], v[128:131], 0
	v_mfma_f32_16x16x32_bf16 v[136:139], v[12:15], v[108:111], v[136:139]
	v_mfma_f32_16x16x32_bf16 v[140:143], v[16:19], v[60:63], 0
	v_mfma_f32_16x16x32_bf16 v[158:161], v[12:15], v[116:119], v[158:161]
	v_mfma_f32_16x16x32_bf16 v[166:169], v[16:19], v[112:115], 0
	v_mfma_f32_16x16x32_bf16 v[170:173], v[12:15], v[124:127], v[170:173]
	v_mfma_f32_16x16x32_bf16 v[174:177], v[16:19], v[120:123], 0
	v_mfma_f32_16x16x32_bf16 v[10:13], v[12:15], v[132:135], v[8:11]
	v_mfma_f32_16x16x32_bf16 v[14:17], v[16:19], v[128:131], 0
	v_mfma_f32_16x16x32_bf16 v[14:17], v[20:23], v[132:135], v[14:17]
	v_mfma_f32_16x16x32_bf16 v[140:143], v[20:23], v[108:111], v[140:143]
	v_mfma_f32_16x16x32_bf16 v[166:169], v[20:23], v[116:119], v[166:169]
	v_mfma_f32_16x16x32_bf16 v[174:177], v[20:23], v[124:127], v[174:177]
	v_mfma_f32_16x16x32_bf16 v[18:21], v[24:27], v[60:63], 0
	v_mfma_f32_16x16x32_bf16 v[60:63], v[32:35], v[60:63], 0
	v_mfma_f32_16x16x32_bf16 v[18:21], v[28:31], v[108:111], v[18:21]
	v_mfma_f32_16x16x32_bf16 v[60:63], v[36:39], v[108:111], v[60:63]
	v_mfma_f32_16x16x32_bf16 v[108:111], v[24:27], v[112:115], 0
	v_mfma_f32_16x16x32_bf16 v[112:115], v[32:35], v[112:115], 0
	v_mfma_f32_16x16x32_bf16 v[108:111], v[28:31], v[116:119], v[108:111]
	v_mfma_f32_16x16x32_bf16 v[112:115], v[36:39], v[116:119], v[112:115]
	v_mfma_f32_16x16x32_bf16 v[116:119], v[24:27], v[120:123], 0
	v_mfma_f32_16x16x32_bf16 v[22:25], v[24:27], v[128:131], 0
	v_mfma_f32_16x16x32_bf16 v[116:119], v[28:31], v[124:127], v[116:119]
	v_mfma_f32_16x16x32_bf16 v[22:25], v[28:31], v[132:135], v[22:25]
	v_mfma_f32_16x16x32_bf16 v[26:29], v[32:35], v[128:131], 0
	v_mfma_f32_16x16x32_bf16 v[120:123], v[32:35], v[120:123], 0
	v_mfma_f32_16x16x32_bf16 v[26:29], v[36:39], v[132:135], v[26:29]
	v_mfma_f32_16x16x32_bf16 v[120:123], v[36:39], v[124:127], v[120:123]
	s_setprio 0
	s_barrier
; #define PG8_STAGE(bufoff, gbase, voff) do { _Pragma("unroll") for (int _i = 0; _i < 2; ++_i) \
;         __builtin_amdgcn_global_load_lds((const unsigned*)((const char*)(gbase) + (voff)[_i]), (PG8_LAS unsigned*)(lds + (bufoff) + ldsw + _i * 8192), 16, 0, 0); } while (0)
; #define PG8_LDA(dst, b, h) do { _Pragma("unroll") for (int m = 0; m < 4; ++m) _Pragma("unroll") for (int k = 0; k < 2; ++k) dst[m][k] = *(const PG8_LAS bf16x8*)(lds + PG8_SA(b, h) + aoff + m * 2048 + k * 1024); } while (0)
; #define PG8_LDB(dst, b, h) do { _Pragma("unroll") for (int n = 0; n < 2; ++n) _Pragma("unroll") for (int k = 0; k < 2; ++k) dst[n][k] = *(const PG8_LAS bf16x8*)(lds + PG8_SB(b, h) + boff + n * 2048 + k * 1024); } while (0)
; #define PG8_MMA(ai, bj, At, Bt) do { __builtin_amdgcn_s_setprio(1); _Pragma("unroll") for (int m = 0; m < 4; ++m) _Pragma("unroll") for (int n = 0; n < 2; ++n) _Pragma("unroll") for (int k = 0; k < 2; ++k) \
;         acc[ai][bj][m][n] = __builtin_amdgcn_mfma_f32_16x16x32_bf16(Bt[n][k], At[m][k], acc[ai][bj][m][n], 0, 0, 0); __builtin_amdgcn_s_setprio(0); } while (0)
; #define PG8_WAIT_V(n) asm volatile("s_waitcnt vmcnt(" #n ")" ::: "memory")
; #define PG8_WAIT_L(n) asm volatile("s_waitcnt lgkmcnt(" #n ")" ::: "memory")
; #define PG8_BAR __builtin_amdgcn_s_barrier()
; #define PG8_SCHED __builtin_amdgcn_sched_barrier(0)
; template <class Epi, class Sched, bool ALIGN_EPI = false, bool SP2 = false>
; __device__ __forceinline__ void gemm_phase(PG8_LAS unsigned char* lds, const Gemm g, const Sched& S, const Epi& E, const int wid) {
;     ...
;             PG8_WAIT_V(8); PG8_WAIT_L(0); PG8_BAR; PG8_MMA(1, 0, At, B0); PG8_MMA(1, 1, At, B1); PG8_BAR; PG8_SCHED;
;             PG8_LDB(B0, 1, 0); PG8_LDB(B1, 1, 1); PG8_SCHED; PG8_LDA(At, 1, 0); PG8_STAGE(PG8_SA(0, 1), a2 + hsA, voffA);
;             PG8_WAIT_V(8); PG8_WAIT_L(0); PG8_BAR; PG8_MMA(0, 0, At, B0); PG8_MMA(0, 1, At, B1); PG8_BAR; PG8_SCHED;
;             PG8_LDA(At, 1, 1); PG8_STAGE(PG8_SB(1, 0), b3, voffB); PG8_STAGE(PG8_SB(1, 1), b3 + hsB, voffB); PG8_STAGE(PG8_SA(1, 0), a3, voffA);
	s_add_i32 s81, 0, 0x18000
	s_add_i32 s79, 0, 0x1c000
	v_add_u32_e32 v8, s81, v162
	v_add_u32_e32 v9, s79, v162
	ds_read_b128 v[30:33], v8
	ds_read_b128 v[34:37], v8 offset:1024
	ds_read_b128 v[124:127], v8 offset:2048
	ds_read_b128 v[128:131], v8 offset:3072
	ds_read_b128 v[132:135], v9
	ds_read_b128 v[178:181], v9 offset:1024
	ds_read_b128 v[182:185], v9 offset:2048
	ds_read_b128 v[186:189], v9 offset:3072
	s_add_u32 s76, s40, 0x600100
	s_addc_u32 s77, s41, 0
	s_mov_b32 m0, s48
	v_lshl_add_u64 v[38:39], s[76:77], 0, v[150:151]
	ds_read_b128 v[190:193], v163 offset:32768
	ds_read_b128 v[194:197], v163 offset:33792
	ds_read_b128 v[198:201], v163 offset:34816
	ds_read_b128 v[202:205], v163 offset:35840
	ds_read_b128 v[206:209], v163 offset:36864
	ds_read_b128 v[210:213], v163 offset:37888
	ds_read_b128 v[214:217], v163 offset:38912
	ds_read_b128 v[218:221], v163 offset:39936
	global_load_lds_dwordx4 v[38:39], off
	v_lshl_add_u64 v[38:39], s[76:77], 0, v[146:147]
	s_mov_b32 m0, s49
	s_nop 0
	global_load_lds_dwordx4 v[38:39], off
	s_waitcnt vmcnt(8)
	s_waitcnt lgkmcnt(0)
	s_barrier
	s_setprio 1
	s_waitcnt lgkmcnt(0)
	v_mfma_f32_16x16x32_bf16 v[64:67], v[30:33], v[190:193], v[64:67]
	v_mfma_f32_16x16x32_bf16 v[68:71], v[124:127], v[190:193], v[68:71]
	v_mfma_f32_16x16x32_bf16 v[72:75], v[30:33], v[198:201], v[72:75]
	v_mfma_f32_16x16x32_bf16 v[76:79], v[124:127], v[198:201], v[76:79]
	v_mfma_f32_16x16x32_bf16 v[80:83], v[30:33], v[206:209], v[80:83]
	v_mfma_f32_16x16x32_bf16 v[84:87], v[124:127], v[206:209], v[84:87]
	v_mfma_f32_16x16x32_bf16 v[88:91], v[30:33], v[214:217], v[88:91]
	v_mfma_f32_16x16x32_bf16 v[92:95], v[124:127], v[214:217], v[92:95]
	v_mfma_f32_16x16x32_bf16 v[64:67], v[34:37], v[194:197], v[64:67]
	v_mfma_f32_16x16x32_bf16 v[68:71], v[128:131], v[194:197], v[68:71]
	v_mfma_f32_16x16x32_bf16 v[72:75], v[34:37], v[202:205], v[72:75]
	v_mfma_f32_16x16x32_bf16 v[76:79], v[128:131], v[202:205], v[76:79]
	v_mfma_f32_16x16x32_bf16 v[80:83], v[34:37], v[210:213], v[80:83]
	v_mfma_f32_16x16x32_bf16 v[84:87], v[128:131], v[210:213], v[84:87]
	v_mfma_f32_16x16x32_bf16 v[88:91], v[34:37], v[218:221], v[88:91]
	v_mfma_f32_16x16x32_bf16 v[92:95], v[128:131], v[218:221], v[92:95]
	v_mfma_f32_16x16x32_bf16 v[96:99], v[132:135], v[190:193], v[96:99]
	v_mfma_f32_16x16x32_bf16 v[100:103], v[182:185], v[190:193], v[100:103]
	v_mfma_f32_16x16x32_bf16 v[104:107], v[132:135], v[198:201], v[104:107]
	v_mfma_f32_16x16x32_bf16 v[38:41], v[182:185], v[198:201], v[40:43]
	v_mfma_f32_16x16x32_bf16 v[42:45], v[132:135], v[206:209], v[44:47]
	v_mfma_f32_16x16x32_bf16 v[46:49], v[182:185], v[206:209], v[48:51]
	v_mfma_f32_16x16x32_bf16 v[50:53], v[132:135], v[214:217], v[52:55]
	v_mfma_f32_16x16x32_bf16 v[54:57], v[182:185], v[214:217], v[56:59]
	v_mfma_f32_16x16x32_bf16 v[96:99], v[178:181], v[194:197], v[96:99]
	v_mfma_f32_16x16x32_bf16 v[100:103], v[186:189], v[194:197], v[100:103]
	v_mfma_f32_16x16x32_bf16 v[104:107], v[178:181], v[202:205], v[104:107]
	v_mfma_f32_16x16x32_bf16 v[38:41], v[186:189], v[202:205], v[38:41]
	v_mfma_f32_16x16x32_bf16 v[42:45], v[178:181], v[210:213], v[42:45]
	v_mfma_f32_16x16x32_bf16 v[46:49], v[186:189], v[210:213], v[46:49]
	v_mfma_f32_16x16x32_bf16 v[50:53], v[178:181], v[218:221], v[50:53]
	v_mfma_f32_16x16x32_bf16 v[54:57], v[186:189], v[218:221], v[54:57]
	s_setprio 0
	s_barrier
	s_add_i32 s81, s81, s3
	s_add_i32 s76, s81, 0x2000
	v_lshl_add_u64 v[58:59], v[0:1], 0, s[22:23]
	s_mov_b32 m0, s81
	s_add_u32 s82, s42, 0x18180
	ds_read_b128 v[190:193], v163 offset:49152
	ds_read_b128 v[194:197], v163 offset:50176
	ds_read_b128 v[198:201], v163 offset:51200
	ds_read_b128 v[202:205], v163 offset:52224
	ds_read_b128 v[206:209], v163 offset:53248
	ds_read_b128 v[210:213], v163 offset:54272
	ds_read_b128 v[214:217], v163 offset:55296
	ds_read_b128 v[218:221], v163 offset:56320
	global_load_lds_dwordx4 v[58:59], off
	v_lshl_add_u64 v[58:59], v[2:3], 0, s[22:23]
	s_mov_b32 m0, s76
	s_addc_u32 s83, s43, 0
	s_add_i32 s77, s79, s3
	global_load_lds_dwordx4 v[58:59], off
	v_lshl_add_u64 v[58:59], s[82:83], 0, v[148:149]
	s_mov_b32 m0, s77
	s_add_i32 s79, s77, 0x2000
	global_load_lds_dwordx4 v[58:59], off
	v_lshl_add_u64 v[58:59], s[82:83], 0, v[144:145]
	s_mov_b32 m0, s79
	s_nop 0
	global_load_lds_dwordx4 v[58:59], off
	v_lshl_add_u64 v[58:59], v[4:5], 0, s[22:23]
	s_mov_b32 m0, s53
	s_nop 0
	global_load_lds_dwordx4 v[58:59], off
	v_lshl_add_u64 v[58:59], v[6:7], 0, s[22:23]
	s_mov_b32 m0, s54
	s_nop 0
	global_load_lds_dwordx4 v[58:59], off
	s_waitcnt vmcnt(8)
	s_waitcnt lgkmcnt(0)
	s_barrier
; #define PG8_STAGE(bufoff, gbase, voff) do { _Pragma("unroll") for (int _i = 0; _i < 2; ++_i) \
;         __builtin_amdgcn_global_load_lds((const unsigned*)((const char*)(gbase) + (voff)[_i]), (PG8_LAS unsigned*)(lds + (bufoff) + ldsw + _i * 8192), 16, 0, 0); } while (0)
; #define PG8_LDA(dst, b, h) do { _Pragma("unroll") for (int m = 0; m < 4; ++m) _Pragma("unroll") for (int k = 0; k < 2; ++k) dst[m][k] = *(const PG8_LAS bf16x8*)(lds + PG8_SA(b, h) + aoff + m * 2048 + k * 1024); } while (0)
; #define PG8_LDB(dst, b, h) do { _Pragma("unroll") for (int n = 0; n < 2; ++n) _Pragma("unroll") for (int k = 0; k < 2; ++k) dst[n][k] = *(const PG8_LAS bf16x8*)(lds + PG8_SB(b, h) + boff + n * 2048 + k * 1024); } while (0)
; #define PG8_MMA(ai, bj, At, Bt) do { __builtin_amdgcn_s_setprio(1); _Pragma("unroll") for (int m = 0; m < 4; ++m) _Pragma("unroll") for (int n = 0; n < 2; ++n) _Pragma("unroll") for (int k = 0; k < 2; ++k) \
;         acc[ai][bj][m][n] = __builtin_amdgcn_mfma_f32_16x16x32_bf16(Bt[n][k], At[m][k], acc[ai][bj][m][n], 0, 0, 0); __builtin_amdgcn_s_setprio(0); } while (0)
; #define PG8_WAIT_V(n) asm volatile("s_waitcnt vmcnt(" #n ")" ::: "memory")
; #define PG8_WAIT_L(n) asm volatile("s_waitcnt lgkmcnt(" #n ")" ::: "memory")
; #define PG8_BAR __builtin_amdgcn_s_barrier()
; #define PG8_SCHED __builtin_amdgcn_sched_barrier(0)
; template <class Epi, class Sched, bool ALIGN_EPI = false, bool SP2 = false>
; __device__ __forceinline__ void gemm_phase(PG8_LAS unsigned char* lds, const Gemm g, const Sched& S, const Epi& E, const int wid) {
;     ...
;             PG8_LDB(B0, 0, 0); PG8_LDB(B1, 0, 1); PG8_SCHED; PG8_LDA(At, 0, 0); PG8_STAGE(PG8_SA(1, 1), a1 + hsA, voffA);
;             PG8_WAIT_V(8); PG8_WAIT_L(0); PG8_BAR; PG8_MMA(0, 0, At, B0); PG8_MMA(0, 1, At, B1); PG8_BAR; PG8_SCHED;
;             PG8_LDA(At, 0, 1); PG8_STAGE(PG8_SB(0, 0), b2, voffB); PG8_STAGE(PG8_SB(0, 1), b2 + hsB, voffB); PG8_STAGE(PG8_SA(0, 0), a2, voffA);
;     ...
;             PG8_LDA(At, 1, 1); PG8_STAGE(PG8_SB(1, 0), b3, voffB); PG8_STAGE(PG8_SB(1, 1), b3 + hsB, voffB); PG8_STAGE(PG8_SA(1, 0), a3, voffA);
;             PG8_WAIT_V(8); PG8_WAIT_L(0); PG8_BAR; PG8_MMA(1, 0, At, B0); PG8_MMA(1, 1, At, B1); PG8_BAR; PG8_SCHED;
	s_setprio 1
	s_waitcnt lgkmcnt(0)
	v_mfma_f32_16x16x32_bf16 v[136:139], v[30:33], v[190:193], v[136:139]
	v_mfma_f32_16x16x32_bf16 v[10:13], v[30:33], v[214:217], v[10:13]
	v_mfma_f32_16x16x32_bf16 v[14:17], v[124:127], v[214:217], v[14:17]
	v_mfma_f32_16x16x32_bf16 v[136:139], v[34:37], v[194:197], v[136:139]
	v_mfma_f32_16x16x32_bf16 v[140:143], v[124:127], v[190:193], v[140:143]
	v_mfma_f32_16x16x32_bf16 v[158:161], v[30:33], v[198:201], v[158:161]
	v_mfma_f32_16x16x32_bf16 v[166:169], v[124:127], v[198:201], v[166:169]
	v_mfma_f32_16x16x32_bf16 v[170:173], v[30:33], v[206:209], v[170:173]
	v_mfma_f32_16x16x32_bf16 v[174:177], v[124:127], v[206:209], v[174:177]
	v_mfma_f32_16x16x32_bf16 v[10:13], v[34:37], v[218:221], v[10:13]
	v_mfma_f32_16x16x32_bf16 v[14:17], v[128:131], v[218:221], v[14:17]
	v_mfma_f32_16x16x32_bf16 v[140:143], v[128:131], v[194:197], v[140:143]
	v_mfma_f32_16x16x32_bf16 v[158:161], v[34:37], v[202:205], v[158:161]
	v_mfma_f32_16x16x32_bf16 v[166:169], v[128:131], v[202:205], v[166:169]
	v_mfma_f32_16x16x32_bf16 v[170:173], v[34:37], v[210:213], v[170:173]
	v_mfma_f32_16x16x32_bf16 v[174:177], v[128:131], v[210:213], v[174:177]
	v_mfma_f32_16x16x32_bf16 v[30:33], v[182:185], v[190:193], v[60:63]
	v_mfma_f32_16x16x32_bf16 v[34:37], v[132:135], v[198:201], v[108:111]
	v_mfma_f32_16x16x32_bf16 v[58:61], v[182:185], v[198:201], v[112:115]
	v_mfma_f32_16x16x32_bf16 v[108:111], v[132:135], v[206:209], v[116:119]
	v_mfma_f32_16x16x32_bf16 v[112:115], v[182:185], v[206:209], v[120:123]
	v_mfma_f32_16x16x32_bf16 v[22:25], v[132:135], v[214:217], v[22:25]
	v_mfma_f32_16x16x32_bf16 v[26:29], v[182:185], v[214:217], v[26:29]
	v_mfma_f32_16x16x32_bf16 v[18:21], v[132:135], v[190:193], v[18:21]
	v_mfma_f32_16x16x32_bf16 v[30:33], v[186:189], v[194:197], v[30:33]
	v_mfma_f32_16x16x32_bf16 v[34:37], v[178:181], v[202:205], v[34:37]
	v_mfma_f32_16x16x32_bf16 v[58:61], v[186:189], v[202:205], v[58:61]
	v_mfma_f32_16x16x32_bf16 v[108:111], v[178:181], v[210:213], v[108:111]
	v_mfma_f32_16x16x32_bf16 v[112:115], v[186:189], v[210:213], v[112:115]
	v_mfma_f32_16x16x32_bf16 v[22:25], v[178:181], v[218:221], v[22:25]
	v_mfma_f32_16x16x32_bf16 v[26:29], v[186:189], v[218:221], v[26:29]
	v_mfma_f32_16x16x32_bf16 v[18:21], v[178:181], v[194:197], v[18:21]
	s_setprio 0
	s_barrier
	ds_read_b128 v[116:119], v164
	ds_read_b128 v[120:123], v164 offset:1024
	ds_read_b128 v[124:127], v164 offset:2048
	ds_read_b128 v[128:131], v164 offset:3072
	ds_read_b128 v[132:135], v165
	ds_read_b128 v[178:181], v165 offset:1024
	ds_read_b128 v[182:185], v165 offset:2048
	ds_read_b128 v[186:189], v165 offset:3072
	s_add_u32 s82, s40, 0x600180
	s_addc_u32 s83, s41, 0
	s_mov_b32 m0, s78
	v_lshl_add_u64 v[62:63], s[82:83], 0, v[150:151]
	ds_read_b128 v[190:193], v163
	ds_read_b128 v[194:197], v163 offset:1024
	ds_read_b128 v[198:201], v163 offset:2048
	ds_read_b128 v[202:205], v163 offset:3072
	ds_read_b128 v[206:209], v163 offset:4096
	ds_read_b128 v[210:213], v163 offset:5120
	ds_read_b128 v[214:217], v163 offset:6144
	ds_read_b128 v[218:221], v163 offset:7168
	global_load_lds_dwordx4 v[62:63], off
	v_lshl_add_u64 v[62:63], s[82:83], 0, v[146:147]
	s_mov_b32 m0, s65
	s_nop 0
	global_load_lds_dwordx4 v[62:63], off
	s_waitcnt vmcnt(8)
	s_waitcnt lgkmcnt(0)
	s_barrier
	s_setprio 1
	s_waitcnt lgkmcnt(0)
	v_mfma_f32_16x16x32_bf16 v[62:65], v[116:119], v[190:193], v[64:67]
	v_mfma_f32_16x16x32_bf16 v[66:69], v[124:127], v[190:193], v[68:71]
	v_mfma_f32_16x16x32_bf16 v[70:73], v[116:119], v[198:201], v[72:75]
	v_mfma_f32_16x16x32_bf16 v[74:77], v[124:127], v[198:201], v[76:79]
	v_mfma_f32_16x16x32_bf16 v[78:81], v[116:119], v[206:209], v[80:83]
	v_mfma_f32_16x16x32_bf16 v[82:85], v[124:127], v[206:209], v[84:87]
	v_mfma_f32_16x16x32_bf16 v[86:89], v[116:119], v[214:217], v[88:91]
	v_mfma_f32_16x16x32_bf16 v[90:93], v[124:127], v[214:217], v[92:95]
	v_mfma_f32_16x16x32_bf16 v[62:65], v[120:123], v[194:197], v[62:65]
	v_mfma_f32_16x16x32_bf16 v[66:69], v[128:131], v[194:197], v[66:69]
	v_mfma_f32_16x16x32_bf16 v[70:73], v[120:123], v[202:205], v[70:73]
	v_mfma_f32_16x16x32_bf16 v[74:77], v[128:131], v[202:205], v[74:77]
	v_mfma_f32_16x16x32_bf16 v[78:81], v[120:123], v[210:213], v[78:81]
	v_mfma_f32_16x16x32_bf16 v[82:85], v[128:131], v[210:213], v[82:85]
	v_mfma_f32_16x16x32_bf16 v[86:89], v[120:123], v[218:221], v[86:89]
	v_mfma_f32_16x16x32_bf16 v[90:93], v[128:131], v[218:221], v[90:93]
	v_mfma_f32_16x16x32_bf16 v[94:97], v[132:135], v[190:193], v[96:99]
	v_mfma_f32_16x16x32_bf16 v[98:101], v[182:185], v[190:193], v[100:103]
	v_mfma_f32_16x16x32_bf16 v[102:105], v[132:135], v[198:201], v[104:107]
	v_mfma_f32_16x16x32_bf16 v[38:41], v[182:185], v[198:201], v[38:41]
	v_mfma_f32_16x16x32_bf16 v[42:45], v[132:135], v[206:209], v[42:45]
	v_mfma_f32_16x16x32_bf16 v[46:49], v[182:185], v[206:209], v[46:49]
	v_mfma_f32_16x16x32_bf16 v[50:53], v[132:135], v[214:217], v[50:53]
	v_mfma_f32_16x16x32_bf16 v[54:57], v[182:185], v[214:217], v[54:57]
	v_mfma_f32_16x16x32_bf16 v[94:97], v[178:181], v[194:197], v[94:97]
	v_mfma_f32_16x16x32_bf16 v[98:101], v[186:189], v[194:197], v[98:101]
	v_mfma_f32_16x16x32_bf16 v[102:105], v[178:181], v[202:205], v[102:105]
	v_mfma_f32_16x16x32_bf16 v[38:41], v[186:189], v[202:205], v[38:41]
	v_mfma_f32_16x16x32_bf16 v[42:45], v[178:181], v[210:213], v[42:45]
	v_mfma_f32_16x16x32_bf16 v[46:49], v[186:189], v[210:213], v[46:49]
	v_mfma_f32_16x16x32_bf16 v[50:53], v[178:181], v[218:221], v[50:53]
	v_mfma_f32_16x16x32_bf16 v[54:57], v[186:189], v[218:221], v[54:57]
	s_setprio 0
	s_barrier
; #define PG8_STAGE(bufoff, gbase, voff) do { _Pragma("unroll") for (int _i = 0; _i < 2; ++_i) \
;         __builtin_amdgcn_global_load_lds((const unsigned*)((const char*)(gbase) + (voff)[_i]), (PG8_LAS unsigned*)(lds + (bufoff) + ldsw + _i * 8192), 16, 0, 0); } while (0)
; #define PG8_LDA(dst, b, h) do { _Pragma("unroll") for (int m = 0; m < 4; ++m) _Pragma("unroll") for (int k = 0; k < 2; ++k) dst[m][k] = *(const PG8_LAS bf16x8*)(lds + PG8_SA(b, h) + aoff + m * 2048 + k * 1024); } while (0)
; #define PG8_LDB(dst, b, h) do { _Pragma("unroll") for (int n = 0; n < 2; ++n) _Pragma("unroll") for (int k = 0; k < 2; ++k) dst[n][k] = *(const PG8_LAS bf16x8*)(lds + PG8_SB(b, h) + boff + n * 2048 + k * 1024); } while (0)
; #define PG8_MMA(ai, bj, At, Bt) do { __builtin_amdgcn_s_setprio(1); _Pragma("unroll") for (int m = 0; m < 4; ++m) _Pragma("unroll") for (int n = 0; n < 2; ++n) _Pragma("unroll") for (int k = 0; k < 2; ++k) \
;         acc[ai][bj][m][n] = __builtin_amdgcn_mfma_f32_16x16x32_bf16(Bt[n][k], At[m][k], acc[ai][bj][m][n], 0, 0, 0); __builtin_amdgcn_s_setprio(0); } while (0)
; #define PG8_WAIT_V(n) asm volatile("s_waitcnt vmcnt(" #n ")" ::: "memory")
; #define PG8_WAIT_L(n) asm volatile("s_waitcnt lgkmcnt(" #n ")" ::: "memory")
; #define PG8_BAR __builtin_amdgcn_s_barrier()
; #define PG8_SCHED __builtin_amdgcn_sched_barrier(0)
; template <class Epi, class Sched, bool ALIGN_EPI = false, bool SP2 = false>
; __device__ __forceinline__ void gemm_phase(PG8_LAS unsigned char* lds, const Gemm g, const Sched& S, const Epi& E, const int wid) {
;     ...
;             PG8_LDA(At, 0, 1); PG8_STAGE(PG8_SB(0, 0), b2, voffB); PG8_STAGE(PG8_SB(0, 1), b2 + hsB, voffB); PG8_STAGE(PG8_SA(0, 0), a2, voffA);
;             PG8_WAIT_V(8); PG8_WAIT_L(0); PG8_BAR; PG8_MMA(1, 0, At, B0); PG8_MMA(1, 1, At, B1); PG8_BAR; PG8_SCHED;
;             PG8_LDB(B0, 1, 0); PG8_LDB(B1, 1, 1); PG8_SCHED; PG8_LDA(At, 1, 0); PG8_STAGE(PG8_SA(0, 1), a2 + hsA, voffA);
;             PG8_WAIT_V(8); PG8_WAIT_L(0); PG8_BAR; PG8_MMA(0, 0, At, B0); PG8_MMA(0, 1, At, B1); PG8_BAR; PG8_SCHED;
	s_mov_b32 m0, s75
	v_lshl_add_u64 v[106:107], v[0:1], 0, s[24:25]
	s_add_u32 s82, s42, 0x18200
	ds_read_b128 v[190:193], v163 offset:16384
	ds_read_b128 v[194:197], v163 offset:17408
	ds_read_b128 v[198:201], v163 offset:18432
	ds_read_b128 v[202:205], v163 offset:19456
	ds_read_b128 v[206:209], v163 offset:20480
	ds_read_b128 v[210:213], v163 offset:21504
	ds_read_b128 v[214:217], v163 offset:22528
	ds_read_b128 v[218:221], v163 offset:23552
	global_load_lds_dwordx4 v[106:107], off
	v_lshl_add_u64 v[106:107], v[2:3], 0, s[24:25]
	s_mov_b32 m0, s66
	s_addc_u32 s83, s43, 0
	global_load_lds_dwordx4 v[106:107], off
	v_lshl_add_u64 v[106:107], s[82:83], 0, v[148:149]
	s_mov_b32 m0, s67
	s_nop 0
	global_load_lds_dwordx4 v[106:107], off
	v_lshl_add_u64 v[106:107], s[82:83], 0, v[144:145]
	s_mov_b32 m0, s74
	s_nop 0
	global_load_lds_dwordx4 v[106:107], off
	v_lshl_add_u64 v[106:107], v[4:5], 0, s[24:25]
	s_mov_b32 m0, s46
	s_nop 0
	global_load_lds_dwordx4 v[106:107], off
	v_lshl_add_u64 v[106:107], v[6:7], 0, s[24:25]
	s_mov_b32 m0, s47
	s_nop 0
	global_load_lds_dwordx4 v[106:107], off
	s_waitcnt vmcnt(8)
	s_waitcnt lgkmcnt(0)
	s_barrier
	s_setprio 1
	s_waitcnt lgkmcnt(0)
	v_mfma_f32_16x16x32_bf16 v[136:139], v[116:119], v[190:193], v[136:139]
	v_mfma_f32_16x16x32_bf16 v[10:13], v[116:119], v[214:217], v[10:13]
	v_mfma_f32_16x16x32_bf16 v[14:17], v[124:127], v[214:217], v[14:17]
	v_mfma_f32_16x16x32_bf16 v[136:139], v[120:123], v[194:197], v[136:139]
	v_mfma_f32_16x16x32_bf16 v[140:143], v[124:127], v[190:193], v[140:143]
	v_mfma_f32_16x16x32_bf16 v[158:161], v[116:119], v[198:201], v[158:161]
	v_mfma_f32_16x16x32_bf16 v[166:169], v[124:127], v[198:201], v[166:169]
	v_mfma_f32_16x16x32_bf16 v[170:173], v[116:119], v[206:209], v[170:173]
	v_mfma_f32_16x16x32_bf16 v[174:177], v[124:127], v[206:209], v[174:177]
	v_mfma_f32_16x16x32_bf16 v[10:13], v[120:123], v[218:221], v[10:13]
	v_mfma_f32_16x16x32_bf16 v[14:17], v[128:131], v[218:221], v[14:17]
	v_mfma_f32_16x16x32_bf16 v[140:143], v[128:131], v[194:197], v[140:143]
	v_mfma_f32_16x16x32_bf16 v[158:161], v[120:123], v[202:205], v[158:161]
	v_mfma_f32_16x16x32_bf16 v[166:169], v[128:131], v[202:205], v[166:169]
	v_mfma_f32_16x16x32_bf16 v[170:173], v[120:123], v[210:213], v[170:173]
	v_mfma_f32_16x16x32_bf16 v[174:177], v[128:131], v[210:213], v[174:177]
	v_mfma_f32_16x16x32_bf16 v[30:33], v[182:185], v[190:193], v[30:33]
	v_mfma_f32_16x16x32_bf16 v[34:37], v[132:135], v[198:201], v[34:37]
	v_mfma_f32_16x16x32_bf16 v[58:61], v[182:185], v[198:201], v[58:61]
	v_mfma_f32_16x16x32_bf16 v[106:109], v[132:135], v[206:209], v[108:111]
	v_mfma_f32_16x16x32_bf16 v[110:113], v[182:185], v[206:209], v[112:115]
	v_mfma_f32_16x16x32_bf16 v[22:25], v[132:135], v[214:217], v[22:25]
	v_mfma_f32_16x16x32_bf16 v[26:29], v[182:185], v[214:217], v[26:29]
	v_mfma_f32_16x16x32_bf16 v[18:21], v[132:135], v[190:193], v[18:21]
	v_mfma_f32_16x16x32_bf16 v[30:33], v[186:189], v[194:197], v[30:33]
	v_mfma_f32_16x16x32_bf16 v[34:37], v[178:181], v[202:205], v[34:37]
	v_mfma_f32_16x16x32_bf16 v[58:61], v[186:189], v[202:205], v[58:61]
	v_mfma_f32_16x16x32_bf16 v[106:109], v[178:181], v[210:213], v[106:109]
	v_mfma_f32_16x16x32_bf16 v[110:113], v[186:189], v[210:213], v[110:113]
	v_mfma_f32_16x16x32_bf16 v[22:25], v[178:181], v[218:221], v[22:25]
	v_mfma_f32_16x16x32_bf16 v[26:29], v[186:189], v[218:221], v[26:29]
	v_mfma_f32_16x16x32_bf16 v[18:21], v[178:181], v[194:197], v[18:21]
	s_setprio 0
	s_barrier
	ds_read_b128 v[114:117], v8
	ds_read_b128 v[118:121], v8 offset:1024
	ds_read_b128 v[122:125], v8 offset:2048
	ds_read_b128 v[126:129], v8 offset:3072
	ds_read_b128 v[130:133], v9
	ds_read_b128 v[178:181], v9 offset:1024
	ds_read_b128 v[182:185], v9 offset:2048
	ds_read_b128 v[186:189], v9 offset:3072
	s_add_u32 s82, s40, 0x600200
	s_addc_u32 s83, s41, 0
	s_mov_b32 m0, s48
	v_lshl_add_u64 v[134:135], s[82:83], 0, v[150:151]
	ds_read_b128 v[190:193], v163 offset:32768
	ds_read_b128 v[194:197], v163 offset:33792
	ds_read_b128 v[198:201], v163 offset:34816
	ds_read_b128 v[202:205], v163 offset:35840
	ds_read_b128 v[206:209], v163 offset:36864
	ds_read_b128 v[210:213], v163 offset:37888
	ds_read_b128 v[214:217], v163 offset:38912
	ds_read_b128 v[218:221], v163 offset:39936
	global_load_lds_dwordx4 v[134:135], off
	v_lshl_add_u64 v[134:135], s[82:83], 0, v[146:147]
	s_mov_b32 m0, s49
	s_nop 0
	global_load_lds_dwordx4 v[134:135], off
	s_waitcnt vmcnt(8)
	s_waitcnt lgkmcnt(0)
	s_barrier
	s_setprio 1
	s_waitcnt lgkmcnt(0)
	v_mfma_f32_16x16x32_bf16 v[62:65], v[114:117], v[190:193], v[62:65]
	v_mfma_f32_16x16x32_bf16 v[66:69], v[122:125], v[190:193], v[66:69]
	v_mfma_f32_16x16x32_bf16 v[70:73], v[114:117], v[198:201], v[70:73]
	v_mfma_f32_16x16x32_bf16 v[74:77], v[122:125], v[198:201], v[74:77]
	v_mfma_f32_16x16x32_bf16 v[78:81], v[114:117], v[206:209], v[78:81]
	v_mfma_f32_16x16x32_bf16 v[82:85], v[122:125], v[206:209], v[82:85]
	v_mfma_f32_16x16x32_bf16 v[86:89], v[114:117], v[214:217], v[86:89]
	v_mfma_f32_16x16x32_bf16 v[90:93], v[122:125], v[214:217], v[90:93]
	v_mfma_f32_16x16x32_bf16 v[62:65], v[118:121], v[194:197], v[62:65]
	v_mfma_f32_16x16x32_bf16 v[66:69], v[126:129], v[194:197], v[66:69]
	v_mfma_f32_16x16x32_bf16 v[70:73], v[118:121], v[202:205], v[70:73]
	v_mfma_f32_16x16x32_bf16 v[74:77], v[126:129], v[202:205], v[74:77]
	v_mfma_f32_16x16x32_bf16 v[78:81], v[118:121], v[210:213], v[78:81]
	v_mfma_f32_16x16x32_bf16 v[82:85], v[126:129], v[210:213], v[82:85]
	v_mfma_f32_16x16x32_bf16 v[86:89], v[118:121], v[218:221], v[86:89]
	v_mfma_f32_16x16x32_bf16 v[90:93], v[126:129], v[218:221], v[90:93]
	v_mfma_f32_16x16x32_bf16 v[94:97], v[130:133], v[190:193], v[94:97]
	v_mfma_f32_16x16x32_bf16 v[98:101], v[182:185], v[190:193], v[98:101]
	v_mfma_f32_16x16x32_bf16 v[102:105], v[130:133], v[198:201], v[102:105]
	v_mfma_f32_16x16x32_bf16 v[38:41], v[182:185], v[198:201], v[38:41]
	v_mfma_f32_16x16x32_bf16 v[42:45], v[130:133], v[206:209], v[42:45]
	v_mfma_f32_16x16x32_bf16 v[46:49], v[182:185], v[206:209], v[46:49]
	v_mfma_f32_16x16x32_bf16 v[50:53], v[130:133], v[214:217], v[50:53]
	v_mfma_f32_16x16x32_bf16 v[54:57], v[182:185], v[214:217], v[54:57]
	v_mfma_f32_16x16x32_bf16 v[94:97], v[178:181], v[194:197], v[94:97]
	v_mfma_f32_16x16x32_bf16 v[98:101], v[186:189], v[194:197], v[98:101]
	v_mfma_f32_16x16x32_bf16 v[102:105], v[178:181], v[202:205], v[102:105]
	v_mfma_f32_16x16x32_bf16 v[38:41], v[186:189], v[202:205], v[38:41]
	v_mfma_f32_16x16x32_bf16 v[42:45], v[178:181], v[210:213], v[42:45]
	v_mfma_f32_16x16x32_bf16 v[46:49], v[186:189], v[210:213], v[46:49]
	v_mfma_f32_16x16x32_bf16 v[50:53], v[178:181], v[218:221], v[50:53]
	v_mfma_f32_16x16x32_bf16 v[54:57], v[186:189], v[218:221], v[54:57]
	s_setprio 0
	s_barrier
; #define PG8_STAGE(bufoff, gbase, voff) do { _Pragma("unroll") for (int _i = 0; _i < 2; ++_i) \
;         __builtin_amdgcn_global_load_lds((const unsigned*)((const char*)(gbase) + (voff)[_i]), (PG8_LAS unsigned*)(lds + (bufoff) + ldsw + _i * 8192), 16, 0, 0); } while (0)
; #define PG8_LDA(dst, b, h) do { _Pragma("unroll") for (int m = 0; m < 4; ++m) _Pragma("unroll") for (int k = 0; k < 2; ++k) dst[m][k] = *(const PG8_LAS bf16x8*)(lds + PG8_SA(b, h) + aoff + m * 2048 + k * 1024); } while (0)
; #define PG8_LDB(dst, b, h) do { _Pragma("unroll") for (int n = 0; n < 2; ++n) _Pragma("unroll") for (int k = 0; k < 2; ++k) dst[n][k] = *(const PG8_LAS bf16x8*)(lds + PG8_SB(b, h) + boff + n * 2048 + k * 1024); } while (0)
; #define PG8_MMA(ai, bj, At, Bt) do { __builtin_amdgcn_s_setprio(1); _Pragma("unroll") for (int m = 0; m < 4; ++m) _Pragma("unroll") for (int n = 0; n < 2; ++n) _Pragma("unroll") for (int k = 0; k < 2; ++k) \
;         acc[ai][bj][m][n] = __builtin_amdgcn_mfma_f32_16x16x32_bf16(Bt[n][k], At[m][k], acc[ai][bj][m][n], 0, 0, 0); __builtin_amdgcn_s_setprio(0); } while (0)
; #define PG8_WAIT_V(n) asm volatile("s_waitcnt vmcnt(" #n ")" ::: "memory")
; #define PG8_WAIT_L(n) asm volatile("s_waitcnt lgkmcnt(" #n ")" ::: "memory")
; #define PG8_BAR __builtin_amdgcn_s_barrier()
; #define PG8_SCHED __builtin_amdgcn_sched_barrier(0)
; template <class Epi, class Sched, bool ALIGN_EPI = false, bool SP2 = false>
; __device__ __forceinline__ void gemm_phase(PG8_LAS unsigned char* lds, const Gemm g, const Sched& S, const Epi& E, const int wid) {
;     ...
;             PG8_LDB(B0, 0, 0); PG8_LDB(B1, 0, 1); PG8_SCHED; PG8_LDA(At, 0, 0); PG8_STAGE(PG8_SA(1, 1), a1 + hsA, voffA);
;             PG8_WAIT_V(8); PG8_WAIT_L(0); PG8_BAR; PG8_MMA(0, 0, At, B0); PG8_MMA(0, 1, At, B1); PG8_BAR; PG8_SCHED;
;             PG8_LDA(At, 0, 1); PG8_STAGE(PG8_SB(0, 0), b2, voffB); PG8_STAGE(PG8_SB(0, 1), b2 + hsB, voffB); PG8_STAGE(PG8_SA(0, 0), a2, voffA);
;     ...
;             PG8_LDA(At, 1, 1); PG8_STAGE(PG8_SB(1, 0), b3, voffB); PG8_STAGE(PG8_SB(1, 1), b3 + hsB, voffB); PG8_STAGE(PG8_SA(1, 0), a3, voffA);
;             PG8_WAIT_V(8); PG8_WAIT_L(0); PG8_BAR; PG8_MMA(1, 0, At, B0); PG8_MMA(1, 1, At, B1); PG8_BAR; PG8_SCHED;
	s_mov_b32 m0, s81
	v_lshl_add_u64 v[0:1], v[0:1], 0, s[26:27]
	s_add_u32 s42, s42, 0x18280
	ds_read_b128 v[190:193], v163 offset:49152
	ds_read_b128 v[194:197], v163 offset:50176
	ds_read_b128 v[198:201], v163 offset:51200
	ds_read_b128 v[202:205], v163 offset:52224
	ds_read_b128 v[206:209], v163 offset:53248
	ds_read_b128 v[210:213], v163 offset:54272
	ds_read_b128 v[214:217], v163 offset:55296
	ds_read_b128 v[218:221], v163 offset:56320
	global_load_lds_dwordx4 v[0:1], off
	v_lshl_add_u64 v[0:1], v[2:3], 0, s[26:27]
	s_mov_b32 m0, s76
	s_addc_u32 s43, s43, 0
	global_load_lds_dwordx4 v[0:1], off
	v_lshl_add_u64 v[0:1], s[42:43], 0, v[148:149]
	s_mov_b32 m0, s77
	s_nop 0
	global_load_lds_dwordx4 v[0:1], off
	v_lshl_add_u64 v[0:1], s[42:43], 0, v[144:145]
	s_mov_b32 m0, s79
	s_nop 0
	global_load_lds_dwordx4 v[0:1], off
	v_lshl_add_u64 v[0:1], v[4:5], 0, s[26:27]
	s_mov_b32 m0, s53
	s_nop 0
	global_load_lds_dwordx4 v[0:1], off
	v_lshl_add_u64 v[0:1], v[6:7], 0, s[26:27]
	s_mov_b32 m0, s54
	s_nop 0
	global_load_lds_dwordx4 v[0:1], off
	s_waitcnt vmcnt(8)
	s_waitcnt lgkmcnt(0)
	s_barrier
	s_setprio 1
	s_waitcnt lgkmcnt(0)
	v_mfma_f32_16x16x32_bf16 v[0:3], v[114:117], v[190:193], v[136:139]
	v_mfma_f32_16x16x32_bf16 v[4:7], v[122:125], v[190:193], v[140:143]
	v_mfma_f32_16x16x32_bf16 v[134:137], v[114:117], v[198:201], v[158:161]
	v_mfma_f32_16x16x32_bf16 v[138:141], v[122:125], v[198:201], v[166:169]
	v_mfma_f32_16x16x32_bf16 v[10:13], v[114:117], v[214:217], v[10:13]
	v_mfma_f32_16x16x32_bf16 v[14:17], v[122:125], v[214:217], v[14:17]
	v_mfma_f32_16x16x32_bf16 v[0:3], v[118:121], v[194:197], v[0:3]
	v_mfma_f32_16x16x32_bf16 v[4:7], v[126:129], v[194:197], v[4:7]
	v_mfma_f32_16x16x32_bf16 v[134:137], v[118:121], v[202:205], v[134:137]
	v_mfma_f32_16x16x32_bf16 v[138:141], v[126:129], v[202:205], v[138:141]
	v_mfma_f32_16x16x32_bf16 v[158:161], v[114:117], v[206:209], v[170:173]
	v_mfma_f32_16x16x32_bf16 v[166:169], v[122:125], v[206:209], v[174:177]
	v_mfma_f32_16x16x32_bf16 v[10:13], v[118:121], v[218:221], v[10:13]
	v_mfma_f32_16x16x32_bf16 v[14:17], v[126:129], v[218:221], v[14:17]
	v_mfma_f32_16x16x32_bf16 v[158:161], v[118:121], v[210:213], v[158:161]
	v_mfma_f32_16x16x32_bf16 v[166:169], v[126:129], v[210:213], v[166:169]
	v_mfma_f32_16x16x32_bf16 v[30:33], v[182:185], v[190:193], v[30:33]
	v_mfma_f32_16x16x32_bf16 v[34:37], v[130:133], v[198:201], v[34:37]
	v_mfma_f32_16x16x32_bf16 v[58:61], v[182:185], v[198:201], v[58:61]
	v_mfma_f32_16x16x32_bf16 v[106:109], v[130:133], v[206:209], v[106:109]
	v_mfma_f32_16x16x32_bf16 v[110:113], v[182:185], v[206:209], v[110:113]
	v_mfma_f32_16x16x32_bf16 v[22:25], v[130:133], v[214:217], v[22:25]
	v_mfma_f32_16x16x32_bf16 v[26:29], v[182:185], v[214:217], v[26:29]
	v_mfma_f32_16x16x32_bf16 v[18:21], v[130:133], v[190:193], v[18:21]
	v_mfma_f32_16x16x32_bf16 v[30:33], v[186:189], v[194:197], v[30:33]
	v_mfma_f32_16x16x32_bf16 v[34:37], v[178:181], v[202:205], v[34:37]
	v_mfma_f32_16x16x32_bf16 v[58:61], v[186:189], v[202:205], v[58:61]
	v_mfma_f32_16x16x32_bf16 v[106:109], v[178:181], v[210:213], v[106:109]
	v_mfma_f32_16x16x32_bf16 v[110:113], v[186:189], v[210:213], v[110:113]
	v_mfma_f32_16x16x32_bf16 v[22:25], v[178:181], v[218:221], v[22:25]
	v_mfma_f32_16x16x32_bf16 v[26:29], v[186:189], v[218:221], v[26:29]
	v_mfma_f32_16x16x32_bf16 v[18:21], v[178:181], v[194:197], v[18:21]
	s_setprio 0
	s_barrier
	ds_read_b128 v[114:117], v164
	ds_read_b128 v[118:121], v164 offset:1024
	ds_read_b128 v[122:125], v164 offset:2048
	ds_read_b128 v[126:129], v164 offset:3072
	ds_read_b128 v[130:133], v165
	ds_read_b128 v[170:173], v165 offset:1024
	ds_read_b128 v[174:177], v165 offset:2048
	ds_read_b128 v[178:181], v165 offset:3072
	s_add_u32 s40, s40, 0x600280
	s_addc_u32 s41, s41, 0
	s_mov_b32 m0, s78
	v_lshl_add_u64 v[142:143], s[40:41], 0, v[150:151]
	ds_read_b128 v[182:185], v163
	ds_read_b128 v[186:189], v163 offset:1024
	ds_read_b128 v[190:193], v163 offset:2048
	ds_read_b128 v[194:197], v163 offset:3072
	ds_read_b128 v[198:201], v163 offset:4096
	ds_read_b128 v[202:205], v163 offset:5120
	ds_read_b128 v[206:209], v163 offset:6144
	ds_read_b128 v[210:213], v163 offset:7168
	global_load_lds_dwordx4 v[142:143], off
	v_lshl_add_u64 v[142:143], s[40:41], 0, v[146:147]
	s_mov_b32 m0, s65
	s_nop 0
	global_load_lds_dwordx4 v[142:143], off
	s_waitcnt vmcnt(8)
	s_waitcnt lgkmcnt(0)
	s_barrier
	s_setprio 1
	s_waitcnt lgkmcnt(0)
	v_mfma_f32_16x16x32_bf16 v[62:65], v[114:117], v[182:185], v[62:65]
	v_mfma_f32_16x16x32_bf16 v[66:69], v[122:125], v[182:185], v[66:69]
	v_mfma_f32_16x16x32_bf16 v[70:73], v[114:117], v[190:193], v[70:73]
	v_mfma_f32_16x16x32_bf16 v[74:77], v[122:125], v[190:193], v[74:77]
	v_mfma_f32_16x16x32_bf16 v[78:81], v[114:117], v[198:201], v[78:81]
	v_mfma_f32_16x16x32_bf16 v[82:85], v[122:125], v[198:201], v[82:85]
	v_mfma_f32_16x16x32_bf16 v[86:89], v[114:117], v[206:209], v[86:89]
	v_mfma_f32_16x16x32_bf16 v[90:93], v[122:125], v[206:209], v[90:93]
	v_mfma_f32_16x16x32_bf16 v[62:65], v[118:121], v[186:189], v[62:65]
	v_mfma_f32_16x16x32_bf16 v[66:69], v[126:129], v[186:189], v[66:69]
	v_mfma_f32_16x16x32_bf16 v[70:73], v[118:121], v[194:197], v[70:73]
	v_mfma_f32_16x16x32_bf16 v[74:77], v[126:129], v[194:197], v[74:77]
	v_mfma_f32_16x16x32_bf16 v[78:81], v[118:121], v[202:205], v[78:81]
	v_mfma_f32_16x16x32_bf16 v[82:85], v[126:129], v[202:205], v[82:85]
	v_mfma_f32_16x16x32_bf16 v[86:89], v[118:121], v[210:213], v[86:89]
	v_mfma_f32_16x16x32_bf16 v[90:93], v[126:129], v[210:213], v[90:93]
	v_mfma_f32_16x16x32_bf16 v[94:97], v[130:133], v[182:185], v[94:97]
	v_mfma_f32_16x16x32_bf16 v[214:217], v[170:173], v[186:189], v[94:97]
	v_mfma_f32_16x16x32_bf16 v[94:97], v[174:177], v[182:185], v[98:101]
	v_mfma_f32_16x16x32_bf16 v[38:41], v[174:177], v[190:193], v[38:41]
	v_mfma_f32_16x16x32_bf16 v[42:45], v[130:133], v[198:201], v[42:45]
	v_mfma_f32_16x16x32_bf16 v[46:49], v[174:177], v[198:201], v[46:49]
	v_mfma_f32_16x16x32_bf16 v[50:53], v[130:133], v[206:209], v[50:53]
	v_mfma_f32_16x16x32_bf16 v[54:57], v[174:177], v[206:209], v[54:57]
	v_mfma_f32_16x16x32_bf16 v[182:185], v[178:181], v[186:189], v[94:97]
	v_mfma_f32_16x16x32_bf16 v[94:97], v[130:133], v[190:193], v[102:105]
	v_mfma_f32_16x16x32_bf16 v[38:41], v[178:181], v[194:197], v[38:41]
	v_mfma_f32_16x16x32_bf16 v[42:45], v[170:173], v[202:205], v[42:45]
	v_mfma_f32_16x16x32_bf16 v[46:49], v[178:181], v[202:205], v[46:49]
	v_mfma_f32_16x16x32_bf16 v[50:53], v[170:173], v[210:213], v[50:53]
	v_mfma_f32_16x16x32_bf16 v[54:57], v[178:181], v[210:213], v[54:57]
	v_mfma_f32_16x16x32_bf16 v[186:189], v[170:173], v[194:197], v[94:97]
	s_setprio 0
	s_barrier
; #define PG8_STAGE(bufoff, gbase, voff) do { _Pragma("unroll") for (int _i = 0; _i < 2; ++_i) \
;         __builtin_amdgcn_global_load_lds((const unsigned*)((const char*)(gbase) + (voff)[_i]), (PG8_LAS unsigned*)(lds + (bufoff) + ldsw + _i * 8192), 16, 0, 0); } while (0)
; #define PG8_LDA(dst, b, h) do { _Pragma("unroll") for (int m = 0; m < 4; ++m) _Pragma("unroll") for (int k = 0; k < 2; ++k) dst[m][k] = *(const PG8_LAS bf16x8*)(lds + PG8_SA(b, h) + aoff + m * 2048 + k * 1024); } while (0)
; #define PG8_LDB(dst, b, h) do { _Pragma("unroll") for (int n = 0; n < 2; ++n) _Pragma("unroll") for (int k = 0; k < 2; ++k) dst[n][k] = *(const PG8_LAS bf16x8*)(lds + PG8_SB(b, h) + boff + n * 2048 + k * 1024); } while (0)
; #define PG8_MMA(ai, bj, At, Bt) do { __builtin_amdgcn_s_setprio(1); _Pragma("unroll") for (int m = 0; m < 4; ++m) _Pragma("unroll") for (int n = 0; n < 2; ++n) _Pragma("unroll") for (int k = 0; k < 2; ++k) \
;         acc[ai][bj][m][n] = __builtin_amdgcn_mfma_f32_16x16x32_bf16(Bt[n][k], At[m][k], acc[ai][bj][m][n], 0, 0, 0); __builtin_amdgcn_s_setprio(0); } while (0)
; #define PG8_WAIT_V(n) asm volatile("s_waitcnt vmcnt(" #n ")" ::: "memory")
; #define PG8_WAIT_L(n) asm volatile("s_waitcnt lgkmcnt(" #n ")" ::: "memory")
; #define PG8_BAR __builtin_amdgcn_s_barrier()
; #define PG8_SCHED __builtin_amdgcn_sched_barrier(0)
; template <class Epi, class Sched, bool ALIGN_EPI = false, bool SP2 = false>
; __device__ __forceinline__ void gemm_phase(PG8_LAS unsigned char* lds, const Gemm g, const Sched& S, const Epi& E, const int wid) {
;     ...
;             PG8_LDA(At, 0, 1); PG8_STAGE(PG8_SB(0, 0), b2, voffB); PG8_STAGE(PG8_SB(0, 1), b2 + hsB, voffB); PG8_STAGE(PG8_SA(0, 0), a2, voffA);
;             PG8_WAIT_V(8); PG8_WAIT_L(0); PG8_BAR; PG8_MMA(1, 0, At, B0); PG8_MMA(1, 1, At, B1); PG8_BAR; PG8_SCHED;
;             PG8_LDB(B0, 1, 0); PG8_LDB(B1, 1, 1); PG8_SCHED; PG8_LDA(At, 1, 0); PG8_STAGE(PG8_SA(0, 1), a2 + hsA, voffA);
;             PG8_WAIT_V(8); PG8_WAIT_L(0); PG8_BAR; PG8_MMA(0, 0, At, B0); PG8_MMA(0, 1, At, B1); PG8_BAR; PG8_SCHED;
;             PG8_LDA(At, 1, 1); PG8_STAGE(PG8_SB(1, 0), b3, voffB); PG8_STAGE(PG8_SB(1, 1), b3 + hsB, voffB); PG8_STAGE(PG8_SA(1, 0), a3, voffA);
	s_mov_b32 m0, s75
	v_lshl_add_u64 v[250:251], s[38:39], 0, v[148:149]
	s_add_u32 s40, s38, 0x18000
	ds_read_b128 v[94:97], v163 offset:16384
	ds_read_b128 v[98:101], v163 offset:17408
	ds_read_b128 v[102:105], v163 offset:18432
	ds_read_b128 v[190:193], v163 offset:19456
	ds_read_b128 v[194:197], v163 offset:20480
	ds_read_b128 v[198:201], v163 offset:21504
	ds_read_b128 v[202:205], v163 offset:22528
	ds_read_b128 v[206:209], v163 offset:23552
	global_load_lds_dwordx4 v[250:251], off
	v_lshl_add_u64 v[252:253], s[38:39], 0, v[144:145]
	s_mov_b32 m0, s66
	s_addc_u32 s41, s39, 0
	global_load_lds_dwordx4 v[252:253], off
	v_lshl_add_u64 v[142:143], s[40:41], 0, v[148:149]
	s_mov_b32 m0, s67
	v_lshl_add_u64 v[154:155], s[4:5], 0, v[150:151]
	global_load_lds_dwordx4 v[142:143], off
	v_lshl_add_u64 v[142:143], s[40:41], 0, v[144:145]
	s_mov_b32 m0, s74
	v_lshl_add_u64 v[156:157], s[4:5], 0, v[146:147]
	global_load_lds_dwordx4 v[142:143], off
	s_mov_b32 m0, s46
	s_nop 0
	global_load_lds_dwordx4 v[154:155], off
	s_mov_b32 m0, s47
	s_nop 0
	global_load_lds_dwordx4 v[156:157], off
	s_waitcnt vmcnt(8)
	s_waitcnt lgkmcnt(0)
	s_barrier
	s_setprio 1
	s_waitcnt lgkmcnt(0)
	v_mfma_f32_16x16x32_bf16 v[134:137], v[114:117], v[102:105], v[134:137]
	v_mfma_f32_16x16x32_bf16 v[210:213], v[118:121], v[190:193], v[134:137]
	v_mfma_f32_16x16x32_bf16 v[134:137], v[122:125], v[102:105], v[138:141]
	v_mfma_f32_16x16x32_bf16 v[0:3], v[114:117], v[94:97], v[0:3]
	v_mfma_f32_16x16x32_bf16 v[4:7], v[122:125], v[94:97], v[4:7]
	v_mfma_f32_16x16x32_bf16 v[140:143], v[126:129], v[190:193], v[134:137]
	v_mfma_f32_16x16x32_bf16 v[134:137], v[114:117], v[194:197], v[158:161]
	v_mfma_f32_16x16x32_bf16 v[10:13], v[114:117], v[202:205], v[10:13]
	v_mfma_f32_16x16x32_bf16 v[14:17], v[122:125], v[202:205], v[14:17]
	v_mfma_f32_16x16x32_bf16 v[0:3], v[118:121], v[98:101], v[0:3]
	v_mfma_f32_16x16x32_bf16 v[4:7], v[126:129], v[98:101], v[4:7]
	v_mfma_f32_16x16x32_bf16 v[158:161], v[118:121], v[198:201], v[134:137]
	v_mfma_f32_16x16x32_bf16 v[134:137], v[122:125], v[194:197], v[166:169]
	v_mfma_f32_16x16x32_bf16 v[10:13], v[118:121], v[206:209], v[10:13]
	v_mfma_f32_16x16x32_bf16 v[14:17], v[126:129], v[206:209], v[14:17]
	v_mfma_f32_16x16x32_bf16 v[166:169], v[126:129], v[198:201], v[134:137]
	v_mfma_f32_16x16x32_bf16 v[30:33], v[174:177], v[94:97], v[30:33]
	v_mfma_f32_16x16x32_bf16 v[120:123], v[178:181], v[98:101], v[30:33]
	v_mfma_f32_16x16x32_bf16 v[30:33], v[130:133], v[102:105], v[34:37]
	v_mfma_f32_16x16x32_bf16 v[218:221], v[170:173], v[190:193], v[30:33]
	v_mfma_f32_16x16x32_bf16 v[30:33], v[174:177], v[102:105], v[58:61]
	v_mfma_f32_16x16x32_bf16 v[18:21], v[130:133], v[94:97], v[18:21]
	v_mfma_f32_16x16x32_bf16 v[190:193], v[178:181], v[190:193], v[30:33]
	v_mfma_f32_16x16x32_bf16 v[30:33], v[130:133], v[194:197], v[106:109]
	v_mfma_f32_16x16x32_bf16 v[22:25], v[130:133], v[202:205], v[22:25]
	v_mfma_f32_16x16x32_bf16 v[18:21], v[170:173], v[98:101], v[18:21]
	v_mfma_f32_16x16x32_bf16 v[222:225], v[170:173], v[198:201], v[30:33]
	v_mfma_f32_16x16x32_bf16 v[30:33], v[174:177], v[194:197], v[110:113]
	v_mfma_f32_16x16x32_bf16 v[170:173], v[170:173], v[206:209], v[22:25]
	v_mfma_f32_16x16x32_bf16 v[22:25], v[174:177], v[202:205], v[26:29]
	v_mfma_f32_16x16x32_bf16 v[194:197], v[178:181], v[198:201], v[30:33]
	v_mfma_f32_16x16x32_bf16 v[174:177], v[178:181], v[206:209], v[22:25]
	s_setprio 0
	s_barrier
	s_nop 3
	ds_read_b128 v[22:25], v8
	ds_read_b128 v[26:29], v8 offset:1024
	ds_read_b128 v[58:61], v8 offset:2048
	ds_read_b128 v[178:181], v8 offset:3072
	ds_read_b128 v[198:201], v9
	ds_read_b128 v[202:205], v9 offset:1024
	ds_read_b128 v[206:209], v9 offset:2048
	ds_read_b128 v[226:229], v9 offset:3072
	s_add_u32 s40, s4, 0x600000
	s_addc_u32 s41, s5, 0
	s_mov_b32 m0, s48
	v_lshl_add_u64 v[8:9], s[40:41], 0, v[150:151]
	ds_read_b128 v[30:33], v163 offset:32768
	ds_read_b128 v[34:37], v163 offset:33792
	ds_read_b128 v[108:111], v163 offset:34816
	ds_read_b128 v[230:233], v163 offset:35840
	ds_read_b128 v[234:237], v163 offset:36864
	ds_read_b128 v[238:241], v163 offset:37888
	ds_read_b128 v[242:245], v163 offset:38912
	ds_read_b128 v[246:249], v163 offset:39936
	global_load_lds_dwordx4 v[8:9], off
	v_lshl_add_u64 v[8:9], s[40:41], 0, v[146:147]
	s_mov_b32 m0, s49
	s_nop 0
	global_load_lds_dwordx4 v[8:9], off
	s_waitcnt vmcnt(8)
	s_waitcnt lgkmcnt(0)
	s_barrier
; #define PG8_STAGE(bufoff, gbase, voff) do { _Pragma("unroll") for (int _i = 0; _i < 2; ++_i) \
;         __builtin_amdgcn_global_load_lds((const unsigned*)((const char*)(gbase) + (voff)[_i]), (PG8_LAS unsigned*)(lds + (bufoff) + ldsw + _i * 8192), 16, 0, 0); } while (0)
; #define PG8_LDA(dst, b, h) do { _Pragma("unroll") for (int m = 0; m < 4; ++m) _Pragma("unroll") for (int k = 0; k < 2; ++k) dst[m][k] = *(const PG8_LAS bf16x8*)(lds + PG8_SA(b, h) + aoff + m * 2048 + k * 1024); } while (0)
; #define PG8_MMA(ai, bj, At, Bt) do { __builtin_amdgcn_s_setprio(1); _Pragma("unroll") for (int m = 0; m < 4; ++m) _Pragma("unroll") for (int n = 0; n < 2; ++n) _Pragma("unroll") for (int k = 0; k < 2; ++k) \
;         acc[ai][bj][m][n] = __builtin_amdgcn_mfma_f32_16x16x32_bf16(Bt[n][k], At[m][k], acc[ai][bj][m][n], 0, 0, 0); __builtin_amdgcn_s_setprio(0); } while (0)
; #define PG8_WAIT_V(n) asm volatile("s_waitcnt vmcnt(" #n ")" ::: "memory")
; #define PG8_WAIT_L(n) asm volatile("s_waitcnt lgkmcnt(" #n ")" ::: "memory")
; #define PG8_BAR __builtin_amdgcn_s_barrier()
; #define PG8_SCHED __builtin_amdgcn_sched_barrier(0)
; template <class Epi, class Sched, bool ALIGN_EPI = false, bool SP2 = false>
; __device__ __forceinline__ void gemm_phase(PG8_LAS unsigned char* lds, const Gemm g, const Sched& S, const Epi& E, const int wid) {
;     ...
;             PG8_WAIT_V(8); PG8_WAIT_L(0); PG8_BAR; PG8_MMA(0, 0, At, B0); PG8_MMA(0, 1, At, B1); PG8_BAR; PG8_SCHED;
;             PG8_LDA(At, 1, 1); PG8_STAGE(PG8_SB(1, 0), b3, voffB); PG8_STAGE(PG8_SB(1, 1), b3 + hsB, voffB); PG8_STAGE(PG8_SA(1, 0), a3, voffA);
;             PG8_WAIT_V(8); PG8_WAIT_L(0); PG8_BAR; PG8_MMA(1, 0, At, B0); PG8_MMA(1, 1, At, B1); PG8_BAR; PG8_SCHED;
	s_setprio 1
	s_waitcnt lgkmcnt(0)
	v_mfma_f32_16x16x32_bf16 v[62:65], v[22:25], v[30:33], v[62:65]
	v_mfma_f32_16x16x32_bf16 v[132:135], v[26:29], v[34:37], v[62:65]
	v_mfma_f32_16x16x32_bf16 v[62:65], v[58:61], v[30:33], v[66:69]
	v_mfma_f32_16x16x32_bf16 v[136:139], v[178:181], v[34:37], v[62:65]
	v_mfma_f32_16x16x32_bf16 v[62:65], v[22:25], v[108:111], v[70:73]
	v_mfma_f32_16x16x32_bf16 v[112:115], v[26:29], v[230:233], v[62:65]
	v_mfma_f32_16x16x32_bf16 v[62:65], v[58:61], v[108:111], v[74:77]
	v_mfma_f32_16x16x32_bf16 v[116:119], v[178:181], v[230:233], v[62:65]
	v_mfma_f32_16x16x32_bf16 v[62:65], v[22:25], v[234:237], v[78:81]
	v_mfma_f32_16x16x32_bf16 v[96:99], v[26:29], v[238:241], v[62:65]
	v_mfma_f32_16x16x32_bf16 v[62:65], v[58:61], v[234:237], v[82:85]
	v_mfma_f32_16x16x32_bf16 v[100:103], v[178:181], v[238:241], v[62:65]
	v_mfma_f32_16x16x32_bf16 v[62:65], v[22:25], v[242:245], v[86:89]
	v_mfma_f32_16x16x32_bf16 v[80:83], v[26:29], v[246:249], v[62:65]
	v_mfma_f32_16x16x32_bf16 v[62:65], v[58:61], v[242:245], v[90:93]
	v_mfma_f32_16x16x32_bf16 v[84:87], v[178:181], v[246:249], v[62:65]
	v_mfma_f32_16x16x32_bf16 v[62:65], v[198:201], v[30:33], v[214:217]
	v_mfma_f32_16x16x32_bf16 v[30:33], v[206:209], v[30:33], v[182:185]
	v_mfma_f32_16x16x32_bf16 v[128:131], v[226:229], v[34:37], v[30:33]
	v_mfma_f32_16x16x32_bf16 v[30:33], v[198:201], v[108:111], v[186:189]
	v_mfma_f32_16x16x32_bf16 v[104:107], v[202:205], v[230:233], v[30:33]
	v_mfma_f32_16x16x32_bf16 v[30:33], v[206:209], v[108:111], v[38:41]
	v_mfma_f32_16x16x32_bf16 v[108:111], v[226:229], v[230:233], v[30:33]
	v_mfma_f32_16x16x32_bf16 v[30:33], v[198:201], v[234:237], v[42:45]
	v_mfma_f32_16x16x32_bf16 v[88:91], v[202:205], v[238:241], v[30:33]
	v_mfma_f32_16x16x32_bf16 v[30:33], v[206:209], v[234:237], v[46:49]
	v_mfma_f32_16x16x32_bf16 v[92:95], v[226:229], v[238:241], v[30:33]
	v_mfma_f32_16x16x32_bf16 v[30:33], v[198:201], v[242:245], v[50:53]
	v_mfma_f32_16x16x32_bf16 v[72:75], v[202:205], v[246:249], v[30:33]
	v_mfma_f32_16x16x32_bf16 v[30:33], v[206:209], v[242:245], v[54:57]
	v_mfma_f32_16x16x32_bf16 v[124:127], v[202:205], v[34:37], v[62:65]
	v_mfma_f32_16x16x32_bf16 v[76:79], v[226:229], v[246:249], v[30:33]
	s_setprio 0
	s_barrier
	s_mov_b32 m0, s81
	v_lshl_add_u64 v[8:9], v[250:251], 0, s[14:15]
	s_add_u32 s40, s38, 0x18080
	ds_read_b128 v[40:43], v163 offset:49152
	ds_read_b128 v[44:47], v163 offset:50176
	ds_read_b128 v[182:185], v163 offset:51200
	ds_read_b128 v[186:189], v163 offset:52224
	ds_read_b128 v[214:217], v163 offset:53248
	ds_read_b128 v[230:233], v163 offset:54272
	ds_read_b128 v[234:237], v163 offset:55296
	ds_read_b128 v[238:241], v163 offset:56320
	global_load_lds_dwordx4 v[8:9], off
	v_lshl_add_u64 v[8:9], v[252:253], 0, s[14:15]
	s_mov_b32 m0, s76
	s_addc_u32 s41, s39, 0
	global_load_lds_dwordx4 v[8:9], off
	v_lshl_add_u64 v[8:9], s[40:41], 0, v[148:149]
	s_mov_b32 m0, s77
	s_nop 0
	global_load_lds_dwordx4 v[8:9], off
	v_lshl_add_u64 v[8:9], s[40:41], 0, v[144:145]
	s_mov_b32 m0, s79
	s_nop 0
	global_load_lds_dwordx4 v[8:9], off
	v_lshl_add_u64 v[8:9], v[154:155], 0, s[14:15]
	s_mov_b32 m0, s53
	s_nop 0
	global_load_lds_dwordx4 v[8:9], off
	v_lshl_add_u64 v[8:9], v[156:157], 0, s[14:15]
	s_mov_b32 m0, s54
	s_nop 0
	global_load_lds_dwordx4 v[8:9], off
	s_waitcnt vmcnt(8)
	s_waitcnt lgkmcnt(0)
	s_barrier
	s_setprio 1
	s_waitcnt lgkmcnt(0)
	v_mfma_f32_16x16x32_bf16 v[0:3], v[22:25], v[40:43], v[0:3]
	v_mfma_f32_16x16x32_bf16 v[64:67], v[26:29], v[44:47], v[0:3]
	v_mfma_f32_16x16x32_bf16 v[0:3], v[58:61], v[40:43], v[4:7]
	v_mfma_f32_16x16x32_bf16 v[68:71], v[178:181], v[44:47], v[0:3]
	v_mfma_f32_16x16x32_bf16 v[0:3], v[22:25], v[182:185], v[210:213]
	v_mfma_f32_16x16x32_bf16 v[48:51], v[26:29], v[186:189], v[0:3]
	v_mfma_f32_16x16x32_bf16 v[0:3], v[58:61], v[182:185], v[140:143]
	v_mfma_f32_16x16x32_bf16 v[52:55], v[178:181], v[186:189], v[0:3]
	v_mfma_f32_16x16x32_bf16 v[0:3], v[22:25], v[214:217], v[158:161]
	v_mfma_f32_16x16x32_bf16 v[32:35], v[26:29], v[230:233], v[0:3]
	v_mfma_f32_16x16x32_bf16 v[0:3], v[58:61], v[214:217], v[166:169]
	v_mfma_f32_16x16x32_bf16 v[36:39], v[178:181], v[230:233], v[0:3]
	v_mfma_f32_16x16x32_bf16 v[0:3], v[22:25], v[234:237], v[10:13]
	v_mfma_f32_16x16x32_bf16 v[8:11], v[26:29], v[238:241], v[0:3]
	v_mfma_f32_16x16x32_bf16 v[0:3], v[58:61], v[234:237], v[14:17]
	v_mfma_f32_16x16x32_bf16 v[12:15], v[178:181], v[238:241], v[0:3]
	v_mfma_f32_16x16x32_bf16 v[0:3], v[198:201], v[40:43], v[18:21]
	v_mfma_f32_16x16x32_bf16 v[56:59], v[202:205], v[44:47], v[0:3]
	v_mfma_f32_16x16x32_bf16 v[0:3], v[206:209], v[40:43], v[120:123]
	v_mfma_f32_16x16x32_bf16 v[60:63], v[226:229], v[44:47], v[0:3]
	v_mfma_f32_16x16x32_bf16 v[0:3], v[198:201], v[182:185], v[218:221]
	v_mfma_f32_16x16x32_bf16 v[40:43], v[202:205], v[186:189], v[0:3]
	v_mfma_f32_16x16x32_bf16 v[0:3], v[206:209], v[182:185], v[190:193]
	v_mfma_f32_16x16x32_bf16 v[44:47], v[226:229], v[186:189], v[0:3]
	v_mfma_f32_16x16x32_bf16 v[0:3], v[198:201], v[214:217], v[222:225]
	v_mfma_f32_16x16x32_bf16 v[24:27], v[202:205], v[230:233], v[0:3]
	v_mfma_f32_16x16x32_bf16 v[0:3], v[206:209], v[214:217], v[194:197]
	v_mfma_f32_16x16x32_bf16 v[28:31], v[226:229], v[230:233], v[0:3]
	v_mfma_f32_16x16x32_bf16 v[0:3], v[198:201], v[234:237], v[170:173]
	v_mfma_f32_16x16x32_bf16 v[4:7], v[206:209], v[234:237], v[174:177]
	v_mfma_f32_16x16x32_bf16 v[0:3], v[202:205], v[238:241], v[0:3]
	v_mfma_f32_16x16x32_bf16 v[4:7], v[226:229], v[238:241], v[4:7]
	s_setprio 0
	s_barrier
	s_andn2_b64 vcc, exec, s[16:17]
	s_cbranch_vccnz .LBB0_960
	s_barrier

; #define PG8_STAGE(bufoff, gbase, voff) do { _Pragma("unroll") for (int _i = 0; _i < 2; ++_i) \
;         __builtin_amdgcn_global_load_lds((const unsigned*)((const char*)(gbase) + (voff)[_i]), (PG8_LAS unsigned*)(lds + (bufoff) + ldsw + _i * 8192), 16, 0, 0); } while (0)
; #define PG8_LDA(dst, b, h) do { _Pragma("unroll") for (int m = 0; m < 4; ++m) _Pragma("unroll") for (int k = 0; k < 2; ++k) dst[m][k] = *(const PG8_LAS bf16x8*)(lds + PG8_SA(b, h) + aoff + m * 2048 + k * 1024); } while (0)
; #define PG8_LDB(dst, b, h) do { _Pragma("unroll") for (int n = 0; n < 2; ++n) _Pragma("unroll") for (int k = 0; k < 2; ++k) dst[n][k] = *(const PG8_LAS bf16x8*)(lds + PG8_SB(b, h) + boff + n * 2048 + k * 1024); } while (0)
; #define PG8_MMA(ai, bj, At, Bt) do { __builtin_amdgcn_s_setprio(1); _Pragma("unroll") for (int m = 0; m < 4; ++m) _Pragma("unroll") for (int n = 0; n < 2; ++n) _Pragma("unroll") for (int k = 0; k < 2; ++k) \
;         acc[ai][bj][m][n] = __builtin_amdgcn_mfma_f32_16x16x32_bf16(Bt[n][k], At[m][k], acc[ai][bj][m][n], 0, 0, 0); __builtin_amdgcn_s_setprio(0); } while (0)
; #define PG8_WAIT_V(n) asm volatile("s_waitcnt vmcnt(" #n ")" ::: "memory")
; #define PG8_WAIT_L(n) asm volatile("s_waitcnt lgkmcnt(" #n ")" ::: "memory")
; #define PG8_BAR __builtin_amdgcn_s_barrier()
; #define PG8_SCHED __builtin_amdgcn_sched_barrier(0)
; template <class Epi, class Sched, bool ALIGN_EPI = false, bool SP2 = false>
; __device__ __forceinline__ void gemm_phase(PG8_LAS unsigned char* lds, const Gemm g, const Sched& S, const Epi& E, const int wid) {
;     ...
;             PG8_LDB(B0, 0, 0); PG8_LDB(B1, 0, 1); PG8_SCHED; PG8_LDA(At, 0, 0); PG8_STAGE(PG8_SA(1, 1), a1 + hsA, voffA);
;             PG8_WAIT_V(8); PG8_WAIT_L(0); PG8_BAR; PG8_MMA(0, 0, At, B0); PG8_MMA(0, 1, At, B1); PG8_BAR; PG8_SCHED;
;             PG8_LDA(At, 0, 1); PG8_STAGE(PG8_SB(0, 0), b2, voffB); PG8_STAGE(PG8_SB(0, 1), b2 + hsB, voffB); PG8_STAGE(PG8_SA(0, 0), a2, voffA);
.LBB0_1177:
	ds_read_b128 v[128:131], v205
	ds_read_b128 v[132:135], v205 offset:1024
	ds_read_b128 v[136:139], v205 offset:2048
	ds_read_b128 v[140:143], v205 offset:3072
	ds_read_b128 v[144:147], v206
	ds_read_b128 v[148:151], v206 offset:1024
	ds_read_b128 v[152:155], v206 offset:2048
	ds_read_b128 v[156:159], v206 offset:3072
	s_add_u32 s40, s38, 0xfffc0080
	s_addc_u32 s41, s39, -1
	s_cmp_eq_u32 s64, 12
	s_cselect_b32 s43, s29, s41
	s_cselect_b32 s42, s60, s40
	s_cselect_b32 s41, s27, s63
	s_cselect_b32 s40, s61, s62
	v_lshl_add_u64 v[200:201], s[38:39], 0, v[170:171]
	s_add_i32 m0, s37, 0xc000
	ds_read_b128 v[176:179], v207
	ds_read_b128 v[180:183], v207 offset:1024
	ds_read_b128 v[184:187], v207 offset:2048
	ds_read_b128 v[188:191], v207 offset:3072
	ds_read_b128 v[192:195], v207 offset:4096
	ds_read_b128 v[196:199], v207 offset:5120
	ds_read_b128 v[208:211], v207 offset:6144
	ds_read_b128 v[212:215], v207 offset:7168
	global_load_lds_dwordx4 v[200:201], off
	v_lshl_add_u64 v[200:201], s[38:39], 0, v[168:169]
	s_add_i32 m0, s37, 0xe000
	s_nop 0
	global_load_lds_dwordx4 v[200:201], off
	s_waitcnt vmcnt(8)
	s_waitcnt lgkmcnt(0)
	s_barrier
	s_setprio 1
	s_waitcnt lgkmcnt(0)
	v_mfma_f32_16x16x32_bf16 v[124:127], v[128:131], v[176:179], v[124:127]
	v_mfma_f32_16x16x32_bf16 v[120:123], v[136:139], v[176:179], v[120:123]
	v_mfma_f32_16x16x32_bf16 v[116:119], v[128:131], v[184:187], v[116:119]
	v_mfma_f32_16x16x32_bf16 v[112:115], v[136:139], v[184:187], v[112:115]
	v_mfma_f32_16x16x32_bf16 v[108:111], v[128:131], v[192:195], v[108:111]
	v_mfma_f32_16x16x32_bf16 v[104:107], v[136:139], v[192:195], v[104:107]
	v_mfma_f32_16x16x32_bf16 v[100:103], v[128:131], v[208:211], v[100:103]
	v_mfma_f32_16x16x32_bf16 v[96:99], v[136:139], v[208:211], v[96:99]
	v_mfma_f32_16x16x32_bf16 v[124:127], v[132:135], v[180:183], v[124:127]
	v_mfma_f32_16x16x32_bf16 v[120:123], v[140:143], v[180:183], v[120:123]
	v_mfma_f32_16x16x32_bf16 v[116:119], v[132:135], v[188:191], v[116:119]
	v_mfma_f32_16x16x32_bf16 v[112:115], v[140:143], v[188:191], v[112:115]
	v_mfma_f32_16x16x32_bf16 v[108:111], v[132:135], v[196:199], v[108:111]
	v_mfma_f32_16x16x32_bf16 v[104:107], v[140:143], v[196:199], v[104:107]
	v_mfma_f32_16x16x32_bf16 v[100:103], v[132:135], v[212:215], v[100:103]
	v_mfma_f32_16x16x32_bf16 v[96:99], v[140:143], v[212:215], v[96:99]
	v_mfma_f32_16x16x32_bf16 v[60:63], v[144:147], v[176:179], v[60:63]
	v_mfma_f32_16x16x32_bf16 v[56:59], v[152:155], v[176:179], v[56:59]
	v_mfma_f32_16x16x32_bf16 v[52:55], v[144:147], v[184:187], v[52:55]
	v_mfma_f32_16x16x32_bf16 v[48:51], v[152:155], v[184:187], v[48:51]
	v_mfma_f32_16x16x32_bf16 v[44:47], v[144:147], v[192:195], v[44:47]
	v_mfma_f32_16x16x32_bf16 v[40:43], v[152:155], v[192:195], v[40:43]
	v_mfma_f32_16x16x32_bf16 v[36:39], v[144:147], v[208:211], v[36:39]
	v_mfma_f32_16x16x32_bf16 v[32:35], v[152:155], v[208:211], v[32:35]
	v_mfma_f32_16x16x32_bf16 v[60:63], v[148:151], v[180:183], v[60:63]
	v_mfma_f32_16x16x32_bf16 v[56:59], v[156:159], v[180:183], v[56:59]
	v_mfma_f32_16x16x32_bf16 v[52:55], v[148:151], v[188:191], v[52:55]
	v_mfma_f32_16x16x32_bf16 v[48:51], v[156:159], v[188:191], v[48:51]
	v_mfma_f32_16x16x32_bf16 v[44:47], v[148:151], v[196:199], v[44:47]
	v_mfma_f32_16x16x32_bf16 v[40:43], v[156:159], v[196:199], v[40:43]
	v_mfma_f32_16x16x32_bf16 v[36:39], v[148:151], v[212:215], v[36:39]
	v_mfma_f32_16x16x32_bf16 v[32:35], v[156:159], v[212:215], v[32:35]
	s_setprio 0
	s_barrier
	s_add_i32 s65, s54, s45
	v_lshl_add_u64 v[200:201], s[40:41], 0, v[162:163]
	s_mov_b32 m0, s65
	ds_read_b128 v[176:179], v207 offset:16384
	ds_read_b128 v[180:183], v207 offset:17408
	ds_read_b128 v[184:187], v207 offset:18432
	ds_read_b128 v[188:191], v207 offset:19456
	ds_read_b128 v[192:195], v207 offset:20480
	ds_read_b128 v[196:199], v207 offset:21504
	ds_read_b128 v[208:211], v207 offset:22528
	ds_read_b128 v[212:215], v207 offset:23552
	global_load_lds_dwordx4 v[200:201], off
	s_add_i32 m0, s65, 0x2000
	s_add_u32 s66, s40, 0x40000
	v_lshl_add_u64 v[216:217], s[40:41], 0, v[166:167]
	s_addc_u32 s67, s41, 0
	s_add_i32 s65, s55, s45
	global_load_lds_dwordx4 v[216:217], off
	v_lshl_add_u64 v[218:219], s[66:67], 0, v[162:163]
	s_mov_b32 m0, s65
	v_lshl_add_u64 v[220:221], s[42:43], 0, v[164:165]
	global_load_lds_dwordx4 v[218:219], off
	v_lshl_add_u64 v[218:219], s[66:67], 0, v[166:167]
	s_add_i32 m0, s65, 0x2000
	s_nop 0
	global_load_lds_dwordx4 v[218:219], off
	v_lshl_add_u64 v[218:219], s[42:43], 0, v[160:161]
	s_mov_b32 m0, s37
	s_nop 0
	global_load_lds_dwordx4 v[218:219], off
	s_mov_b32 m0, s46
	s_nop 0
	global_load_lds_dwordx4 v[220:221], off
	s_waitcnt vmcnt(8)
	s_waitcnt lgkmcnt(0)
	s_barrier
; #define PG8_STAGE(bufoff, gbase, voff) do { _Pragma("unroll") for (int _i = 0; _i < 2; ++_i) \
;         __builtin_amdgcn_global_load_lds((const unsigned*)((const char*)(gbase) + (voff)[_i]), (PG8_LAS unsigned*)(lds + (bufoff) + ldsw + _i * 8192), 16, 0, 0); } while (0)
; #define PG8_LDA(dst, b, h) do { _Pragma("unroll") for (int m = 0; m < 4; ++m) _Pragma("unroll") for (int k = 0; k < 2; ++k) dst[m][k] = *(const PG8_LAS bf16x8*)(lds + PG8_SA(b, h) + aoff + m * 2048 + k * 1024); } while (0)
; #define PG8_LDB(dst, b, h) do { _Pragma("unroll") for (int n = 0; n < 2; ++n) _Pragma("unroll") for (int k = 0; k < 2; ++k) dst[n][k] = *(const PG8_LAS bf16x8*)(lds + PG8_SB(b, h) + boff + n * 2048 + k * 1024); } while (0)
; #define PG8_MMA(ai, bj, At, Bt) do { __builtin_amdgcn_s_setprio(1); _Pragma("unroll") for (int m = 0; m < 4; ++m) _Pragma("unroll") for (int n = 0; n < 2; ++n) _Pragma("unroll") for (int k = 0; k < 2; ++k) \
;         acc[ai][bj][m][n] = __builtin_amdgcn_mfma_f32_16x16x32_bf16(Bt[n][k], At[m][k], acc[ai][bj][m][n], 0, 0, 0); __builtin_amdgcn_s_setprio(0); } while (0)
; #define PG8_WAIT_V(n) asm volatile("s_waitcnt vmcnt(" #n ")" ::: "memory")
; #define PG8_WAIT_L(n) asm volatile("s_waitcnt lgkmcnt(" #n ")" ::: "memory")
; #define PG8_BAR __builtin_amdgcn_s_barrier()
; #define PG8_SCHED __builtin_amdgcn_sched_barrier(0)
; template <class Epi, class Sched, bool ALIGN_EPI = false, bool SP2 = false>
; __device__ __forceinline__ void gemm_phase(PG8_LAS unsigned char* lds, const Gemm g, const Sched& S, const Epi& E, const int wid) {
;     ...
;             PG8_WAIT_V(8); PG8_WAIT_L(0); PG8_BAR; PG8_MMA(1, 0, At, B0); PG8_MMA(1, 1, At, B1); PG8_BAR; PG8_SCHED;
;             PG8_LDB(B0, 1, 0); PG8_LDB(B1, 1, 1); PG8_SCHED; PG8_LDA(At, 1, 0); PG8_STAGE(PG8_SA(0, 1), a2 + hsA, voffA);
;             PG8_WAIT_V(8); PG8_WAIT_L(0); PG8_BAR; PG8_MMA(0, 0, At, B0); PG8_MMA(0, 1, At, B1); PG8_BAR; PG8_SCHED;
	s_setprio 1
	s_waitcnt lgkmcnt(0)
	v_mfma_f32_16x16x32_bf16 v[92:95], v[128:131], v[176:179], v[92:95]
	v_mfma_f32_16x16x32_bf16 v[88:91], v[136:139], v[176:179], v[88:91]
	v_mfma_f32_16x16x32_bf16 v[84:87], v[128:131], v[184:187], v[84:87]
	v_mfma_f32_16x16x32_bf16 v[80:83], v[136:139], v[184:187], v[80:83]
	v_mfma_f32_16x16x32_bf16 v[76:79], v[128:131], v[192:195], v[76:79]
	v_mfma_f32_16x16x32_bf16 v[72:75], v[136:139], v[192:195], v[72:75]
	v_mfma_f32_16x16x32_bf16 v[68:71], v[128:131], v[208:211], v[68:71]
	v_mfma_f32_16x16x32_bf16 v[64:67], v[136:139], v[208:211], v[64:67]
	v_mfma_f32_16x16x32_bf16 v[92:95], v[132:135], v[180:183], v[92:95]
	v_mfma_f32_16x16x32_bf16 v[88:91], v[140:143], v[180:183], v[88:91]
	v_mfma_f32_16x16x32_bf16 v[84:87], v[132:135], v[188:191], v[84:87]
	v_mfma_f32_16x16x32_bf16 v[80:83], v[140:143], v[188:191], v[80:83]
	v_mfma_f32_16x16x32_bf16 v[76:79], v[132:135], v[196:199], v[76:79]
	v_mfma_f32_16x16x32_bf16 v[72:75], v[140:143], v[196:199], v[72:75]
	v_mfma_f32_16x16x32_bf16 v[68:71], v[132:135], v[212:215], v[68:71]
	v_mfma_f32_16x16x32_bf16 v[64:67], v[140:143], v[212:215], v[64:67]
	v_mfma_f32_16x16x32_bf16 v[28:31], v[144:147], v[176:179], v[28:31]
	v_mfma_f32_16x16x32_bf16 v[24:27], v[152:155], v[176:179], v[24:27]
	v_mfma_f32_16x16x32_bf16 v[20:23], v[144:147], v[184:187], v[20:23]
	v_mfma_f32_16x16x32_bf16 v[16:19], v[152:155], v[184:187], v[16:19]
	v_mfma_f32_16x16x32_bf16 v[12:15], v[144:147], v[192:195], v[12:15]
	v_mfma_f32_16x16x32_bf16 v[8:11], v[152:155], v[192:195], v[8:11]
	v_mfma_f32_16x16x32_bf16 v[4:7], v[144:147], v[208:211], v[4:7]
	v_mfma_f32_16x16x32_bf16 v[0:3], v[152:155], v[208:211], v[0:3]
	v_mfma_f32_16x16x32_bf16 v[28:31], v[148:151], v[180:183], v[28:31]
	v_mfma_f32_16x16x32_bf16 v[24:27], v[156:159], v[180:183], v[24:27]
	v_mfma_f32_16x16x32_bf16 v[20:23], v[148:151], v[188:191], v[20:23]
	v_mfma_f32_16x16x32_bf16 v[16:19], v[156:159], v[188:191], v[16:19]
	v_mfma_f32_16x16x32_bf16 v[12:15], v[148:151], v[196:199], v[12:15]
	v_mfma_f32_16x16x32_bf16 v[8:11], v[156:159], v[196:199], v[8:11]
	v_mfma_f32_16x16x32_bf16 v[4:7], v[148:151], v[212:215], v[4:7]
	v_mfma_f32_16x16x32_bf16 v[0:3], v[156:159], v[212:215], v[0:3]
	s_setprio 0
	s_barrier
	s_add_i32 s65, 0, 0x18000
	s_add_i32 s66, 0, 0x1c000
	v_add_u32_e32 v140, s65, v203
	v_add_u32_e32 v156, s66, v203
	ds_read_b128 v[128:131], v140
	ds_read_b128 v[132:135], v140 offset:1024
	ds_read_b128 v[136:139], v140 offset:2048
	ds_read_b128 v[140:143], v140 offset:3072
	ds_read_b128 v[144:147], v156
	ds_read_b128 v[148:151], v156 offset:1024
	ds_read_b128 v[152:155], v156 offset:2048
	ds_read_b128 v[156:159], v156 offset:3072
	s_add_u32 s42, s42, 0x40000
	s_addc_u32 s43, s43, 0
	s_mov_b32 m0, s47
	v_lshl_add_u64 v[222:223], s[42:43], 0, v[160:161]
	ds_read_b128 v[176:179], v207 offset:32768
	ds_read_b128 v[180:183], v207 offset:33792
	ds_read_b128 v[184:187], v207 offset:34816
	ds_read_b128 v[188:191], v207 offset:35840
	ds_read_b128 v[192:195], v207 offset:36864
	ds_read_b128 v[196:199], v207 offset:37888
	ds_read_b128 v[208:211], v207 offset:38912
	ds_read_b128 v[212:215], v207 offset:39936
	global_load_lds_dwordx4 v[222:223], off
	v_lshl_add_u64 v[222:223], s[42:43], 0, v[164:165]
	s_mov_b32 m0, s48
	s_nop 0
	global_load_lds_dwordx4 v[222:223], off
	s_waitcnt vmcnt(8)
	s_waitcnt lgkmcnt(0)
	s_barrier
	s_setprio 1
	s_waitcnt lgkmcnt(0)
	v_mfma_f32_16x16x32_bf16 v[124:127], v[128:131], v[176:179], v[124:127]
	v_mfma_f32_16x16x32_bf16 v[120:123], v[136:139], v[176:179], v[120:123]
	v_mfma_f32_16x16x32_bf16 v[116:119], v[128:131], v[184:187], v[116:119]
	v_mfma_f32_16x16x32_bf16 v[112:115], v[136:139], v[184:187], v[112:115]
	v_mfma_f32_16x16x32_bf16 v[108:111], v[128:131], v[192:195], v[108:111]
	v_mfma_f32_16x16x32_bf16 v[104:107], v[136:139], v[192:195], v[104:107]
	v_mfma_f32_16x16x32_bf16 v[100:103], v[128:131], v[208:211], v[100:103]
	v_mfma_f32_16x16x32_bf16 v[96:99], v[136:139], v[208:211], v[96:99]
	v_mfma_f32_16x16x32_bf16 v[124:127], v[132:135], v[180:183], v[124:127]
	v_mfma_f32_16x16x32_bf16 v[120:123], v[140:143], v[180:183], v[120:123]
	v_mfma_f32_16x16x32_bf16 v[116:119], v[132:135], v[188:191], v[116:119]
	v_mfma_f32_16x16x32_bf16 v[112:115], v[140:143], v[188:191], v[112:115]
	v_mfma_f32_16x16x32_bf16 v[108:111], v[132:135], v[196:199], v[108:111]
	v_mfma_f32_16x16x32_bf16 v[104:107], v[140:143], v[196:199], v[104:107]
	v_mfma_f32_16x16x32_bf16 v[100:103], v[132:135], v[212:215], v[100:103]
	v_mfma_f32_16x16x32_bf16 v[96:99], v[140:143], v[212:215], v[96:99]
	v_mfma_f32_16x16x32_bf16 v[60:63], v[144:147], v[176:179], v[60:63]
	v_mfma_f32_16x16x32_bf16 v[56:59], v[152:155], v[176:179], v[56:59]
	v_mfma_f32_16x16x32_bf16 v[52:55], v[144:147], v[184:187], v[52:55]
	v_mfma_f32_16x16x32_bf16 v[48:51], v[152:155], v[184:187], v[48:51]
	v_mfma_f32_16x16x32_bf16 v[44:47], v[144:147], v[192:195], v[44:47]
	v_mfma_f32_16x16x32_bf16 v[40:43], v[152:155], v[192:195], v[40:43]
	v_mfma_f32_16x16x32_bf16 v[36:39], v[144:147], v[208:211], v[36:39]
	v_mfma_f32_16x16x32_bf16 v[32:35], v[152:155], v[208:211], v[32:35]
	v_mfma_f32_16x16x32_bf16 v[60:63], v[148:151], v[180:183], v[60:63]
	v_mfma_f32_16x16x32_bf16 v[56:59], v[156:159], v[180:183], v[56:59]
	v_mfma_f32_16x16x32_bf16 v[52:55], v[148:151], v[188:191], v[52:55]
	v_mfma_f32_16x16x32_bf16 v[48:51], v[156:159], v[188:191], v[48:51]
	v_mfma_f32_16x16x32_bf16 v[44:47], v[148:151], v[196:199], v[44:47]
	v_mfma_f32_16x16x32_bf16 v[40:43], v[156:159], v[196:199], v[40:43]
	v_mfma_f32_16x16x32_bf16 v[36:39], v[148:151], v[212:215], v[36:39]
	v_mfma_f32_16x16x32_bf16 v[32:35], v[156:159], v[212:215], v[32:35]
	s_setprio 0
	s_barrier
; #define PG8_STAGE(bufoff, gbase, voff) do { _Pragma("unroll") for (int _i = 0; _i < 2; ++_i) \
;         __builtin_amdgcn_global_load_lds((const unsigned*)((const char*)(gbase) + (voff)[_i]), (PG8_LAS unsigned*)(lds + (bufoff) + ldsw + _i * 8192), 16, 0, 0); } while (0)
; #define PG8_LDA(dst, b, h) do { _Pragma("unroll") for (int m = 0; m < 4; ++m) _Pragma("unroll") for (int k = 0; k < 2; ++k) dst[m][k] = *(const PG8_LAS bf16x8*)(lds + PG8_SA(b, h) + aoff + m * 2048 + k * 1024); } while (0)
; #define PG8_MMA(ai, bj, At, Bt) do { __builtin_amdgcn_s_setprio(1); _Pragma("unroll") for (int m = 0; m < 4; ++m) _Pragma("unroll") for (int n = 0; n < 2; ++n) _Pragma("unroll") for (int k = 0; k < 2; ++k) \
;         acc[ai][bj][m][n] = __builtin_amdgcn_mfma_f32_16x16x32_bf16(Bt[n][k], At[m][k], acc[ai][bj][m][n], 0, 0, 0); __builtin_amdgcn_s_setprio(0); } while (0)
; #define PG8_WAIT_V(n) asm volatile("s_waitcnt vmcnt(" #n ")" ::: "memory")
; #define PG8_WAIT_L(n) asm volatile("s_waitcnt lgkmcnt(" #n ")" ::: "memory")
; #define PG8_BAR __builtin_amdgcn_s_barrier()
; #define PG8_SCHED __builtin_amdgcn_sched_barrier(0)
; template <class Epi, class Sched, bool ALIGN_EPI = false, bool SP2 = false>
; __device__ __forceinline__ void gemm_phase(PG8_LAS unsigned char* lds, const Gemm g, const Sched& S, const Epi& E, const int wid) {
;     ...
;             PG8_LDA(At, 1, 1); PG8_STAGE(PG8_SB(1, 0), b3, voffB); PG8_STAGE(PG8_SB(1, 1), b3 + hsB, voffB); PG8_STAGE(PG8_SA(1, 0), a3, voffA);
;             PG8_WAIT_V(8); PG8_WAIT_L(0); PG8_BAR; PG8_MMA(1, 0, At, B0); PG8_MMA(1, 1, At, B1); PG8_BAR; PG8_SCHED;
;     ...
;         if constexpr (ALIGN_EPI) { if (wr == 0) PG8_BAR; }
	s_add_i32 s42, s65, s45
	v_lshl_add_u64 v[200:201], v[200:201], 0, s[16:17]
	s_mov_b32 m0, s42
	ds_read_b128 v[176:179], v207 offset:49152
	ds_read_b128 v[180:183], v207 offset:50176
	ds_read_b128 v[184:187], v207 offset:51200
	ds_read_b128 v[188:191], v207 offset:52224
	ds_read_b128 v[192:195], v207 offset:53248
	ds_read_b128 v[196:199], v207 offset:54272
	ds_read_b128 v[208:211], v207 offset:55296
	ds_read_b128 v[212:215], v207 offset:56320
	global_load_lds_dwordx4 v[200:201], off
	s_add_i32 m0, s42, 0x2000
	s_add_u32 s40, s40, 0x40080
	v_lshl_add_u64 v[200:201], v[216:217], 0, s[16:17]
	s_addc_u32 s41, s41, 0
	s_add_i32 s42, s66, s45
	global_load_lds_dwordx4 v[200:201], off
	v_lshl_add_u64 v[200:201], s[40:41], 0, v[162:163]
	s_mov_b32 m0, s42
	s_nop 0
	global_load_lds_dwordx4 v[200:201], off
	v_lshl_add_u64 v[200:201], s[40:41], 0, v[166:167]
	s_add_i32 m0, s42, 0x2000
	s_nop 0
	global_load_lds_dwordx4 v[200:201], off
	v_lshl_add_u64 v[200:201], v[218:219], 0, s[16:17]
	s_mov_b32 m0, s50
	s_nop 0
	global_load_lds_dwordx4 v[200:201], off
	v_lshl_add_u64 v[200:201], v[220:221], 0, s[16:17]
	s_mov_b32 m0, s51
	s_nop 0
	global_load_lds_dwordx4 v[200:201], off
	s_waitcnt vmcnt(8)
	s_waitcnt lgkmcnt(0)
	s_barrier
	s_setprio 1
	s_waitcnt lgkmcnt(0)
	v_mfma_f32_16x16x32_bf16 v[92:95], v[128:131], v[176:179], v[92:95]
	v_mfma_f32_16x16x32_bf16 v[88:91], v[136:139], v[176:179], v[88:91]
	v_mfma_f32_16x16x32_bf16 v[84:87], v[128:131], v[184:187], v[84:87]
	v_mfma_f32_16x16x32_bf16 v[80:83], v[136:139], v[184:187], v[80:83]
	v_mfma_f32_16x16x32_bf16 v[76:79], v[128:131], v[192:195], v[76:79]
	v_mfma_f32_16x16x32_bf16 v[72:75], v[136:139], v[192:195], v[72:75]
	v_mfma_f32_16x16x32_bf16 v[68:71], v[128:131], v[208:211], v[68:71]
	v_mfma_f32_16x16x32_bf16 v[64:67], v[136:139], v[208:211], v[64:67]
	v_mfma_f32_16x16x32_bf16 v[92:95], v[132:135], v[180:183], v[92:95]
	v_mfma_f32_16x16x32_bf16 v[88:91], v[140:143], v[180:183], v[88:91]
	v_mfma_f32_16x16x32_bf16 v[84:87], v[132:135], v[188:191], v[84:87]
	v_mfma_f32_16x16x32_bf16 v[80:83], v[140:143], v[188:191], v[80:83]
	v_mfma_f32_16x16x32_bf16 v[76:79], v[132:135], v[196:199], v[76:79]
	v_mfma_f32_16x16x32_bf16 v[72:75], v[140:143], v[196:199], v[72:75]
	v_mfma_f32_16x16x32_bf16 v[68:71], v[132:135], v[212:215], v[68:71]
	v_mfma_f32_16x16x32_bf16 v[64:67], v[140:143], v[212:215], v[64:67]
	v_mfma_f32_16x16x32_bf16 v[28:31], v[144:147], v[176:179], v[28:31]
	v_mfma_f32_16x16x32_bf16 v[24:27], v[152:155], v[176:179], v[24:27]
	v_mfma_f32_16x16x32_bf16 v[20:23], v[144:147], v[184:187], v[20:23]
	v_mfma_f32_16x16x32_bf16 v[16:19], v[152:155], v[184:187], v[16:19]
	v_mfma_f32_16x16x32_bf16 v[12:15], v[144:147], v[192:195], v[12:15]
	v_mfma_f32_16x16x32_bf16 v[8:11], v[152:155], v[192:195], v[8:11]
	v_mfma_f32_16x16x32_bf16 v[4:7], v[144:147], v[208:211], v[4:7]
	v_mfma_f32_16x16x32_bf16 v[0:3], v[152:155], v[208:211], v[0:3]
	v_mfma_f32_16x16x32_bf16 v[28:31], v[148:151], v[180:183], v[28:31]
	v_mfma_f32_16x16x32_bf16 v[24:27], v[156:159], v[180:183], v[24:27]
	v_mfma_f32_16x16x32_bf16 v[20:23], v[148:151], v[188:191], v[20:23]
	v_mfma_f32_16x16x32_bf16 v[16:19], v[156:159], v[188:191], v[16:19]
	v_mfma_f32_16x16x32_bf16 v[12:15], v[148:151], v[196:199], v[12:15]
	v_mfma_f32_16x16x32_bf16 v[8:11], v[156:159], v[196:199], v[8:11]
	v_mfma_f32_16x16x32_bf16 v[4:7], v[148:151], v[212:215], v[4:7]
	v_mfma_f32_16x16x32_bf16 v[0:3], v[156:159], v[212:215], v[0:3]
	s_setprio 0
	s_barrier
	s_add_i32 s64, s64, 2
	s_add_u32 s62, s62, 0x100
	s_addc_u32 s63, s63, 0
	s_add_u32 s38, s38, 0x100
	s_addc_u32 s39, s39, 0
	s_cmp_gt_u32 s64, 13
	s_cbranch_scc0 .LBB0_1177
	s_and_b64 vcc, exec, s[18:19]
	s_cbranch_vccz .LBB0_1180
	s_barrier

; #define PG8_STAGE(bufoff, gbase, voff) do { _Pragma("unroll") for (int _i = 0; _i < 2; ++_i) \
;         __builtin_amdgcn_global_load_lds((const unsigned*)((const char*)(gbase) + (voff)[_i]), (PG8_LAS unsigned*)(lds + (bufoff) + ldsw + _i * 8192), 16, 0, 0); } while (0)
; #define PG8_LDA(dst, b, h) do { _Pragma("unroll") for (int m = 0; m < 4; ++m) _Pragma("unroll") for (int k = 0; k < 2; ++k) dst[m][k] = *(const PG8_LAS bf16x8*)(lds + PG8_SA(b, h) + aoff + m * 2048 + k * 1024); } while (0)
; #define PG8_LDB(dst, b, h) do { _Pragma("unroll") for (int n = 0; n < 2; ++n) _Pragma("unroll") for (int k = 0; k < 2; ++k) dst[n][k] = *(const PG8_LAS bf16x8*)(lds + PG8_SB(b, h) + boff + n * 2048 + k * 1024); } while (0)
; #define PG8_MMA(ai, bj, At, Bt) do { __builtin_amdgcn_s_setprio(1); _Pragma("unroll") for (int m = 0; m < 4; ++m) _Pragma("unroll") for (int n = 0; n < 2; ++n) _Pragma("unroll") for (int k = 0; k < 2; ++k) \
;         acc[ai][bj][m][n] = __builtin_amdgcn_mfma_f32_16x16x32_bf16(Bt[n][k], At[m][k], acc[ai][bj][m][n], 0, 0, 0); __builtin_amdgcn_s_setprio(0); } while (0)
; #define PG8_WAIT_V(n) asm volatile("s_waitcnt vmcnt(" #n ")" ::: "memory")
; #define PG8_WAIT_L(n) asm volatile("s_waitcnt lgkmcnt(" #n ")" ::: "memory")
; #define PG8_BAR __builtin_amdgcn_s_barrier()
; #define PG8_SCHED __builtin_amdgcn_sched_barrier(0)
; template <class Epi, class Sched, bool ALIGN_EPI = false, bool SP2 = false>
; __device__ __forceinline__ void gemm_phase(PG8_LAS unsigned char* lds, const Gemm g, const Sched& S, const Epi& E, const int wid) {
;     ...
;             PG8_LDB(B0, 0, 0); PG8_LDB(B1, 0, 1); PG8_SCHED; PG8_LDA(At, 0, 0); PG8_STAGE(PG8_SA(1, 1), a1 + hsA, voffA);
;             PG8_WAIT_V(8); PG8_WAIT_L(0); PG8_BAR; PG8_MMA(0, 0, At, B0); PG8_MMA(0, 1, At, B1); PG8_BAR; PG8_SCHED;
;             PG8_LDA(At, 0, 1); PG8_STAGE(PG8_SB(0, 0), b2, voffB); PG8_STAGE(PG8_SB(0, 1), b2 + hsB, voffB); PG8_STAGE(PG8_SA(0, 0), a2, voffA);
.LBB0_1304:
	ds_read_b128 v[64:67], v199
	ds_read_b128 v[72:75], v199 offset:1024
	ds_read_b128 v[80:83], v199 offset:2048
	ds_read_b128 v[84:87], v199 offset:3072
	ds_read_b128 v[88:91], v200
	ds_read_b128 v[92:95], v200 offset:1024
	ds_read_b128 v[100:103], v200 offset:2048
	ds_read_b128 v[104:107], v200 offset:3072
	s_add_u32 s38, s36, 0xfff80080
	s_addc_u32 s39, s37, -1
	s_cmp_eq_u32 s61, 28
	s_cselect_b32 s41, s5, s39
	s_cselect_b32 s40, s27, s38
	s_cselect_b32 s39, s25, s60
	s_cselect_b32 s38, s58, s59
	v_lshl_add_u64 v[196:197], s[36:37], 0, v[182:183]
	s_add_i32 m0, s35, 0xc000
	ds_read_b128 v[160:163], v201
	ds_read_b128 v[164:167], v201 offset:1024
	ds_read_b128 v[168:171], v201 offset:2048
	ds_read_b128 v[172:175], v201 offset:3072
	ds_read_b128 v[188:191], v201 offset:4096
	ds_read_b128 v[192:195], v201 offset:5120
	ds_read_b128 v[204:207], v201 offset:6144
	ds_read_b128 v[208:211], v201 offset:7168
	global_load_lds_dwordx4 v[196:197], off
	v_lshl_add_u64 v[196:197], s[36:37], 0, v[180:181]
	s_add_i32 m0, s35, 0xe000
	s_nop 0
	global_load_lds_dwordx4 v[196:197], off
	s_waitcnt vmcnt(8)
	s_waitcnt lgkmcnt(0)
	s_barrier
	s_setprio 1
	s_waitcnt lgkmcnt(0)
	v_mfma_f32_16x16x32_bf16 v[156:159], v[64:67], v[160:163], v[156:159]
	v_mfma_f32_16x16x32_bf16 v[152:155], v[80:83], v[160:163], v[152:155]
	v_mfma_f32_16x16x32_bf16 v[140:143], v[64:67], v[168:171], v[140:143]
	v_mfma_f32_16x16x32_bf16 v[136:139], v[80:83], v[168:171], v[136:139]
	v_mfma_f32_16x16x32_bf16 v[124:127], v[64:67], v[188:191], v[124:127]
	v_mfma_f32_16x16x32_bf16 v[120:123], v[80:83], v[188:191], v[120:123]
	v_mfma_f32_16x16x32_bf16 v[108:111], v[64:67], v[204:207], v[108:111]
	v_mfma_f32_16x16x32_bf16 v[96:99], v[80:83], v[204:207], v[96:99]
	v_mfma_f32_16x16x32_bf16 v[156:159], v[72:75], v[164:167], v[156:159]
	v_mfma_f32_16x16x32_bf16 v[152:155], v[84:87], v[164:167], v[152:155]
	v_mfma_f32_16x16x32_bf16 v[140:143], v[72:75], v[172:175], v[140:143]
	v_mfma_f32_16x16x32_bf16 v[136:139], v[84:87], v[172:175], v[136:139]
	v_mfma_f32_16x16x32_bf16 v[124:127], v[72:75], v[192:195], v[124:127]
	v_mfma_f32_16x16x32_bf16 v[120:123], v[84:87], v[192:195], v[120:123]
	v_mfma_f32_16x16x32_bf16 v[108:111], v[72:75], v[208:211], v[108:111]
	v_mfma_f32_16x16x32_bf16 v[96:99], v[84:87], v[208:211], v[96:99]
	v_mfma_f32_16x16x32_bf16 v[148:151], v[88:91], v[160:163], v[148:151]
	v_mfma_f32_16x16x32_bf16 v[144:147], v[100:103], v[160:163], v[144:147]
	v_mfma_f32_16x16x32_bf16 v[132:135], v[88:91], v[168:171], v[132:135]
	v_mfma_f32_16x16x32_bf16 v[128:131], v[100:103], v[168:171], v[128:131]
	v_mfma_f32_16x16x32_bf16 v[116:119], v[88:91], v[188:191], v[116:119]
	v_mfma_f32_16x16x32_bf16 v[112:115], v[100:103], v[188:191], v[112:115]
	v_mfma_f32_16x16x32_bf16 v[76:79], v[88:91], v[204:207], v[76:79]
	v_mfma_f32_16x16x32_bf16 v[68:71], v[100:103], v[204:207], v[68:71]
	v_mfma_f32_16x16x32_bf16 v[148:151], v[92:95], v[164:167], v[148:151]
	v_mfma_f32_16x16x32_bf16 v[144:147], v[104:107], v[164:167], v[144:147]
	v_mfma_f32_16x16x32_bf16 v[132:135], v[92:95], v[172:175], v[132:135]
	v_mfma_f32_16x16x32_bf16 v[128:131], v[104:107], v[172:175], v[128:131]
	v_mfma_f32_16x16x32_bf16 v[116:119], v[92:95], v[192:195], v[116:119]
	v_mfma_f32_16x16x32_bf16 v[112:115], v[104:107], v[192:195], v[112:115]
	v_mfma_f32_16x16x32_bf16 v[76:79], v[92:95], v[208:211], v[76:79]
	v_mfma_f32_16x16x32_bf16 v[68:71], v[104:107], v[208:211], v[68:71]
	s_setprio 0
	s_barrier
	s_add_i32 s62, s56, s44
	v_lshl_add_u64 v[196:197], s[38:39], 0, v[176:177]
	s_mov_b32 m0, s62
	ds_read_b128 v[160:163], v201 offset:16384
	ds_read_b128 v[164:167], v201 offset:17408
	ds_read_b128 v[168:171], v201 offset:18432
	ds_read_b128 v[172:175], v201 offset:19456
	ds_read_b128 v[188:191], v201 offset:20480
	ds_read_b128 v[192:195], v201 offset:21504
	ds_read_b128 v[204:207], v201 offset:22528
	ds_read_b128 v[208:211], v201 offset:23552
	global_load_lds_dwordx4 v[196:197], off
	s_add_i32 m0, s62, 0x2000
	s_add_u32 s62, s38, 0x80000
	v_lshl_add_u64 v[212:213], s[38:39], 0, v[178:179]
	s_addc_u32 s63, s39, 0
	s_add_i32 s64, s57, s44
	global_load_lds_dwordx4 v[212:213], off
	v_lshl_add_u64 v[214:215], s[62:63], 0, v[176:177]
	s_mov_b32 m0, s64
	v_lshl_add_u64 v[216:217], s[40:41], 0, v[178:179]
	global_load_lds_dwordx4 v[214:215], off
	v_lshl_add_u64 v[214:215], s[62:63], 0, v[178:179]
	s_add_i32 m0, s64, 0x2000
	s_nop 0
	global_load_lds_dwordx4 v[214:215], off
	v_lshl_add_u64 v[214:215], s[40:41], 0, v[176:177]
	s_mov_b32 m0, s35
	s_nop 0
	global_load_lds_dwordx4 v[214:215], off
	s_mov_b32 m0, s45
	s_nop 0
	global_load_lds_dwordx4 v[216:217], off
	s_waitcnt vmcnt(8)
	s_waitcnt lgkmcnt(0)
	s_barrier
; #define PG8_STAGE(bufoff, gbase, voff) do { _Pragma("unroll") for (int _i = 0; _i < 2; ++_i) \
;         __builtin_amdgcn_global_load_lds((const unsigned*)((const char*)(gbase) + (voff)[_i]), (PG8_LAS unsigned*)(lds + (bufoff) + ldsw + _i * 8192), 16, 0, 0); } while (0)
; #define PG8_LDA(dst, b, h) do { _Pragma("unroll") for (int m = 0; m < 4; ++m) _Pragma("unroll") for (int k = 0; k < 2; ++k) dst[m][k] = *(const PG8_LAS bf16x8*)(lds + PG8_SA(b, h) + aoff + m * 2048 + k * 1024); } while (0)
; #define PG8_LDB(dst, b, h) do { _Pragma("unroll") for (int n = 0; n < 2; ++n) _Pragma("unroll") for (int k = 0; k < 2; ++k) dst[n][k] = *(const PG8_LAS bf16x8*)(lds + PG8_SB(b, h) + boff + n * 2048 + k * 1024); } while (0)
; #define PG8_MMA(ai, bj, At, Bt) do { __builtin_amdgcn_s_setprio(1); _Pragma("unroll") for (int m = 0; m < 4; ++m) _Pragma("unroll") for (int n = 0; n < 2; ++n) _Pragma("unroll") for (int k = 0; k < 2; ++k) \
;         acc[ai][bj][m][n] = __builtin_amdgcn_mfma_f32_16x16x32_bf16(Bt[n][k], At[m][k], acc[ai][bj][m][n], 0, 0, 0); __builtin_amdgcn_s_setprio(0); } while (0)
; #define PG8_WAIT_V(n) asm volatile("s_waitcnt vmcnt(" #n ")" ::: "memory")
; #define PG8_WAIT_L(n) asm volatile("s_waitcnt lgkmcnt(" #n ")" ::: "memory")
; #define PG8_BAR __builtin_amdgcn_s_barrier()
; #define PG8_SCHED __builtin_amdgcn_sched_barrier(0)
; template <class Epi, class Sched, bool ALIGN_EPI = false, bool SP2 = false>
; __device__ __forceinline__ void gemm_phase(PG8_LAS unsigned char* lds, const Gemm g, const Sched& S, const Epi& E, const int wid) {
;     ...
;             PG8_WAIT_V(8); PG8_WAIT_L(0); PG8_BAR; PG8_MMA(1, 0, At, B0); PG8_MMA(1, 1, At, B1); PG8_BAR; PG8_SCHED;
;             PG8_LDB(B0, 1, 0); PG8_LDB(B1, 1, 1); PG8_SCHED; PG8_LDA(At, 1, 0); PG8_STAGE(PG8_SA(0, 1), a2 + hsA, voffA);
;             PG8_WAIT_V(8); PG8_WAIT_L(0); PG8_BAR; PG8_MMA(0, 0, At, B0); PG8_MMA(0, 1, At, B1); PG8_BAR; PG8_SCHED;
	s_setprio 1
	s_waitcnt lgkmcnt(0)
	v_mfma_f32_16x16x32_bf16 v[60:63], v[64:67], v[160:163], v[60:63]
	v_mfma_f32_16x16x32_bf16 v[56:59], v[80:83], v[160:163], v[56:59]
	v_mfma_f32_16x16x32_bf16 v[44:47], v[64:67], v[168:171], v[44:47]
	v_mfma_f32_16x16x32_bf16 v[40:43], v[80:83], v[168:171], v[40:43]
	v_mfma_f32_16x16x32_bf16 v[28:31], v[64:67], v[188:191], v[28:31]
	v_mfma_f32_16x16x32_bf16 v[24:27], v[80:83], v[188:191], v[24:27]
	v_mfma_f32_16x16x32_bf16 v[12:15], v[64:67], v[204:207], v[12:15]
	v_mfma_f32_16x16x32_bf16 v[8:11], v[80:83], v[204:207], v[8:11]
	v_mfma_f32_16x16x32_bf16 v[60:63], v[72:75], v[164:167], v[60:63]
	v_mfma_f32_16x16x32_bf16 v[56:59], v[84:87], v[164:167], v[56:59]
	v_mfma_f32_16x16x32_bf16 v[44:47], v[72:75], v[172:175], v[44:47]
	v_mfma_f32_16x16x32_bf16 v[40:43], v[84:87], v[172:175], v[40:43]
	v_mfma_f32_16x16x32_bf16 v[28:31], v[72:75], v[192:195], v[28:31]
	v_mfma_f32_16x16x32_bf16 v[24:27], v[84:87], v[192:195], v[24:27]
	v_mfma_f32_16x16x32_bf16 v[12:15], v[72:75], v[208:211], v[12:15]
	v_mfma_f32_16x16x32_bf16 v[8:11], v[84:87], v[208:211], v[8:11]
	v_mfma_f32_16x16x32_bf16 v[52:55], v[88:91], v[160:163], v[52:55]
	v_mfma_f32_16x16x32_bf16 v[48:51], v[100:103], v[160:163], v[48:51]
	v_mfma_f32_16x16x32_bf16 v[36:39], v[88:91], v[168:171], v[36:39]
	v_mfma_f32_16x16x32_bf16 v[32:35], v[100:103], v[168:171], v[32:35]
	v_mfma_f32_16x16x32_bf16 v[20:23], v[88:91], v[188:191], v[20:23]
	v_mfma_f32_16x16x32_bf16 v[16:19], v[100:103], v[188:191], v[16:19]
	v_mfma_f32_16x16x32_bf16 v[4:7], v[88:91], v[204:207], v[4:7]
	v_mfma_f32_16x16x32_bf16 v[0:3], v[100:103], v[204:207], v[0:3]
	v_mfma_f32_16x16x32_bf16 v[52:55], v[92:95], v[164:167], v[52:55]
	v_mfma_f32_16x16x32_bf16 v[48:51], v[104:107], v[164:167], v[48:51]
	v_mfma_f32_16x16x32_bf16 v[36:39], v[92:95], v[172:175], v[36:39]
	v_mfma_f32_16x16x32_bf16 v[32:35], v[104:107], v[172:175], v[32:35]
	v_mfma_f32_16x16x32_bf16 v[20:23], v[92:95], v[192:195], v[20:23]
	v_mfma_f32_16x16x32_bf16 v[16:19], v[104:107], v[192:195], v[16:19]
	v_mfma_f32_16x16x32_bf16 v[4:7], v[92:95], v[208:211], v[4:7]
	v_mfma_f32_16x16x32_bf16 v[0:3], v[104:107], v[208:211], v[0:3]
	s_setprio 0
	s_barrier
	s_add_i32 s62, 0, 0x18000
	s_add_i32 s63, 0, 0x1c000
	v_add_u32_e32 v84, s62, v198
	v_add_u32_e32 v104, s63, v198
	ds_read_b128 v[64:67], v84
	ds_read_b128 v[72:75], v84 offset:1024
	ds_read_b128 v[80:83], v84 offset:2048
	ds_read_b128 v[84:87], v84 offset:3072
	ds_read_b128 v[88:91], v104
	ds_read_b128 v[92:95], v104 offset:1024
	ds_read_b128 v[100:103], v104 offset:2048
	ds_read_b128 v[104:107], v104 offset:3072
	s_add_u32 s40, s40, 0x80000
	s_addc_u32 s41, s41, 0
	s_mov_b32 m0, s46
	v_lshl_add_u64 v[218:219], s[40:41], 0, v[176:177]
	ds_read_b128 v[160:163], v201 offset:32768
	ds_read_b128 v[164:167], v201 offset:33792
	ds_read_b128 v[168:171], v201 offset:34816
	ds_read_b128 v[172:175], v201 offset:35840
	ds_read_b128 v[188:191], v201 offset:36864
	ds_read_b128 v[192:195], v201 offset:37888
	ds_read_b128 v[204:207], v201 offset:38912
	ds_read_b128 v[208:211], v201 offset:39936
	global_load_lds_dwordx4 v[218:219], off
	v_lshl_add_u64 v[218:219], s[40:41], 0, v[178:179]
	s_mov_b32 m0, s47
	s_nop 0
	global_load_lds_dwordx4 v[218:219], off
	s_waitcnt vmcnt(8)
	s_waitcnt lgkmcnt(0)
	s_barrier
	s_setprio 1
	s_waitcnt lgkmcnt(0)
	v_mfma_f32_16x16x32_bf16 v[156:159], v[64:67], v[160:163], v[156:159]
	v_mfma_f32_16x16x32_bf16 v[152:155], v[80:83], v[160:163], v[152:155]
	v_mfma_f32_16x16x32_bf16 v[140:143], v[64:67], v[168:171], v[140:143]
	v_mfma_f32_16x16x32_bf16 v[136:139], v[80:83], v[168:171], v[136:139]
	v_mfma_f32_16x16x32_bf16 v[124:127], v[64:67], v[188:191], v[124:127]
	v_mfma_f32_16x16x32_bf16 v[120:123], v[80:83], v[188:191], v[120:123]
	v_mfma_f32_16x16x32_bf16 v[108:111], v[64:67], v[204:207], v[108:111]
	v_mfma_f32_16x16x32_bf16 v[96:99], v[80:83], v[204:207], v[96:99]
	v_mfma_f32_16x16x32_bf16 v[156:159], v[72:75], v[164:167], v[156:159]
	v_mfma_f32_16x16x32_bf16 v[152:155], v[84:87], v[164:167], v[152:155]
	v_mfma_f32_16x16x32_bf16 v[140:143], v[72:75], v[172:175], v[140:143]
	v_mfma_f32_16x16x32_bf16 v[136:139], v[84:87], v[172:175], v[136:139]
	v_mfma_f32_16x16x32_bf16 v[124:127], v[72:75], v[192:195], v[124:127]
	v_mfma_f32_16x16x32_bf16 v[120:123], v[84:87], v[192:195], v[120:123]
	v_mfma_f32_16x16x32_bf16 v[108:111], v[72:75], v[208:211], v[108:111]
	v_mfma_f32_16x16x32_bf16 v[96:99], v[84:87], v[208:211], v[96:99]
	v_mfma_f32_16x16x32_bf16 v[148:151], v[88:91], v[160:163], v[148:151]
	v_mfma_f32_16x16x32_bf16 v[144:147], v[100:103], v[160:163], v[144:147]
	v_mfma_f32_16x16x32_bf16 v[132:135], v[88:91], v[168:171], v[132:135]
	v_mfma_f32_16x16x32_bf16 v[128:131], v[100:103], v[168:171], v[128:131]
	v_mfma_f32_16x16x32_bf16 v[116:119], v[88:91], v[188:191], v[116:119]
	v_mfma_f32_16x16x32_bf16 v[112:115], v[100:103], v[188:191], v[112:115]
	v_mfma_f32_16x16x32_bf16 v[76:79], v[88:91], v[204:207], v[76:79]
	v_mfma_f32_16x16x32_bf16 v[68:71], v[100:103], v[204:207], v[68:71]
	v_mfma_f32_16x16x32_bf16 v[148:151], v[92:95], v[164:167], v[148:151]
	v_mfma_f32_16x16x32_bf16 v[144:147], v[104:107], v[164:167], v[144:147]
	v_mfma_f32_16x16x32_bf16 v[132:135], v[92:95], v[172:175], v[132:135]
	v_mfma_f32_16x16x32_bf16 v[128:131], v[104:107], v[172:175], v[128:131]
	v_mfma_f32_16x16x32_bf16 v[116:119], v[92:95], v[192:195], v[116:119]
	v_mfma_f32_16x16x32_bf16 v[112:115], v[104:107], v[192:195], v[112:115]
	v_mfma_f32_16x16x32_bf16 v[76:79], v[92:95], v[208:211], v[76:79]
	v_mfma_f32_16x16x32_bf16 v[68:71], v[104:107], v[208:211], v[68:71]
	s_setprio 0
	s_barrier
; #define PG8_STAGE(bufoff, gbase, voff) do { _Pragma("unroll") for (int _i = 0; _i < 2; ++_i) \
;         __builtin_amdgcn_global_load_lds((const unsigned*)((const char*)(gbase) + (voff)[_i]), (PG8_LAS unsigned*)(lds + (bufoff) + ldsw + _i * 8192), 16, 0, 0); } while (0)
; #define PG8_LDA(dst, b, h) do { _Pragma("unroll") for (int m = 0; m < 4; ++m) _Pragma("unroll") for (int k = 0; k < 2; ++k) dst[m][k] = *(const PG8_LAS bf16x8*)(lds + PG8_SA(b, h) + aoff + m * 2048 + k * 1024); } while (0)
; #define PG8_MMA(ai, bj, At, Bt) do { __builtin_amdgcn_s_setprio(1); _Pragma("unroll") for (int m = 0; m < 4; ++m) _Pragma("unroll") for (int n = 0; n < 2; ++n) _Pragma("unroll") for (int k = 0; k < 2; ++k) \
;         acc[ai][bj][m][n] = __builtin_amdgcn_mfma_f32_16x16x32_bf16(Bt[n][k], At[m][k], acc[ai][bj][m][n], 0, 0, 0); __builtin_amdgcn_s_setprio(0); } while (0)
; #define PG8_WAIT_V(n) asm volatile("s_waitcnt vmcnt(" #n ")" ::: "memory")
; #define PG8_WAIT_L(n) asm volatile("s_waitcnt lgkmcnt(" #n ")" ::: "memory")
; #define PG8_BAR __builtin_amdgcn_s_barrier()
; #define PG8_SCHED __builtin_amdgcn_sched_barrier(0)
; template <class Epi, class Sched, bool ALIGN_EPI = false, bool SP2 = false>
; __device__ __forceinline__ void gemm_phase(PG8_LAS unsigned char* lds, const Gemm g, const Sched& S, const Epi& E, const int wid) {
;     ...
;             PG8_LDA(At, 1, 1); PG8_STAGE(PG8_SB(1, 0), b3, voffB); PG8_STAGE(PG8_SB(1, 1), b3 + hsB, voffB); PG8_STAGE(PG8_SA(1, 0), a3, voffA);
;             PG8_WAIT_V(8); PG8_WAIT_L(0); PG8_BAR; PG8_MMA(1, 0, At, B0); PG8_MMA(1, 1, At, B1); PG8_BAR; PG8_SCHED;
;     ...
;         if constexpr (ALIGN_EPI) { if (wr == 0) PG8_BAR; }
	s_add_i32 s40, s62, s44
	v_lshl_add_u64 v[196:197], v[196:197], 0, s[20:21]
	s_mov_b32 m0, s40
	ds_read_b128 v[160:163], v201 offset:49152
	ds_read_b128 v[164:167], v201 offset:50176
	ds_read_b128 v[168:171], v201 offset:51200
	ds_read_b128 v[172:175], v201 offset:52224
	ds_read_b128 v[188:191], v201 offset:53248
	ds_read_b128 v[192:195], v201 offset:54272
	ds_read_b128 v[204:207], v201 offset:55296
	ds_read_b128 v[208:211], v201 offset:56320
	global_load_lds_dwordx4 v[196:197], off
	s_add_i32 m0, s40, 0x2000
	s_add_u32 s38, s38, 0x80080
	v_lshl_add_u64 v[196:197], v[212:213], 0, s[20:21]
	s_addc_u32 s39, s39, 0
	s_add_i32 s40, s63, s44
	global_load_lds_dwordx4 v[196:197], off
	v_lshl_add_u64 v[196:197], s[38:39], 0, v[176:177]
	s_mov_b32 m0, s40
	s_nop 0
	global_load_lds_dwordx4 v[196:197], off
	v_lshl_add_u64 v[196:197], s[38:39], 0, v[178:179]
	s_add_i32 m0, s40, 0x2000
	s_nop 0
	global_load_lds_dwordx4 v[196:197], off
	v_lshl_add_u64 v[196:197], v[214:215], 0, s[20:21]
	s_mov_b32 m0, s51
	s_nop 0
	global_load_lds_dwordx4 v[196:197], off
	v_lshl_add_u64 v[196:197], v[216:217], 0, s[20:21]
	s_mov_b32 m0, s52
	s_nop 0
	global_load_lds_dwordx4 v[196:197], off
	s_waitcnt vmcnt(8)
	s_waitcnt lgkmcnt(0)
	s_barrier
	s_setprio 1
	s_waitcnt lgkmcnt(0)
	v_mfma_f32_16x16x32_bf16 v[60:63], v[64:67], v[160:163], v[60:63]
	v_mfma_f32_16x16x32_bf16 v[56:59], v[80:83], v[160:163], v[56:59]
	v_mfma_f32_16x16x32_bf16 v[44:47], v[64:67], v[168:171], v[44:47]
	v_mfma_f32_16x16x32_bf16 v[40:43], v[80:83], v[168:171], v[40:43]
	v_mfma_f32_16x16x32_bf16 v[28:31], v[64:67], v[188:191], v[28:31]
	v_mfma_f32_16x16x32_bf16 v[24:27], v[80:83], v[188:191], v[24:27]
	v_mfma_f32_16x16x32_bf16 v[12:15], v[64:67], v[204:207], v[12:15]
	v_mfma_f32_16x16x32_bf16 v[8:11], v[80:83], v[204:207], v[8:11]
	v_mfma_f32_16x16x32_bf16 v[60:63], v[72:75], v[164:167], v[60:63]
	v_mfma_f32_16x16x32_bf16 v[56:59], v[84:87], v[164:167], v[56:59]
	v_mfma_f32_16x16x32_bf16 v[44:47], v[72:75], v[172:175], v[44:47]
	v_mfma_f32_16x16x32_bf16 v[40:43], v[84:87], v[172:175], v[40:43]
	v_mfma_f32_16x16x32_bf16 v[28:31], v[72:75], v[192:195], v[28:31]
	v_mfma_f32_16x16x32_bf16 v[24:27], v[84:87], v[192:195], v[24:27]
	v_mfma_f32_16x16x32_bf16 v[12:15], v[72:75], v[208:211], v[12:15]
	v_mfma_f32_16x16x32_bf16 v[8:11], v[84:87], v[208:211], v[8:11]
	v_mfma_f32_16x16x32_bf16 v[52:55], v[88:91], v[160:163], v[52:55]
	v_mfma_f32_16x16x32_bf16 v[48:51], v[100:103], v[160:163], v[48:51]
	v_mfma_f32_16x16x32_bf16 v[36:39], v[88:91], v[168:171], v[36:39]
	v_mfma_f32_16x16x32_bf16 v[32:35], v[100:103], v[168:171], v[32:35]
	v_mfma_f32_16x16x32_bf16 v[20:23], v[88:91], v[188:191], v[20:23]
	v_mfma_f32_16x16x32_bf16 v[16:19], v[100:103], v[188:191], v[16:19]
	v_mfma_f32_16x16x32_bf16 v[4:7], v[88:91], v[204:207], v[4:7]
	v_mfma_f32_16x16x32_bf16 v[0:3], v[100:103], v[204:207], v[0:3]
	v_mfma_f32_16x16x32_bf16 v[52:55], v[92:95], v[164:167], v[52:55]
	v_mfma_f32_16x16x32_bf16 v[48:51], v[104:107], v[164:167], v[48:51]
	v_mfma_f32_16x16x32_bf16 v[36:39], v[92:95], v[172:175], v[36:39]
	v_mfma_f32_16x16x32_bf16 v[32:35], v[104:107], v[172:175], v[32:35]
	v_mfma_f32_16x16x32_bf16 v[20:23], v[92:95], v[192:195], v[20:23]
	v_mfma_f32_16x16x32_bf16 v[16:19], v[104:107], v[192:195], v[16:19]
	v_mfma_f32_16x16x32_bf16 v[4:7], v[92:95], v[208:211], v[4:7]
	v_mfma_f32_16x16x32_bf16 v[0:3], v[104:107], v[208:211], v[0:3]
	s_setprio 0
	s_barrier
	s_add_i32 s61, s61, 2
	s_add_u32 s59, s59, 0x100
	s_addc_u32 s60, s60, 0
	s_add_u32 s36, s36, 0x100
	s_addc_u32 s37, s37, 0
	s_cmp_gt_u32 s61, 29
	s_cbranch_scc0 .LBB0_1304
	s_and_b64 vcc, exec, s[22:23]
	s_cbranch_vccz .LBB0_1307
	s_barrier

; #define PG8_STAGE(bufoff, gbase, voff) do { _Pragma("unroll") for (int _i = 0; _i < 2; ++_i) \
;         __builtin_amdgcn_global_load_lds((const unsigned*)((const char*)(gbase) + (voff)[_i]), (PG8_LAS unsigned*)(lds + (bufoff) + ldsw + _i * 8192), 16, 0, 0); } while (0)
; #define PG8_LDA(dst, b, h) do { _Pragma("unroll") for (int m = 0; m < 4; ++m) _Pragma("unroll") for (int k = 0; k < 2; ++k) dst[m][k] = *(const PG8_LAS bf16x8*)(lds + PG8_SA(b, h) + aoff + m * 2048 + k * 1024); } while (0)
; #define PG8_LDB(dst, b, h) do { _Pragma("unroll") for (int n = 0; n < 2; ++n) _Pragma("unroll") for (int k = 0; k < 2; ++k) dst[n][k] = *(const PG8_LAS bf16x8*)(lds + PG8_SB(b, h) + boff + n * 2048 + k * 1024); } while (0)
; #define PG8_MMA(ai, bj, At, Bt) do { __builtin_amdgcn_s_setprio(1); _Pragma("unroll") for (int m = 0; m < 4; ++m) _Pragma("unroll") for (int n = 0; n < 2; ++n) _Pragma("unroll") for (int k = 0; k < 2; ++k) \
;         acc[ai][bj][m][n] = __builtin_amdgcn_mfma_f32_16x16x32_bf16(Bt[n][k], At[m][k], acc[ai][bj][m][n], 0, 0, 0); __builtin_amdgcn_s_setprio(0); } while (0)
; #define PG8_WAIT_V(n) asm volatile("s_waitcnt vmcnt(" #n ")" ::: "memory")
; #define PG8_WAIT_L(n) asm volatile("s_waitcnt lgkmcnt(" #n ")" ::: "memory")
; #define PG8_BAR __builtin_amdgcn_s_barrier()
; #define PG8_SCHED __builtin_amdgcn_sched_barrier(0)
; template <class Epi, class Sched, bool ALIGN_EPI = false, bool SP2 = false>
; __device__ __forceinline__ void gemm_phase(PG8_LAS unsigned char* lds, const Gemm g, const Sched& S, const Epi& E, const int wid) {
;     ...
;             PG8_LDB(B0, 0, 0); PG8_LDB(B1, 0, 1); PG8_SCHED; PG8_LDA(At, 0, 0); PG8_STAGE(PG8_SA(1, 1), a1 + hsA, voffA);
;             PG8_WAIT_V(8); PG8_WAIT_L(0); PG8_BAR; PG8_MMA(0, 0, At, B0); PG8_MMA(0, 1, At, B1); PG8_BAR; PG8_SCHED;
;             PG8_LDA(At, 0, 1); PG8_STAGE(PG8_SB(0, 0), b2, voffB); PG8_STAGE(PG8_SB(0, 1), b2 + hsB, voffB); PG8_STAGE(PG8_SA(0, 0), a2, voffA);
.LBB0_1385:
	ds_read_b128 v[128:131], v171
	ds_read_b128 v[132:135], v171 offset:1024
	ds_read_b128 v[136:139], v171 offset:2048
	ds_read_b128 v[140:143], v171 offset:3072
	ds_read_b128 v[160:163], v173
	ds_read_b128 v[164:167], v173 offset:1024
	ds_read_b128 v[180:183], v173 offset:2048
	ds_read_b128 v[184:187], v173 offset:3072
	s_add_u32 s8, s6, 0xfff80080
	s_addc_u32 s9, s7, -1
	s_cmp_eq_u32 s60, 28
	s_cselect_b32 s31, s5, s9
	s_cselect_b32 s30, s25, s8
	s_cselect_b32 s9, s23, s59
	s_cselect_b32 s8, s57, s58
	v_lshl_add_u64 v[220:221], s[6:7], 0, v[154:155]
	s_add_i32 m0, s39, 0xc000
	ds_read_b128 v[188:191], v175
	ds_read_b128 v[192:195], v175 offset:1024
	ds_read_b128 v[196:199], v175 offset:2048
	ds_read_b128 v[200:203], v175 offset:3072
	ds_read_b128 v[204:207], v175 offset:4096
	ds_read_b128 v[208:211], v175 offset:5120
	ds_read_b128 v[212:215], v175 offset:6144
	ds_read_b128 v[216:219], v175 offset:7168
	global_load_lds_dwordx4 v[220:221], off
	v_lshl_add_u64 v[220:221], s[6:7], 0, v[152:153]
	s_add_i32 m0, s39, 0xe000
	s_nop 0
	global_load_lds_dwordx4 v[220:221], off
	s_waitcnt vmcnt(8)
	s_waitcnt lgkmcnt(0)
	s_barrier
	s_setprio 1
	s_waitcnt lgkmcnt(0)
	v_mfma_f32_16x16x32_bf16 v[124:127], v[128:131], v[188:191], v[124:127]
	v_mfma_f32_16x16x32_bf16 v[120:123], v[136:139], v[188:191], v[120:123]
	v_mfma_f32_16x16x32_bf16 v[108:111], v[128:131], v[196:199], v[108:111]
	v_mfma_f32_16x16x32_bf16 v[104:107], v[136:139], v[196:199], v[104:107]
	v_mfma_f32_16x16x32_bf16 v[92:95], v[128:131], v[204:207], v[92:95]
	v_mfma_f32_16x16x32_bf16 v[88:91], v[136:139], v[204:207], v[88:91]
	v_mfma_f32_16x16x32_bf16 v[76:79], v[128:131], v[212:215], v[76:79]
	v_mfma_f32_16x16x32_bf16 v[72:75], v[136:139], v[212:215], v[72:75]
	v_mfma_f32_16x16x32_bf16 v[124:127], v[132:135], v[192:195], v[124:127]
	v_mfma_f32_16x16x32_bf16 v[120:123], v[140:143], v[192:195], v[120:123]
	v_mfma_f32_16x16x32_bf16 v[108:111], v[132:135], v[200:203], v[108:111]
	v_mfma_f32_16x16x32_bf16 v[104:107], v[140:143], v[200:203], v[104:107]
	v_mfma_f32_16x16x32_bf16 v[92:95], v[132:135], v[208:211], v[92:95]
	v_mfma_f32_16x16x32_bf16 v[88:91], v[140:143], v[208:211], v[88:91]
	v_mfma_f32_16x16x32_bf16 v[76:79], v[132:135], v[216:219], v[76:79]
	v_mfma_f32_16x16x32_bf16 v[72:75], v[140:143], v[216:219], v[72:75]
	v_mfma_f32_16x16x32_bf16 v[116:119], v[160:163], v[188:191], v[116:119]
	v_mfma_f32_16x16x32_bf16 v[112:115], v[180:183], v[188:191], v[112:115]
	v_mfma_f32_16x16x32_bf16 v[100:103], v[160:163], v[196:199], v[100:103]
	v_mfma_f32_16x16x32_bf16 v[96:99], v[180:183], v[196:199], v[96:99]
	v_mfma_f32_16x16x32_bf16 v[84:87], v[160:163], v[204:207], v[84:87]
	v_mfma_f32_16x16x32_bf16 v[80:83], v[180:183], v[204:207], v[80:83]
	v_mfma_f32_16x16x32_bf16 v[68:71], v[160:163], v[212:215], v[68:71]
	v_mfma_f32_16x16x32_bf16 v[64:67], v[180:183], v[212:215], v[64:67]
	v_mfma_f32_16x16x32_bf16 v[116:119], v[164:167], v[192:195], v[116:119]
	v_mfma_f32_16x16x32_bf16 v[112:115], v[184:187], v[192:195], v[112:115]
	v_mfma_f32_16x16x32_bf16 v[100:103], v[164:167], v[200:203], v[100:103]
	v_mfma_f32_16x16x32_bf16 v[96:99], v[184:187], v[200:203], v[96:99]
	v_mfma_f32_16x16x32_bf16 v[84:87], v[164:167], v[208:211], v[84:87]
	v_mfma_f32_16x16x32_bf16 v[80:83], v[184:187], v[208:211], v[80:83]
	v_mfma_f32_16x16x32_bf16 v[68:71], v[164:167], v[216:219], v[68:71]
	v_mfma_f32_16x16x32_bf16 v[64:67], v[184:187], v[216:219], v[64:67]
	s_setprio 0
	s_barrier
	s_add_i32 s61, s52, s36
	v_lshl_add_u64 v[220:221], s[8:9], 0, v[148:149]
	s_mov_b32 m0, s61
	ds_read_b128 v[188:191], v175 offset:16384
	ds_read_b128 v[192:195], v175 offset:17408
	ds_read_b128 v[196:199], v175 offset:18432
	ds_read_b128 v[200:203], v175 offset:19456
	ds_read_b128 v[204:207], v175 offset:20480
	ds_read_b128 v[208:211], v175 offset:21504
	ds_read_b128 v[212:215], v175 offset:22528
	ds_read_b128 v[216:219], v175 offset:23552
	global_load_lds_dwordx4 v[220:221], off
	s_add_i32 m0, s61, 0x2000
	s_add_u32 s62, s8, 0x80000
	v_lshl_add_u64 v[222:223], s[8:9], 0, v[144:145]
	s_addc_u32 s63, s9, 0
	s_add_i32 s61, s53, s36
	global_load_lds_dwordx4 v[222:223], off
	v_lshl_add_u64 v[224:225], s[62:63], 0, v[148:149]
	s_mov_b32 m0, s61
	v_lshl_add_u64 v[226:227], s[30:31], 0, v[146:147]
	global_load_lds_dwordx4 v[224:225], off
	v_lshl_add_u64 v[224:225], s[62:63], 0, v[144:145]
	s_add_i32 m0, s61, 0x2000
	s_nop 0
	global_load_lds_dwordx4 v[224:225], off
	v_lshl_add_u64 v[224:225], s[30:31], 0, v[150:151]
	s_mov_b32 m0, s39
	s_nop 0
	global_load_lds_dwordx4 v[224:225], off
	s_mov_b32 m0, s40
	s_nop 0
	global_load_lds_dwordx4 v[226:227], off
	s_waitcnt vmcnt(8)
	s_waitcnt lgkmcnt(0)
	s_barrier
; #define PG8_STAGE(bufoff, gbase, voff) do { _Pragma("unroll") for (int _i = 0; _i < 2; ++_i) \
;         __builtin_amdgcn_global_load_lds((const unsigned*)((const char*)(gbase) + (voff)[_i]), (PG8_LAS unsigned*)(lds + (bufoff) + ldsw + _i * 8192), 16, 0, 0); } while (0)
; #define PG8_LDA(dst, b, h) do { _Pragma("unroll") for (int m = 0; m < 4; ++m) _Pragma("unroll") for (int k = 0; k < 2; ++k) dst[m][k] = *(const PG8_LAS bf16x8*)(lds + PG8_SA(b, h) + aoff + m * 2048 + k * 1024); } while (0)
; #define PG8_LDB(dst, b, h) do { _Pragma("unroll") for (int n = 0; n < 2; ++n) _Pragma("unroll") for (int k = 0; k < 2; ++k) dst[n][k] = *(const PG8_LAS bf16x8*)(lds + PG8_SB(b, h) + boff + n * 2048 + k * 1024); } while (0)
; #define PG8_MMA(ai, bj, At, Bt) do { __builtin_amdgcn_s_setprio(1); _Pragma("unroll") for (int m = 0; m < 4; ++m) _Pragma("unroll") for (int n = 0; n < 2; ++n) _Pragma("unroll") for (int k = 0; k < 2; ++k) \
;         acc[ai][bj][m][n] = __builtin_amdgcn_mfma_f32_16x16x32_bf16(Bt[n][k], At[m][k], acc[ai][bj][m][n], 0, 0, 0); __builtin_amdgcn_s_setprio(0); } while (0)
; #define PG8_WAIT_V(n) asm volatile("s_waitcnt vmcnt(" #n ")" ::: "memory")
; #define PG8_WAIT_L(n) asm volatile("s_waitcnt lgkmcnt(" #n ")" ::: "memory")
; #define PG8_BAR __builtin_amdgcn_s_barrier()
; #define PG8_SCHED __builtin_amdgcn_sched_barrier(0)
; template <class Epi, class Sched, bool ALIGN_EPI = false, bool SP2 = false>
; __device__ __forceinline__ void gemm_phase(PG8_LAS unsigned char* lds, const Gemm g, const Sched& S, const Epi& E, const int wid) {
;     ...
;             PG8_WAIT_V(8); PG8_WAIT_L(0); PG8_BAR; PG8_MMA(1, 0, At, B0); PG8_MMA(1, 1, At, B1); PG8_BAR; PG8_SCHED;
;             PG8_LDB(B0, 1, 0); PG8_LDB(B1, 1, 1); PG8_SCHED; PG8_LDA(At, 1, 0); PG8_STAGE(PG8_SA(0, 1), a2 + hsA, voffA);
;             PG8_WAIT_V(8); PG8_WAIT_L(0); PG8_BAR; PG8_MMA(0, 0, At, B0); PG8_MMA(0, 1, At, B1); PG8_BAR; PG8_SCHED;
	s_setprio 1
	s_waitcnt lgkmcnt(0)
	v_mfma_f32_16x16x32_bf16 v[60:63], v[128:131], v[188:191], v[60:63]
	v_mfma_f32_16x16x32_bf16 v[56:59], v[136:139], v[188:191], v[56:59]
	v_mfma_f32_16x16x32_bf16 v[44:47], v[128:131], v[196:199], v[44:47]
	v_mfma_f32_16x16x32_bf16 v[40:43], v[136:139], v[196:199], v[40:43]
	v_mfma_f32_16x16x32_bf16 v[28:31], v[128:131], v[204:207], v[28:31]
	v_mfma_f32_16x16x32_bf16 v[24:27], v[136:139], v[204:207], v[24:27]
	v_mfma_f32_16x16x32_bf16 v[12:15], v[128:131], v[212:215], v[12:15]
	v_mfma_f32_16x16x32_bf16 v[8:11], v[136:139], v[212:215], v[8:11]
	v_mfma_f32_16x16x32_bf16 v[60:63], v[132:135], v[192:195], v[60:63]
	v_mfma_f32_16x16x32_bf16 v[56:59], v[140:143], v[192:195], v[56:59]
	v_mfma_f32_16x16x32_bf16 v[44:47], v[132:135], v[200:203], v[44:47]
	v_mfma_f32_16x16x32_bf16 v[40:43], v[140:143], v[200:203], v[40:43]
	v_mfma_f32_16x16x32_bf16 v[28:31], v[132:135], v[208:211], v[28:31]
	v_mfma_f32_16x16x32_bf16 v[24:27], v[140:143], v[208:211], v[24:27]
	v_mfma_f32_16x16x32_bf16 v[12:15], v[132:135], v[216:219], v[12:15]
	v_mfma_f32_16x16x32_bf16 v[8:11], v[140:143], v[216:219], v[8:11]
	v_mfma_f32_16x16x32_bf16 v[52:55], v[160:163], v[188:191], v[52:55]
	v_mfma_f32_16x16x32_bf16 v[48:51], v[180:183], v[188:191], v[48:51]
	v_mfma_f32_16x16x32_bf16 v[36:39], v[160:163], v[196:199], v[36:39]
	v_mfma_f32_16x16x32_bf16 v[32:35], v[180:183], v[196:199], v[32:35]
	v_mfma_f32_16x16x32_bf16 v[20:23], v[160:163], v[204:207], v[20:23]
	v_mfma_f32_16x16x32_bf16 v[16:19], v[180:183], v[204:207], v[16:19]
	v_mfma_f32_16x16x32_bf16 v[4:7], v[160:163], v[212:215], v[4:7]
	v_mfma_f32_16x16x32_bf16 v[0:3], v[180:183], v[212:215], v[0:3]
	v_mfma_f32_16x16x32_bf16 v[52:55], v[164:167], v[192:195], v[52:55]
	v_mfma_f32_16x16x32_bf16 v[48:51], v[184:187], v[192:195], v[48:51]
	v_mfma_f32_16x16x32_bf16 v[36:39], v[164:167], v[200:203], v[36:39]
	v_mfma_f32_16x16x32_bf16 v[32:35], v[184:187], v[200:203], v[32:35]
	v_mfma_f32_16x16x32_bf16 v[20:23], v[164:167], v[208:211], v[20:23]
	v_mfma_f32_16x16x32_bf16 v[16:19], v[184:187], v[208:211], v[16:19]
	v_mfma_f32_16x16x32_bf16 v[4:7], v[164:167], v[216:219], v[4:7]
	v_mfma_f32_16x16x32_bf16 v[0:3], v[184:187], v[216:219], v[0:3]
	s_setprio 0
	s_barrier
	s_add_i32 s61, 0, 0x18000
	s_add_i32 s62, 0, 0x1c000
	v_add_u32_e32 v140, s61, v169
	v_add_u32_e32 v168, s62, v169
	ds_read_b128 v[128:131], v140
	ds_read_b128 v[132:135], v140 offset:1024
	ds_read_b128 v[136:139], v140 offset:2048
	ds_read_b128 v[140:143], v140 offset:3072
	ds_read_b128 v[160:163], v168
	ds_read_b128 v[164:167], v168 offset:1024
	ds_read_b128 v[180:183], v168 offset:2048
	ds_read_b128 v[184:187], v168 offset:3072
	s_add_u32 s30, s30, 0x80000
	s_addc_u32 s31, s31, 0
	s_mov_b32 m0, s41
	v_lshl_add_u64 v[228:229], s[30:31], 0, v[150:151]
	ds_read_b128 v[188:191], v175 offset:32768
	ds_read_b128 v[192:195], v175 offset:33792
	ds_read_b128 v[196:199], v175 offset:34816
	ds_read_b128 v[200:203], v175 offset:35840
	ds_read_b128 v[204:207], v175 offset:36864
	ds_read_b128 v[208:211], v175 offset:37888
	ds_read_b128 v[212:215], v175 offset:38912
	ds_read_b128 v[216:219], v175 offset:39936
	global_load_lds_dwordx4 v[228:229], off
	v_lshl_add_u64 v[228:229], s[30:31], 0, v[146:147]
	s_mov_b32 m0, s42
	s_nop 0
	global_load_lds_dwordx4 v[228:229], off
	s_waitcnt vmcnt(8)
	s_waitcnt lgkmcnt(0)
	s_barrier
	s_setprio 1
	s_waitcnt lgkmcnt(0)
	v_mfma_f32_16x16x32_bf16 v[124:127], v[128:131], v[188:191], v[124:127]
	v_mfma_f32_16x16x32_bf16 v[120:123], v[136:139], v[188:191], v[120:123]
	v_mfma_f32_16x16x32_bf16 v[108:111], v[128:131], v[196:199], v[108:111]
	v_mfma_f32_16x16x32_bf16 v[104:107], v[136:139], v[196:199], v[104:107]
	v_mfma_f32_16x16x32_bf16 v[92:95], v[128:131], v[204:207], v[92:95]
	v_mfma_f32_16x16x32_bf16 v[88:91], v[136:139], v[204:207], v[88:91]
	v_mfma_f32_16x16x32_bf16 v[76:79], v[128:131], v[212:215], v[76:79]
	v_mfma_f32_16x16x32_bf16 v[72:75], v[136:139], v[212:215], v[72:75]
	v_mfma_f32_16x16x32_bf16 v[124:127], v[132:135], v[192:195], v[124:127]
	v_mfma_f32_16x16x32_bf16 v[120:123], v[140:143], v[192:195], v[120:123]
	v_mfma_f32_16x16x32_bf16 v[108:111], v[132:135], v[200:203], v[108:111]
	v_mfma_f32_16x16x32_bf16 v[104:107], v[140:143], v[200:203], v[104:107]
	v_mfma_f32_16x16x32_bf16 v[92:95], v[132:135], v[208:211], v[92:95]
	v_mfma_f32_16x16x32_bf16 v[88:91], v[140:143], v[208:211], v[88:91]
	v_mfma_f32_16x16x32_bf16 v[76:79], v[132:135], v[216:219], v[76:79]
	v_mfma_f32_16x16x32_bf16 v[72:75], v[140:143], v[216:219], v[72:75]
	v_mfma_f32_16x16x32_bf16 v[116:119], v[160:163], v[188:191], v[116:119]
	v_mfma_f32_16x16x32_bf16 v[112:115], v[180:183], v[188:191], v[112:115]
	v_mfma_f32_16x16x32_bf16 v[100:103], v[160:163], v[196:199], v[100:103]
	v_mfma_f32_16x16x32_bf16 v[96:99], v[180:183], v[196:199], v[96:99]
	v_mfma_f32_16x16x32_bf16 v[84:87], v[160:163], v[204:207], v[84:87]
	v_mfma_f32_16x16x32_bf16 v[80:83], v[180:183], v[204:207], v[80:83]
	v_mfma_f32_16x16x32_bf16 v[68:71], v[160:163], v[212:215], v[68:71]
	v_mfma_f32_16x16x32_bf16 v[64:67], v[180:183], v[212:215], v[64:67]
	v_mfma_f32_16x16x32_bf16 v[116:119], v[164:167], v[192:195], v[116:119]
	v_mfma_f32_16x16x32_bf16 v[112:115], v[184:187], v[192:195], v[112:115]
	v_mfma_f32_16x16x32_bf16 v[100:103], v[164:167], v[200:203], v[100:103]
	v_mfma_f32_16x16x32_bf16 v[96:99], v[184:187], v[200:203], v[96:99]
	v_mfma_f32_16x16x32_bf16 v[84:87], v[164:167], v[208:211], v[84:87]
	v_mfma_f32_16x16x32_bf16 v[80:83], v[184:187], v[208:211], v[80:83]
	v_mfma_f32_16x16x32_bf16 v[68:71], v[164:167], v[216:219], v[68:71]
	v_mfma_f32_16x16x32_bf16 v[64:67], v[184:187], v[216:219], v[64:67]
	s_setprio 0
	s_barrier
; #define PG8_STAGE(bufoff, gbase, voff) do { _Pragma("unroll") for (int _i = 0; _i < 2; ++_i) \
;         __builtin_amdgcn_global_load_lds((const unsigned*)((const char*)(gbase) + (voff)[_i]), (PG8_LAS unsigned*)(lds + (bufoff) + ldsw + _i * 8192), 16, 0, 0); } while (0)
; #define PG8_LDA(dst, b, h) do { _Pragma("unroll") for (int m = 0; m < 4; ++m) _Pragma("unroll") for (int k = 0; k < 2; ++k) dst[m][k] = *(const PG8_LAS bf16x8*)(lds + PG8_SA(b, h) + aoff + m * 2048 + k * 1024); } while (0)
; #define PG8_MMA(ai, bj, At, Bt) do { __builtin_amdgcn_s_setprio(1); _Pragma("unroll") for (int m = 0; m < 4; ++m) _Pragma("unroll") for (int n = 0; n < 2; ++n) _Pragma("unroll") for (int k = 0; k < 2; ++k) \
;         acc[ai][bj][m][n] = __builtin_amdgcn_mfma_f32_16x16x32_bf16(Bt[n][k], At[m][k], acc[ai][bj][m][n], 0, 0, 0); __builtin_amdgcn_s_setprio(0); } while (0)
; #define PG8_WAIT_V(n) asm volatile("s_waitcnt vmcnt(" #n ")" ::: "memory")
; #define PG8_WAIT_L(n) asm volatile("s_waitcnt lgkmcnt(" #n ")" ::: "memory")
; #define PG8_BAR __builtin_amdgcn_s_barrier()
; #define PG8_SCHED __builtin_amdgcn_sched_barrier(0)
; template <class Epi, class Sched, bool ALIGN_EPI = false, bool SP2 = false>
; __device__ __forceinline__ void gemm_phase(PG8_LAS unsigned char* lds, const Gemm g, const Sched& S, const Epi& E, const int wid) {
;     ...
;             PG8_LDA(At, 1, 1); PG8_STAGE(PG8_SB(1, 0), b3, voffB); PG8_STAGE(PG8_SB(1, 1), b3 + hsB, voffB); PG8_STAGE(PG8_SA(1, 0), a3, voffA);
;             PG8_WAIT_V(8); PG8_WAIT_L(0); PG8_BAR; PG8_MMA(1, 0, At, B0); PG8_MMA(1, 1, At, B1); PG8_BAR; PG8_SCHED;
;     ...
;         if constexpr (ALIGN_EPI) { if (wr == 0) PG8_BAR; }
	s_add_i32 s30, s61, s36
	v_lshl_add_u64 v[220:221], v[220:221], 0, s[18:19]
	s_mov_b32 m0, s30
	ds_read_b128 v[188:191], v175 offset:49152
	ds_read_b128 v[192:195], v175 offset:50176
	ds_read_b128 v[196:199], v175 offset:51200
	ds_read_b128 v[200:203], v175 offset:52224
	ds_read_b128 v[204:207], v175 offset:53248
	ds_read_b128 v[208:211], v175 offset:54272
	ds_read_b128 v[212:215], v175 offset:55296
	ds_read_b128 v[216:219], v175 offset:56320
	global_load_lds_dwordx4 v[220:221], off
	s_add_i32 m0, s30, 0x2000
	s_add_u32 s8, s8, 0x80080
	v_lshl_add_u64 v[220:221], v[222:223], 0, s[18:19]
	s_addc_u32 s9, s9, 0
	s_add_i32 s30, s62, s36
	global_load_lds_dwordx4 v[220:221], off
	v_lshl_add_u64 v[220:221], s[8:9], 0, v[148:149]
	s_mov_b32 m0, s30
	s_nop 0
	global_load_lds_dwordx4 v[220:221], off
	v_lshl_add_u64 v[220:221], s[8:9], 0, v[144:145]
	s_add_i32 m0, s30, 0x2000
	s_nop 0
	global_load_lds_dwordx4 v[220:221], off
	v_lshl_add_u64 v[220:221], v[224:225], 0, s[18:19]
	s_mov_b32 m0, s45
	s_nop 0
	global_load_lds_dwordx4 v[220:221], off
	v_lshl_add_u64 v[220:221], v[226:227], 0, s[18:19]
	s_mov_b32 m0, s46
	s_nop 0
	global_load_lds_dwordx4 v[220:221], off
	s_waitcnt vmcnt(8)
	s_waitcnt lgkmcnt(0)
	s_barrier
	s_setprio 1
	s_waitcnt lgkmcnt(0)
	v_mfma_f32_16x16x32_bf16 v[60:63], v[128:131], v[188:191], v[60:63]
	v_mfma_f32_16x16x32_bf16 v[56:59], v[136:139], v[188:191], v[56:59]
	v_mfma_f32_16x16x32_bf16 v[44:47], v[128:131], v[196:199], v[44:47]
	v_mfma_f32_16x16x32_bf16 v[40:43], v[136:139], v[196:199], v[40:43]
	v_mfma_f32_16x16x32_bf16 v[28:31], v[128:131], v[204:207], v[28:31]
	v_mfma_f32_16x16x32_bf16 v[24:27], v[136:139], v[204:207], v[24:27]
	v_mfma_f32_16x16x32_bf16 v[12:15], v[128:131], v[212:215], v[12:15]
	v_mfma_f32_16x16x32_bf16 v[8:11], v[136:139], v[212:215], v[8:11]
	v_mfma_f32_16x16x32_bf16 v[60:63], v[132:135], v[192:195], v[60:63]
	v_mfma_f32_16x16x32_bf16 v[56:59], v[140:143], v[192:195], v[56:59]
	v_mfma_f32_16x16x32_bf16 v[44:47], v[132:135], v[200:203], v[44:47]
	v_mfma_f32_16x16x32_bf16 v[40:43], v[140:143], v[200:203], v[40:43]
	v_mfma_f32_16x16x32_bf16 v[28:31], v[132:135], v[208:211], v[28:31]
	v_mfma_f32_16x16x32_bf16 v[24:27], v[140:143], v[208:211], v[24:27]
	v_mfma_f32_16x16x32_bf16 v[12:15], v[132:135], v[216:219], v[12:15]
	v_mfma_f32_16x16x32_bf16 v[8:11], v[140:143], v[216:219], v[8:11]
	v_mfma_f32_16x16x32_bf16 v[52:55], v[160:163], v[188:191], v[52:55]
	v_mfma_f32_16x16x32_bf16 v[48:51], v[180:183], v[188:191], v[48:51]
	v_mfma_f32_16x16x32_bf16 v[36:39], v[160:163], v[196:199], v[36:39]
	v_mfma_f32_16x16x32_bf16 v[32:35], v[180:183], v[196:199], v[32:35]
	v_mfma_f32_16x16x32_bf16 v[20:23], v[160:163], v[204:207], v[20:23]
	v_mfma_f32_16x16x32_bf16 v[16:19], v[180:183], v[204:207], v[16:19]
	v_mfma_f32_16x16x32_bf16 v[4:7], v[160:163], v[212:215], v[4:7]
	v_mfma_f32_16x16x32_bf16 v[0:3], v[180:183], v[212:215], v[0:3]
	v_mfma_f32_16x16x32_bf16 v[52:55], v[164:167], v[192:195], v[52:55]
	v_mfma_f32_16x16x32_bf16 v[48:51], v[184:187], v[192:195], v[48:51]
	v_mfma_f32_16x16x32_bf16 v[36:39], v[164:167], v[200:203], v[36:39]
	v_mfma_f32_16x16x32_bf16 v[32:35], v[184:187], v[200:203], v[32:35]
	v_mfma_f32_16x16x32_bf16 v[20:23], v[164:167], v[208:211], v[20:23]
	v_mfma_f32_16x16x32_bf16 v[16:19], v[184:187], v[208:211], v[16:19]
	v_mfma_f32_16x16x32_bf16 v[4:7], v[164:167], v[216:219], v[4:7]
	v_mfma_f32_16x16x32_bf16 v[0:3], v[184:187], v[216:219], v[0:3]
	s_setprio 0
	s_barrier
	s_add_i32 s60, s60, 2
	s_add_u32 s58, s58, 0x100
	s_addc_u32 s59, s59, 0
	s_add_u32 s6, s6, 0x100
	s_addc_u32 s7, s7, 0
	s_cmp_gt_u32 s60, 29
	s_cbranch_scc0 .LBB0_1385
	s_and_b64 vcc, exec, s[20:21]
	s_cbranch_vccz .LBB0_1388
	s_barrier

; #define PG8_STAGE(bufoff, gbase, voff) do { _Pragma("unroll") for (int _i = 0; _i < 2; ++_i) \
;         __builtin_amdgcn_global_load_lds((const unsigned*)((const char*)(gbase) + (voff)[_i]), (PG8_LAS unsigned*)(lds + (bufoff) + ldsw + _i * 8192), 16, 0, 0); } while (0)
; #define PG8_LDA(dst, b, h) do { _Pragma("unroll") for (int m = 0; m < 4; ++m) _Pragma("unroll") for (int k = 0; k < 2; ++k) dst[m][k] = *(const PG8_LAS bf16x8*)(lds + PG8_SA(b, h) + aoff + m * 2048 + k * 1024); } while (0)
; #define PG8_LDB(dst, b, h) do { _Pragma("unroll") for (int n = 0; n < 2; ++n) _Pragma("unroll") for (int k = 0; k < 2; ++k) dst[n][k] = *(const PG8_LAS bf16x8*)(lds + PG8_SB(b, h) + boff + n * 2048 + k * 1024); } while (0)
; #define PG8_MMA(ai, bj, At, Bt) do { __builtin_amdgcn_s_setprio(1); _Pragma("unroll") for (int m = 0; m < 4; ++m) _Pragma("unroll") for (int n = 0; n < 2; ++n) _Pragma("unroll") for (int k = 0; k < 2; ++k) \
;         acc[ai][bj][m][n] = __builtin_amdgcn_mfma_f32_16x16x32_bf16(Bt[n][k], At[m][k], acc[ai][bj][m][n], 0, 0, 0); __builtin_amdgcn_s_setprio(0); } while (0)
; #define PG8_WAIT_V(n) asm volatile("s_waitcnt vmcnt(" #n ")" ::: "memory")
; #define PG8_WAIT_L(n) asm volatile("s_waitcnt lgkmcnt(" #n ")" ::: "memory")
; #define PG8_BAR __builtin_amdgcn_s_barrier()
; #define PG8_SCHED __builtin_amdgcn_sched_barrier(0)
; template <class Epi, class Sched, bool ALIGN_EPI = false, bool SP2 = false>
; __device__ __forceinline__ void gemm_phase(PG8_LAS unsigned char* lds, const Gemm g, const Sched& S, const Epi& E, const int wid) {
;     ...
;             PG8_LDB(B0, 0, 0); PG8_LDB(B1, 0, 1); PG8_SCHED; PG8_LDA(At, 0, 0); PG8_STAGE(PG8_SA(1, 1), a1 + hsA, voffA);
;             PG8_WAIT_V(8); PG8_WAIT_L(0); PG8_BAR; PG8_MMA(0, 0, At, B0); PG8_MMA(0, 1, At, B1); PG8_BAR; PG8_SCHED;
;             PG8_LDA(At, 0, 1); PG8_STAGE(PG8_SB(0, 0), b2, voffB); PG8_STAGE(PG8_SB(0, 1), b2 + hsB, voffB); PG8_STAGE(PG8_SA(0, 0), a2, voffA);
.LBB0_1462:
	ds_read_b128 v[128:131], v163
	ds_read_b128 v[132:135], v163 offset:1024
	ds_read_b128 v[136:139], v163 offset:2048
	ds_read_b128 v[140:143], v163 offset:3072
	ds_read_b128 v[156:159], v164
	ds_read_b128 v[166:169], v164 offset:1024
	ds_read_b128 v[170:173], v164 offset:2048
	ds_read_b128 v[174:177], v164 offset:3072
	s_add_u32 s28, s26, 0x100
	s_addc_u32 s29, s27, 0
	s_cmpk_eq_i32 s58, 0x54
	s_cselect_b32 s35, s5, s29
	s_cselect_b32 s34, s4, s28
	s_cselect_b32 s31, s25, s57
	s_cselect_b32 s30, s24, s56
	v_lshl_add_u64 v[160:161], s[26:27], 0, v[150:151]
	s_add_i32 m0, s40, 0xc000
	ds_read_b128 v[178:181], v165
	ds_read_b128 v[182:185], v165 offset:1024
	ds_read_b128 v[186:189], v165 offset:2048
	ds_read_b128 v[190:193], v165 offset:3072
	ds_read_b128 v[194:197], v165 offset:4096
	ds_read_b128 v[198:201], v165 offset:5120
	ds_read_b128 v[202:205], v165 offset:6144
	ds_read_b128 v[206:209], v165 offset:7168
	global_load_lds_dwordx4 v[160:161], off
	v_lshl_add_u64 v[160:161], s[26:27], 0, v[148:149]
	s_add_i32 m0, s40, 0xe000
	s_nop 0
	global_load_lds_dwordx4 v[160:161], off
	s_waitcnt vmcnt(8)
	s_waitcnt lgkmcnt(0)
	s_barrier
	s_setprio 1
	s_waitcnt lgkmcnt(0)
	v_mfma_f32_16x16x32_bf16 v[124:127], v[128:131], v[178:181], v[124:127]
	v_mfma_f32_16x16x32_bf16 v[120:123], v[136:139], v[178:181], v[120:123]
	v_mfma_f32_16x16x32_bf16 v[116:119], v[128:131], v[186:189], v[116:119]
	v_mfma_f32_16x16x32_bf16 v[112:115], v[136:139], v[186:189], v[112:115]
	v_mfma_f32_16x16x32_bf16 v[92:95], v[128:131], v[194:197], v[92:95]
	v_mfma_f32_16x16x32_bf16 v[88:91], v[136:139], v[194:197], v[88:91]
	v_mfma_f32_16x16x32_bf16 v[84:87], v[128:131], v[202:205], v[84:87]
	v_mfma_f32_16x16x32_bf16 v[80:83], v[136:139], v[202:205], v[80:83]
	v_mfma_f32_16x16x32_bf16 v[124:127], v[132:135], v[182:185], v[124:127]
	v_mfma_f32_16x16x32_bf16 v[120:123], v[140:143], v[182:185], v[120:123]
	v_mfma_f32_16x16x32_bf16 v[116:119], v[132:135], v[190:193], v[116:119]
	v_mfma_f32_16x16x32_bf16 v[112:115], v[140:143], v[190:193], v[112:115]
	v_mfma_f32_16x16x32_bf16 v[92:95], v[132:135], v[198:201], v[92:95]
	v_mfma_f32_16x16x32_bf16 v[88:91], v[140:143], v[198:201], v[88:91]
	v_mfma_f32_16x16x32_bf16 v[84:87], v[132:135], v[206:209], v[84:87]
	v_mfma_f32_16x16x32_bf16 v[80:83], v[140:143], v[206:209], v[80:83]
	v_mfma_f32_16x16x32_bf16 v[108:111], v[156:159], v[178:181], v[108:111]
	v_mfma_f32_16x16x32_bf16 v[104:107], v[170:173], v[178:181], v[104:107]
	v_mfma_f32_16x16x32_bf16 v[100:103], v[156:159], v[186:189], v[100:103]
	v_mfma_f32_16x16x32_bf16 v[96:99], v[170:173], v[186:189], v[96:99]
	v_mfma_f32_16x16x32_bf16 v[76:79], v[156:159], v[194:197], v[76:79]
	v_mfma_f32_16x16x32_bf16 v[72:75], v[170:173], v[194:197], v[72:75]
	v_mfma_f32_16x16x32_bf16 v[68:71], v[156:159], v[202:205], v[68:71]
	v_mfma_f32_16x16x32_bf16 v[64:67], v[170:173], v[202:205], v[64:67]
	v_mfma_f32_16x16x32_bf16 v[108:111], v[166:169], v[182:185], v[108:111]
	v_mfma_f32_16x16x32_bf16 v[104:107], v[174:177], v[182:185], v[104:107]
	v_mfma_f32_16x16x32_bf16 v[100:103], v[166:169], v[190:193], v[100:103]
	v_mfma_f32_16x16x32_bf16 v[96:99], v[174:177], v[190:193], v[96:99]
	v_mfma_f32_16x16x32_bf16 v[76:79], v[166:169], v[198:201], v[76:79]
	v_mfma_f32_16x16x32_bf16 v[72:75], v[174:177], v[198:201], v[72:75]
	v_mfma_f32_16x16x32_bf16 v[68:71], v[166:169], v[206:209], v[68:71]
	v_mfma_f32_16x16x32_bf16 v[64:67], v[174:177], v[206:209], v[64:67]
	s_setprio 0
	s_barrier
	s_add_i32 s26, s50, s39
	v_lshl_add_u64 v[160:161], s[30:31], 0, v[144:145]
	s_mov_b32 m0, s26
	ds_read_b128 v[178:181], v165 offset:16384
	ds_read_b128 v[182:185], v165 offset:17408
	ds_read_b128 v[186:189], v165 offset:18432
	ds_read_b128 v[190:193], v165 offset:19456
	ds_read_b128 v[194:197], v165 offset:20480
	ds_read_b128 v[198:201], v165 offset:21504
	ds_read_b128 v[202:205], v165 offset:22528
	ds_read_b128 v[206:209], v165 offset:23552
	global_load_lds_dwordx4 v[160:161], off
	s_add_i32 m0, s26, 0x2000
	s_add_u32 s26, s30, 0x160000
	v_lshl_add_u64 v[210:211], s[30:31], 0, v[146:147]
	s_addc_u32 s27, s31, 0
	s_add_i32 s59, s51, s39
	global_load_lds_dwordx4 v[210:211], off
	v_lshl_add_u64 v[212:213], s[26:27], 0, v[144:145]
	s_mov_b32 m0, s59
	v_lshl_add_u64 v[214:215], s[34:35], 0, v[146:147]
	global_load_lds_dwordx4 v[212:213], off
	v_lshl_add_u64 v[212:213], s[26:27], 0, v[146:147]
	s_add_i32 m0, s59, 0x2000
	s_nop 0
	global_load_lds_dwordx4 v[212:213], off
	v_lshl_add_u64 v[212:213], s[34:35], 0, v[144:145]
	s_mov_b32 m0, s40
	s_nop 0
	global_load_lds_dwordx4 v[212:213], off
	s_mov_b32 m0, s41
	s_nop 0
	global_load_lds_dwordx4 v[214:215], off
	s_waitcnt vmcnt(8)
	s_waitcnt lgkmcnt(0)
	s_barrier
; #define PG8_STAGE(bufoff, gbase, voff) do { _Pragma("unroll") for (int _i = 0; _i < 2; ++_i) \
;         __builtin_amdgcn_global_load_lds((const unsigned*)((const char*)(gbase) + (voff)[_i]), (PG8_LAS unsigned*)(lds + (bufoff) + ldsw + _i * 8192), 16, 0, 0); } while (0)
; #define PG8_LDA(dst, b, h) do { _Pragma("unroll") for (int m = 0; m < 4; ++m) _Pragma("unroll") for (int k = 0; k < 2; ++k) dst[m][k] = *(const PG8_LAS bf16x8*)(lds + PG8_SA(b, h) + aoff + m * 2048 + k * 1024); } while (0)
; #define PG8_LDB(dst, b, h) do { _Pragma("unroll") for (int n = 0; n < 2; ++n) _Pragma("unroll") for (int k = 0; k < 2; ++k) dst[n][k] = *(const PG8_LAS bf16x8*)(lds + PG8_SB(b, h) + boff + n * 2048 + k * 1024); } while (0)
; #define PG8_MMA(ai, bj, At, Bt) do { __builtin_amdgcn_s_setprio(1); _Pragma("unroll") for (int m = 0; m < 4; ++m) _Pragma("unroll") for (int n = 0; n < 2; ++n) _Pragma("unroll") for (int k = 0; k < 2; ++k) \
;         acc[ai][bj][m][n] = __builtin_amdgcn_mfma_f32_16x16x32_bf16(Bt[n][k], At[m][k], acc[ai][bj][m][n], 0, 0, 0); __builtin_amdgcn_s_setprio(0); } while (0)
; #define PG8_WAIT_V(n) asm volatile("s_waitcnt vmcnt(" #n ")" ::: "memory")
; #define PG8_WAIT_L(n) asm volatile("s_waitcnt lgkmcnt(" #n ")" ::: "memory")
; #define PG8_BAR __builtin_amdgcn_s_barrier()
; #define PG8_SCHED __builtin_amdgcn_sched_barrier(0)
; template <class Epi, class Sched, bool ALIGN_EPI = false, bool SP2 = false>
; __device__ __forceinline__ void gemm_phase(PG8_LAS unsigned char* lds, const Gemm g, const Sched& S, const Epi& E, const int wid) {
;     ...
;             PG8_WAIT_V(8); PG8_WAIT_L(0); PG8_BAR; PG8_MMA(1, 0, At, B0); PG8_MMA(1, 1, At, B1); PG8_BAR; PG8_SCHED;
;             PG8_LDB(B0, 1, 0); PG8_LDB(B1, 1, 1); PG8_SCHED; PG8_LDA(At, 1, 0); PG8_STAGE(PG8_SA(0, 1), a2 + hsA, voffA);
;             PG8_WAIT_V(8); PG8_WAIT_L(0); PG8_BAR; PG8_MMA(0, 0, At, B0); PG8_MMA(0, 1, At, B1); PG8_BAR; PG8_SCHED;
	s_setprio 1
	s_waitcnt lgkmcnt(0)
	v_mfma_f32_16x16x32_bf16 v[60:63], v[128:131], v[178:181], v[60:63]
	v_mfma_f32_16x16x32_bf16 v[56:59], v[136:139], v[178:181], v[56:59]
	v_mfma_f32_16x16x32_bf16 v[52:55], v[128:131], v[186:189], v[52:55]
	v_mfma_f32_16x16x32_bf16 v[48:51], v[136:139], v[186:189], v[48:51]
	v_mfma_f32_16x16x32_bf16 v[28:31], v[128:131], v[194:197], v[28:31]
	v_mfma_f32_16x16x32_bf16 v[24:27], v[136:139], v[194:197], v[24:27]
	v_mfma_f32_16x16x32_bf16 v[20:23], v[128:131], v[202:205], v[20:23]
	v_mfma_f32_16x16x32_bf16 v[16:19], v[136:139], v[202:205], v[16:19]
	v_mfma_f32_16x16x32_bf16 v[60:63], v[132:135], v[182:185], v[60:63]
	v_mfma_f32_16x16x32_bf16 v[56:59], v[140:143], v[182:185], v[56:59]
	v_mfma_f32_16x16x32_bf16 v[52:55], v[132:135], v[190:193], v[52:55]
	v_mfma_f32_16x16x32_bf16 v[48:51], v[140:143], v[190:193], v[48:51]
	v_mfma_f32_16x16x32_bf16 v[28:31], v[132:135], v[198:201], v[28:31]
	v_mfma_f32_16x16x32_bf16 v[24:27], v[140:143], v[198:201], v[24:27]
	v_mfma_f32_16x16x32_bf16 v[20:23], v[132:135], v[206:209], v[20:23]
	v_mfma_f32_16x16x32_bf16 v[16:19], v[140:143], v[206:209], v[16:19]
	v_mfma_f32_16x16x32_bf16 v[44:47], v[156:159], v[178:181], v[44:47]
	v_mfma_f32_16x16x32_bf16 v[40:43], v[170:173], v[178:181], v[40:43]
	v_mfma_f32_16x16x32_bf16 v[36:39], v[156:159], v[186:189], v[36:39]
	v_mfma_f32_16x16x32_bf16 v[32:35], v[170:173], v[186:189], v[32:35]
	v_mfma_f32_16x16x32_bf16 v[12:15], v[156:159], v[194:197], v[12:15]
	v_mfma_f32_16x16x32_bf16 v[8:11], v[170:173], v[194:197], v[8:11]
	v_mfma_f32_16x16x32_bf16 v[4:7], v[156:159], v[202:205], v[4:7]
	v_mfma_f32_16x16x32_bf16 v[0:3], v[170:173], v[202:205], v[0:3]
	v_mfma_f32_16x16x32_bf16 v[44:47], v[166:169], v[182:185], v[44:47]
	v_mfma_f32_16x16x32_bf16 v[40:43], v[174:177], v[182:185], v[40:43]
	v_mfma_f32_16x16x32_bf16 v[36:39], v[166:169], v[190:193], v[36:39]
	v_mfma_f32_16x16x32_bf16 v[32:35], v[174:177], v[190:193], v[32:35]
	v_mfma_f32_16x16x32_bf16 v[12:15], v[166:169], v[198:201], v[12:15]
	v_mfma_f32_16x16x32_bf16 v[8:11], v[174:177], v[198:201], v[8:11]
	v_mfma_f32_16x16x32_bf16 v[4:7], v[166:169], v[206:209], v[4:7]
	v_mfma_f32_16x16x32_bf16 v[0:3], v[174:177], v[206:209], v[0:3]
	s_setprio 0
	s_barrier
	s_add_i32 s59, 0, 0x18000
	s_add_i32 s60, 0, 0x1c000
	v_add_u32_e32 v140, s59, v162
	v_add_u32_e32 v174, s60, v162
	ds_read_b128 v[128:131], v140
	ds_read_b128 v[132:135], v140 offset:1024
	ds_read_b128 v[136:139], v140 offset:2048
	ds_read_b128 v[140:143], v140 offset:3072
	ds_read_b128 v[156:159], v174
	ds_read_b128 v[166:169], v174 offset:1024
	ds_read_b128 v[170:173], v174 offset:2048
	ds_read_b128 v[174:177], v174 offset:3072
	s_add_u32 s26, s34, 0x160000
	s_addc_u32 s27, s35, 0
	s_mov_b32 m0, s42
	v_lshl_add_u64 v[216:217], s[26:27], 0, v[144:145]
	ds_read_b128 v[178:181], v165 offset:32768
	ds_read_b128 v[182:185], v165 offset:33792
	ds_read_b128 v[186:189], v165 offset:34816
	ds_read_b128 v[190:193], v165 offset:35840
	ds_read_b128 v[194:197], v165 offset:36864
	ds_read_b128 v[198:201], v165 offset:37888
	ds_read_b128 v[202:205], v165 offset:38912
	ds_read_b128 v[206:209], v165 offset:39936
	global_load_lds_dwordx4 v[216:217], off
	v_lshl_add_u64 v[216:217], s[26:27], 0, v[146:147]
	s_mov_b32 m0, s43
	s_nop 0
	global_load_lds_dwordx4 v[216:217], off
	s_waitcnt vmcnt(8)
	s_waitcnt lgkmcnt(0)
	s_barrier
	s_setprio 1
	s_waitcnt lgkmcnt(0)
	v_mfma_f32_16x16x32_bf16 v[124:127], v[128:131], v[178:181], v[124:127]
	v_mfma_f32_16x16x32_bf16 v[120:123], v[136:139], v[178:181], v[120:123]
	v_mfma_f32_16x16x32_bf16 v[116:119], v[128:131], v[186:189], v[116:119]
	v_mfma_f32_16x16x32_bf16 v[112:115], v[136:139], v[186:189], v[112:115]
	v_mfma_f32_16x16x32_bf16 v[92:95], v[128:131], v[194:197], v[92:95]
	v_mfma_f32_16x16x32_bf16 v[88:91], v[136:139], v[194:197], v[88:91]
	v_mfma_f32_16x16x32_bf16 v[84:87], v[128:131], v[202:205], v[84:87]
	v_mfma_f32_16x16x32_bf16 v[80:83], v[136:139], v[202:205], v[80:83]
	v_mfma_f32_16x16x32_bf16 v[124:127], v[132:135], v[182:185], v[124:127]
	v_mfma_f32_16x16x32_bf16 v[120:123], v[140:143], v[182:185], v[120:123]
	v_mfma_f32_16x16x32_bf16 v[116:119], v[132:135], v[190:193], v[116:119]
	v_mfma_f32_16x16x32_bf16 v[112:115], v[140:143], v[190:193], v[112:115]
	v_mfma_f32_16x16x32_bf16 v[92:95], v[132:135], v[198:201], v[92:95]
	v_mfma_f32_16x16x32_bf16 v[88:91], v[140:143], v[198:201], v[88:91]
	v_mfma_f32_16x16x32_bf16 v[84:87], v[132:135], v[206:209], v[84:87]
	v_mfma_f32_16x16x32_bf16 v[80:83], v[140:143], v[206:209], v[80:83]
	v_mfma_f32_16x16x32_bf16 v[108:111], v[156:159], v[178:181], v[108:111]
	v_mfma_f32_16x16x32_bf16 v[104:107], v[170:173], v[178:181], v[104:107]
	v_mfma_f32_16x16x32_bf16 v[100:103], v[156:159], v[186:189], v[100:103]
	v_mfma_f32_16x16x32_bf16 v[96:99], v[170:173], v[186:189], v[96:99]
	v_mfma_f32_16x16x32_bf16 v[76:79], v[156:159], v[194:197], v[76:79]
	v_mfma_f32_16x16x32_bf16 v[72:75], v[170:173], v[194:197], v[72:75]
	v_mfma_f32_16x16x32_bf16 v[68:71], v[156:159], v[202:205], v[68:71]
	v_mfma_f32_16x16x32_bf16 v[64:67], v[170:173], v[202:205], v[64:67]
	v_mfma_f32_16x16x32_bf16 v[108:111], v[166:169], v[182:185], v[108:111]
	v_mfma_f32_16x16x32_bf16 v[104:107], v[174:177], v[182:185], v[104:107]
	v_mfma_f32_16x16x32_bf16 v[100:103], v[166:169], v[190:193], v[100:103]
	v_mfma_f32_16x16x32_bf16 v[96:99], v[174:177], v[190:193], v[96:99]
	v_mfma_f32_16x16x32_bf16 v[76:79], v[166:169], v[198:201], v[76:79]
	v_mfma_f32_16x16x32_bf16 v[72:75], v[174:177], v[198:201], v[72:75]
	v_mfma_f32_16x16x32_bf16 v[68:71], v[166:169], v[206:209], v[68:71]
	v_mfma_f32_16x16x32_bf16 v[64:67], v[174:177], v[206:209], v[64:67]
	s_setprio 0
	s_barrier
; #define PG8_STAGE(bufoff, gbase, voff) do { _Pragma("unroll") for (int _i = 0; _i < 2; ++_i) \
;         __builtin_amdgcn_global_load_lds((const unsigned*)((const char*)(gbase) + (voff)[_i]), (PG8_LAS unsigned*)(lds + (bufoff) + ldsw + _i * 8192), 16, 0, 0); } while (0)
; #define PG8_LDA(dst, b, h) do { _Pragma("unroll") for (int m = 0; m < 4; ++m) _Pragma("unroll") for (int k = 0; k < 2; ++k) dst[m][k] = *(const PG8_LAS bf16x8*)(lds + PG8_SA(b, h) + aoff + m * 2048 + k * 1024); } while (0)
; #define PG8_MMA(ai, bj, At, Bt) do { __builtin_amdgcn_s_setprio(1); _Pragma("unroll") for (int m = 0; m < 4; ++m) _Pragma("unroll") for (int n = 0; n < 2; ++n) _Pragma("unroll") for (int k = 0; k < 2; ++k) \
;         acc[ai][bj][m][n] = __builtin_amdgcn_mfma_f32_16x16x32_bf16(Bt[n][k], At[m][k], acc[ai][bj][m][n], 0, 0, 0); __builtin_amdgcn_s_setprio(0); } while (0)
; #define PG8_WAIT_V(n) asm volatile("s_waitcnt vmcnt(" #n ")" ::: "memory")
; #define PG8_WAIT_L(n) asm volatile("s_waitcnt lgkmcnt(" #n ")" ::: "memory")
; #define PG8_BAR __builtin_amdgcn_s_barrier()
; #define PG8_SCHED __builtin_amdgcn_sched_barrier(0)
; template <class Epi, class Sched, bool ALIGN_EPI = false, bool SP2 = false>
; __device__ __forceinline__ void gemm_phase(PG8_LAS unsigned char* lds, const Gemm g, const Sched& S, const Epi& E, const int wid) {
;     ...
;             PG8_LDA(At, 1, 1); PG8_STAGE(PG8_SB(1, 0), b3, voffB); PG8_STAGE(PG8_SB(1, 1), b3 + hsB, voffB); PG8_STAGE(PG8_SA(1, 0), a3, voffA);
;             PG8_WAIT_V(8); PG8_WAIT_L(0); PG8_BAR; PG8_MMA(1, 0, At, B0); PG8_MMA(1, 1, At, B1); PG8_BAR; PG8_SCHED;
;     ...
;         if constexpr (ALIGN_EPI) { if (wr == 0) PG8_BAR; }
	s_add_i32 s26, s59, s39
	v_lshl_add_u64 v[160:161], v[160:161], 0, s[14:15]
	s_mov_b32 m0, s26
	ds_read_b128 v[178:181], v165 offset:49152
	ds_read_b128 v[182:185], v165 offset:50176
	ds_read_b128 v[186:189], v165 offset:51200
	ds_read_b128 v[190:193], v165 offset:52224
	ds_read_b128 v[194:197], v165 offset:53248
	ds_read_b128 v[198:201], v165 offset:54272
	ds_read_b128 v[202:205], v165 offset:55296
	ds_read_b128 v[206:209], v165 offset:56320
	global_load_lds_dwordx4 v[160:161], off
	s_add_i32 m0, s26, 0x2000
	s_add_u32 s26, s30, 0x160080
	v_lshl_add_u64 v[160:161], v[210:211], 0, s[14:15]
	s_addc_u32 s27, s31, 0
	s_add_i32 s30, s60, s39
	global_load_lds_dwordx4 v[160:161], off
	v_lshl_add_u64 v[160:161], s[26:27], 0, v[144:145]
	s_mov_b32 m0, s30
	s_nop 0
	global_load_lds_dwordx4 v[160:161], off
	v_lshl_add_u64 v[160:161], s[26:27], 0, v[146:147]
	s_add_i32 m0, s30, 0x2000
	s_nop 0
	global_load_lds_dwordx4 v[160:161], off
	v_lshl_add_u64 v[160:161], v[212:213], 0, s[14:15]
	s_mov_b32 m0, s47
	s_nop 0
	global_load_lds_dwordx4 v[160:161], off
	v_lshl_add_u64 v[160:161], v[214:215], 0, s[14:15]
	s_mov_b32 m0, s48
	s_nop 0
	global_load_lds_dwordx4 v[160:161], off
	s_waitcnt vmcnt(8)
	s_waitcnt lgkmcnt(0)
	s_barrier
	s_setprio 1
	s_waitcnt lgkmcnt(0)
	v_mfma_f32_16x16x32_bf16 v[60:63], v[128:131], v[178:181], v[60:63]
	v_mfma_f32_16x16x32_bf16 v[56:59], v[136:139], v[178:181], v[56:59]
	v_mfma_f32_16x16x32_bf16 v[52:55], v[128:131], v[186:189], v[52:55]
	v_mfma_f32_16x16x32_bf16 v[48:51], v[136:139], v[186:189], v[48:51]
	v_mfma_f32_16x16x32_bf16 v[28:31], v[128:131], v[194:197], v[28:31]
	v_mfma_f32_16x16x32_bf16 v[24:27], v[136:139], v[194:197], v[24:27]
	v_mfma_f32_16x16x32_bf16 v[20:23], v[128:131], v[202:205], v[20:23]
	v_mfma_f32_16x16x32_bf16 v[16:19], v[136:139], v[202:205], v[16:19]
	v_mfma_f32_16x16x32_bf16 v[60:63], v[132:135], v[182:185], v[60:63]
	v_mfma_f32_16x16x32_bf16 v[56:59], v[140:143], v[182:185], v[56:59]
	v_mfma_f32_16x16x32_bf16 v[52:55], v[132:135], v[190:193], v[52:55]
	v_mfma_f32_16x16x32_bf16 v[48:51], v[140:143], v[190:193], v[48:51]
	v_mfma_f32_16x16x32_bf16 v[28:31], v[132:135], v[198:201], v[28:31]
	v_mfma_f32_16x16x32_bf16 v[24:27], v[140:143], v[198:201], v[24:27]
	v_mfma_f32_16x16x32_bf16 v[20:23], v[132:135], v[206:209], v[20:23]
	v_mfma_f32_16x16x32_bf16 v[16:19], v[140:143], v[206:209], v[16:19]
	v_mfma_f32_16x16x32_bf16 v[44:47], v[156:159], v[178:181], v[44:47]
	v_mfma_f32_16x16x32_bf16 v[40:43], v[170:173], v[178:181], v[40:43]
	v_mfma_f32_16x16x32_bf16 v[36:39], v[156:159], v[186:189], v[36:39]
	v_mfma_f32_16x16x32_bf16 v[32:35], v[170:173], v[186:189], v[32:35]
	v_mfma_f32_16x16x32_bf16 v[12:15], v[156:159], v[194:197], v[12:15]
	v_mfma_f32_16x16x32_bf16 v[8:11], v[170:173], v[194:197], v[8:11]
	v_mfma_f32_16x16x32_bf16 v[4:7], v[156:159], v[202:205], v[4:7]
	v_mfma_f32_16x16x32_bf16 v[0:3], v[170:173], v[202:205], v[0:3]
	v_mfma_f32_16x16x32_bf16 v[44:47], v[166:169], v[182:185], v[44:47]
	v_mfma_f32_16x16x32_bf16 v[40:43], v[174:177], v[182:185], v[40:43]
	v_mfma_f32_16x16x32_bf16 v[36:39], v[166:169], v[190:193], v[36:39]
	v_mfma_f32_16x16x32_bf16 v[32:35], v[174:177], v[190:193], v[32:35]
	v_mfma_f32_16x16x32_bf16 v[12:15], v[166:169], v[198:201], v[12:15]
	v_mfma_f32_16x16x32_bf16 v[8:11], v[174:177], v[198:201], v[8:11]
	v_mfma_f32_16x16x32_bf16 v[4:7], v[166:169], v[206:209], v[4:7]
	v_mfma_f32_16x16x32_bf16 v[0:3], v[174:177], v[206:209], v[0:3]
	s_setprio 0
	s_barrier
	s_add_i32 s58, s58, 2
	s_add_u32 s56, s56, 0x100
	s_addc_u32 s57, s57, 0
	s_cmpk_gt_u32 s58, 0x55
	s_mov_b64 s[26:27], s[28:29]
	s_cbranch_scc0 .LBB0_1462
	s_and_b64 vcc, exec, s[16:17]
	s_cbranch_vccz .LBB0_1465
	s_barrier
